# attention loop rewritten by hand: 4-deep LDS ring, 1 barrier per KV tile, prefetched K/V fragments, softmax VALU spread over MFMA slots
# speedup vs baseline: 1.0420x; 1.0420x over previous
; __device__ __forceinline__ int v_st(int k, int c) { const int kk = (k & ~0xC) | ((k & 4) << 1) | ((k & 8) >> 1); return ((kk >> 3) * 4 + (c >> 5)) * 512 + ((kk & 7) * 32 + (c & 31)) * 2; }
; __device__ __forceinline__ int v_rd_base(int lane) { return ((lane & 3) << 3) | (((lane >> 2) & 3) << 6) | (((lane >> 4) & 1) << 5) | (((lane >> 5) & 1) << 8); }
; #define SLOAD(i, k0) do { sr_[i].vs0 = St::ld8(&Vh[(long)((k0) + sr) * LDK + sc]); sr_[i].vs1 = St::ld8(&Vh[(long)((k0) + 32 + sr) * LDK + sc]); \
;     sr_[i].ks0 = St::ld8(&Kh[(long)((k0) + sr) * LDK + sc]); sr_[i].ks1 = St::ld8(&Kh[(long)((k0) + 32 + sr) * LDK + sc]); } while (0)
; #define QF(d, e) __uint_as_float(((unsigned)(unsigned short)qr[d][e]) << 16)
; template <typename TQ> ...
;     ...
;   const int tid = tid_, wid = __builtin_amdgcn_readfirstlane(tid >> 6), lane = tid & 63, r32 = lane & 31, hi = lane >> 5;
;   bf16* V_lds = (bf16*)lds; bf16* K_lds = (bf16*)(lds + 2 * SHM_V);
;   float* ws = (float*)(lds + 2 * SHM_V + 2 * SHM_K) + wid * 64; float* li_l = ws;
;   float l_reg = 0; f32x16 o[4] = {}; bf16x8 qr[8];
;   const TQ* Qw = Qb + (long)(wid * QBLK + r32) * LDQ + hi * 8;
; #pragma unroll
;   for (int d0 = 0; d0 < 8; ++d0) qr[d0] = SQ::tobf(SQ::ld8(Qw + d0 * 16));
;   const int sr = tid >> 4, sc = (tid & 15) * 8, vst0 = v_st(sr, sc), vst1 = v_st(32 + sr, sc);
;   const int vb0 = (int)(uintptr_t)V_lds + v_rd_base(lane);
;   struct { typename St::T vs0, vs1, ks0, ks1; } sr_[SDEPTH];
;     ...
;   constexpr int SE = 0, SO = SDEPTH - 1;
;   SLOAD(SE, 0);
;   {
;     float ss = 0.f;
;     ...
; #pragma unroll
;     for (int d0 = 0; d0 < 8; ++d0)
; #pragma unroll
;       for (int e = 0; e < 8; ++e) { const float x = QF(d0, e); ss += x * x; }
; __global__ void __launch_bounds__(NTHR, 2) fwd_megakernel(KArgs a) {
;     ...
;         for (int i = 0; i < upb; ++i) {
;             const int unit = vcu * upb + i; if (unit >= 512) break;
;             const int grp = unit >> 7, rem = unit & 127, gq = rem >> 5, qb = rem & 31, b = grp >> 1, kvh = grp & 1, h = kvh * 4 + gq;
;             const size_t qoff = ((size_t)(b * SEQ + qb * 256)) * DM + h * 128, koff = (size_t)b * SKV * 256 + kvh * 128;
;             att::attn_dense_body<att::bf16>(Q + qoff, Kb + koff, Vb + koff, O + qoff, SKV, (char*)lds_raw, mC, a.g_q, (const float*)(ws + WS_ROPE), (const float*)(ws + WS_ROPE) + 4096, qb * 256);
.LBB0_819:
	s_add_i32 s12, s74, s73
	s_cmpk_gt_i32 s12, 0x1ff
	s_mov_b64 s[0:1], -1
	s_cbranch_scc1 .LBB0_818
	s_lshl_b32 s0, s94, 1
	s_ashr_i32 s96, s12, 8
	s_lshl_b32 s1, s12, 8
	s_and_b32 s95, s0, 0x100
	s_lshl_b32 s0, s96, 13
	s_and_b32 s33, s1, 0x1f00
	s_bfe_u32 s15, s12, 0x10007
	s_or_b32 s0, s0, s33
	s_lshl_b32 s12, s12, 2
	s_ashr_i32 s1, s0, 31
	s_lshl_b32 s13, s15, 9
	s_and_b32 s12, s12, 0x180
	s_lshl_b64 s[0:1], s[0:1], 10
	s_or_b32 s12, s13, s12
	s_or_b32 s0, s0, s12
	s_mul_i32 s12, s96, 0x210000
	s_lshl_b32 s15, s15, 7
	s_or_b32 s12, s12, s15
	s_lshl_b64 s[48:49], s[0:1], 1
	s_mul_hi_i32 s13, s96, 0x210000
	s_add_u32 s0, s20, s48
	s_addc_u32 s1, s21, s49
	s_lshl_b64 s[12:13], s[12:13], 1
	s_add_u32 s54, s69, s12
	s_addc_u32 s55, s70, s13
	v_mov_b32_e32 v114, v0
	s_add_u32 s64, s67, s12
	s_addc_u32 s65, s68, s13
	v_readfirstlane_b32 s53, v114
	s_ashr_i32 s12, s53, 1
	v_mov_b32_e32 v18, s12
	v_bfi_b32 v66, s75, v18, v114
	v_ashrrev_i32_e32 v67, 31, v66
	v_lshlrev_b64 v[18:19], 11, v[66:67]
	v_lshrrev_b32_e32 v20, 1, v114
	v_lshl_add_u64 v[18:19], s[0:1], 0, v[18:19]
	v_and_b32_e32 v194, 16, v20
	v_lshl_add_u64 v[18:19], v[18:19], 0, v[194:195]
	global_load_dwordx4 v[22:25], v[18:19], off offset:224
	global_load_dwordx4 v[28:31], v[18:19], off offset:160
	global_load_dwordx4 v[80:83], v[18:19], off offset:192
	global_load_dwordx4 v[84:87], v[18:19], off offset:128
	global_load_dwordx4 v[116:119], v[18:19], off
	global_load_dwordx4 v[96:99], v[18:19], off offset:32
	global_load_dwordx4 v[120:123], v[18:19], off offset:64
	global_load_dwordx4 v[124:127], v[18:19], off offset:96
	v_and_b32_e32 v42, 32, v114
	global_load_dwordx2 v[100:101], v42, s[26:27]
	global_load_dwordx2 v[60:61], v42, s[26:27] offset:128
	v_ashrrev_i32_e32 v38, 4, v114
	v_ashrrev_i32_e32 v39, 31, v38
	v_lshlrev_b64 v[34:35], 9, v[38:39]
	v_and_b32_e32 v202, 31, v114
	v_or_b32_e32 v32, s33, v202
	s_and_b32 s52, s12, 0xffffffe0
	v_add_u32_e32 v32, s52, v32
	v_ashrrev_i32_e32 v32, 1, v32
	v_and_b32_e32 v32, 0xffffffe0, v32
	v_ashrrev_i32_e32 v33, 31, v32
	v_lshlrev_b64 v[32:33], 2, v[32:33]
	v_mov_b32_e32 v43, v195
	v_lshl_add_u64 v[44:45], s[4:5], 0, v[32:33]
	v_lshl_add_u64 v[32:33], s[6:7], 0, v[32:33]
	v_lshl_add_u64 v[76:77], v[44:45], 0, v[42:43]
	v_lshl_add_u64 v[78:79], v[32:33], 0, v[42:43]
	global_load_dwordx2 v[106:107], v[76:77], off
	global_load_dwordx2 v[104:105], v[78:79], off
	v_add_u32_e32 v40, 32, v38
	v_ashrrev_i32_e32 v41, 31, v40
	v_lshlrev_b64 v[26:27], 9, v[40:41]
	v_lshlrev_b32_e32 v111, 3, v114
	v_and_b32_e32 v18, 0x78, v111
	v_lshlrev_b32_e32 v110, 1, v18
	v_or_b32_e32 v36, v34, v110
	v_mov_b32_e32 v37, v35
	v_or_b32_e32 v26, v26, v110
	v_lshl_add_u64 v[18:19], s[64:65], 0, v[36:37]
	v_lshl_add_u64 v[20:21], s[64:65], 0, v[26:27]
	v_lshl_add_u64 v[26:27], s[54:55], 0, v[26:27]
	v_and_b32_e32 v203, 63, v114
	v_mov_b32_e32 v205, 0
	s_waitcnt vmcnt(11)
	v_lshlrev_b32_e32 v56, 16, v22
	s_waitcnt vmcnt(7)
	v_lshlrev_b32_e32 v163, 16, v117
	v_and_b32_e32 v167, 0xffff0000, v117
	v_lshlrev_b32_e32 v171, 16, v116
	s_waitcnt vmcnt(5)
	v_lshlrev_b32_e32 v170, 16, v120
	v_and_b32_e32 v117, 0xffff0000, v116
	v_and_b32_e32 v116, 0xffff0000, v120
	v_lshlrev_b32_e32 v162, 16, v121
	v_and_b32_e32 v166, 0xffff0000, v121
	v_pk_mul_f32 v[172:173], v[170:171], v[170:171]
	v_pk_mul_f32 v[120:121], v[116:117], v[116:117]
	v_pk_mul_f32 v[164:165], v[162:163], v[162:163]
	v_add_f32_e32 v39, v173, v121
	v_lshlrev_b32_e32 v159, 16, v118
	v_lshlrev_b32_e32 v158, 16, v122
	v_pk_mul_f32 v[168:169], v[166:167], v[166:167]
	v_add_f32_e32 v39, v165, v39
	v_lshlrev_b32_e32 v109, 16, v119
	v_and_b32_e32 v103, 0xffff0000, v119
	v_pk_mul_f32 v[160:161], v[158:159], v[158:159]
	v_and_b32_e32 v119, 0xffff0000, v118
	v_and_b32_e32 v118, 0xffff0000, v122
	v_add_f32_e32 v39, v169, v39
	v_lshlrev_b32_e32 v108, 16, v123
	v_and_b32_e32 v102, 0xffff0000, v123
	v_pk_mul_f32 v[122:123], v[118:119], v[118:119]
	v_add_f32_e32 v39, v161, v39
	v_pk_mul_f32 v[146:147], v[108:109], v[108:109]
	v_add_f32_e32 v39, v123, v39
	v_lshlrev_b32_e32 v64, 16, v87
	v_and_b32_e32 v62, 0xffff0000, v87
	v_lshlrev_b32_e32 v75, 16, v85
	v_and_b32_e32 v73, 0xffff0000, v85
	v_lshlrev_b32_e32 v87, 16, v99
	v_and_b32_e32 v85, 0xffff0000, v99
	v_pk_mul_f32 v[148:149], v[102:103], v[102:103]
	v_lshlrev_b32_e32 v91, 16, v98
	v_and_b32_e32 v89, 0xffff0000, v98
	v_lshlrev_b32_e32 v99, 16, v96
	s_waitcnt vmcnt(4)
; #define QF(d, e) __uint_as_float(((unsigned)(unsigned short)qr[d][e]) << 16)
; template <typename TQ> ...
;     ...
;     float ss = 0.f;
;     ...
; #pragma unroll
;     for (int d0 = 0; d0 < 8; ++d0)
; #pragma unroll
;       for (int e = 0; e < 8; ++e) { const float x = QF(d0, e); ss += x * x; }
;     ss += __shfl_xor(ss, 32);
;     const float rn = (SCALE * 1.4426950408889634f) / sqrtf(ss * (1.0f / 128.0f) + 1e-6f);
;     const int t = trow0 + wid * QBLK + r32; const int prow = t >> 6, pcol = t & 63;
; #pragma unroll
;     for (int hf = 0; hf < 2; ++hf)
; #pragma unroll
;       for (int dd = 0; dd < 2; ++dd) {
;         const int dl = 4 * hf + dd, du = dl + 2;
;         const int f0 = 16 * dd + 8 * hi;
;         const float* cp = rc + (hf ? pcol : prow) * 32 + f0; const float* sp = rsn + (hf ? pcol : prow) * 32 + f0;
;         const float* gl = gq + 16 * dl + 8 * hi; const float* gu = gq + 16 * du + 8 * hi;
;         unsigned wl[4], wu[4];
; #pragma unroll
;         for (int e = 0; e < 8; e += 2) {
;           float o1[2], o2[2];
; #pragma unroll
;           for (int k = 0; k < 2; ++k) { const float x1 = QF(dl, e + k) * rn * gl[e + k], x2 = QF(du, e + k) * rn * gu[e + k]; const float c = cp[e + k], sn = sp[e + k];
;             o1[k] = x1 * c - x2 * sn; o2[k] = x2 * c + x1 * sn; }
;           wl[e >> 1] = cvtpk(o1[0], o1[1]); wu[e >> 1] = cvtpk(o2[0], o2[1]);
;         }
;         u32x4 vl = {wl[0], wl[1], wl[2], wl[3]}, vu = {wu[0], wu[1], wu[2], wu[3]};
;         qr[dl] = *reinterpret_cast<bf16x8*>(&vl); qr[du] = *reinterpret_cast<bf16x8*>(&vu);
;       }
	v_lshlrev_b32_e32 v98, 16, v124
	v_add_f32_e32 v39, v147, v39
	v_lshlrev_b32_e32 v95, 16, v97
	v_and_b32_e32 v93, 0xffff0000, v97
	v_pk_mul_f32 v[156:157], v[98:99], v[98:99]
	v_and_b32_e32 v97, 0xffff0000, v96
	v_and_b32_e32 v96, 0xffff0000, v124
	v_add_f32_e32 v39, v149, v39
	v_lshlrev_b32_e32 v94, 16, v125
	v_and_b32_e32 v92, 0xffff0000, v125
	v_pk_mul_f32 v[124:125], v[96:97], v[96:97]
	v_add_f32_e32 v39, v157, v39
	v_pk_mul_f32 v[152:153], v[94:95], v[94:95]
	v_add_f32_e32 v39, v125, v39
	v_lshlrev_b32_e32 v90, 16, v126
	v_pk_mul_f32 v[154:155], v[92:93], v[92:93]
	v_add_f32_e32 v39, v153, v39
	v_pk_mul_f32 v[150:151], v[90:91], v[90:91]
	v_and_b32_e32 v88, 0xffff0000, v126
	v_add_f32_e32 v39, v155, v39
	v_lshlrev_b32_e32 v65, 16, v83
	v_and_b32_e32 v63, 0xffff0000, v83
	v_lshlrev_b32_e32 v71, 16, v86
	v_and_b32_e32 v69, 0xffff0000, v86
	v_lshlrev_b32_e32 v74, 16, v81
	v_and_b32_e32 v72, 0xffff0000, v81
	v_lshlrev_b32_e32 v83, 16, v84
	v_and_b32_e32 v81, 0xffff0000, v84
	v_lshlrev_b32_e32 v86, 16, v127
	v_and_b32_e32 v84, 0xffff0000, v127
	v_pk_mul_f32 v[126:127], v[88:89], v[88:89]
	v_add_f32_e32 v39, v151, v39
	v_pk_mul_f32 v[142:143], v[86:87], v[86:87]
	v_add_f32_e32 v39, v127, v39
	v_pk_mul_f32 v[144:145], v[84:85], v[84:85]
	v_add_f32_e32 v39, v143, v39
	v_add_f32_e32 v39, v145, v39
	v_add_f32_e32 v39, v172, v39
	v_add_f32_e32 v39, v120, v39
	v_add_f32_e32 v39, v164, v39
	v_add_f32_e32 v39, v168, v39
	v_add_f32_e32 v39, v160, v39
	v_add_f32_e32 v39, v122, v39
	v_add_f32_e32 v39, v146, v39
	v_add_f32_e32 v39, v148, v39
	v_add_f32_e32 v39, v156, v39
	v_add_f32_e32 v39, v124, v39
	v_add_f32_e32 v39, v152, v39
	v_add_f32_e32 v39, v154, v39
	v_add_f32_e32 v39, v150, v39
	v_add_f32_e32 v39, v126, v39
	v_lshlrev_b32_e32 v70, 16, v82
	v_and_b32_e32 v68, 0xffff0000, v82
	v_lshlrev_b32_e32 v82, 16, v80
	v_add_f32_e32 v39, v142, v39
	v_pk_mul_f32 v[138:139], v[82:83], v[82:83]
	v_and_b32_e32 v80, 0xffff0000, v80
	v_add_f32_e32 v39, v144, v39
	v_pk_mul_f32 v[140:141], v[80:81], v[80:81]
	v_add_f32_e32 v39, v139, v39
	v_pk_mul_f32 v[134:135], v[74:75], v[74:75]
	v_add_f32_e32 v39, v141, v39
	v_pk_mul_f32 v[136:137], v[72:73], v[72:73]
	v_add_f32_e32 v39, v135, v39
	v_pk_mul_f32 v[130:131], v[70:71], v[70:71]
	v_add_f32_e32 v39, v137, v39
	v_pk_mul_f32 v[132:133], v[68:69], v[68:69]
	v_add_f32_e32 v39, v131, v39
	v_lshlrev_b32_e32 v55, 16, v29
	v_and_b32_e32 v53, 0xffff0000, v29
	v_lshlrev_b32_e32 v57, 16, v28
	v_and_b32_e32 v59, 0xffff0000, v28
	v_pk_mul_f32 v[28:29], v[64:65], v[64:65]
	v_add_f32_e32 v39, v133, v39
	v_pk_mul_f32 v[128:129], v[62:63], v[62:63]
	v_add_f32_e32 v28, v28, v39
	v_pk_mul_f32 v[112:113], v[56:57], v[56:57]
	v_and_b32_e32 v58, 0xffff0000, v22
	v_add_f32_e32 v28, v128, v28
	v_lshlrev_b32_e32 v54, 16, v23
	v_and_b32_e32 v52, 0xffff0000, v23
	v_pk_mul_f32 v[22:23], v[58:59], v[58:59]
	v_add_f32_e32 v28, v113, v28
	v_add_f32_e32 v23, v23, v28
	v_fmac_f32_e32 v23, v55, v55
	v_lshlrev_b32_e32 v51, 16, v30
	v_fmac_f32_e32 v23, v53, v53
	v_and_b32_e32 v49, 0xffff0000, v30
	v_fmac_f32_e32 v23, v51, v51
	v_lshlrev_b32_e32 v47, 16, v31
	v_fmac_f32_e32 v23, v49, v49
	v_and_b32_e32 v45, 0xffff0000, v31
	v_fmac_f32_e32 v23, v47, v47
	v_fmac_f32_e32 v23, v45, v45
	v_add_f32_e32 v23, v138, v23
	v_add_f32_e32 v23, v140, v23
	v_add_f32_e32 v23, v134, v23
	v_add_f32_e32 v23, v136, v23
	v_add_f32_e32 v23, v130, v23
	v_add_f32_e32 v23, v132, v23
	v_add_f32_e32 v23, v29, v23
	v_add_f32_e32 v23, v129, v23
	v_mov_b32_e32 v32, v52
	v_mov_b32_e32 v33, v54
	v_add_f32_e32 v23, v112, v23
	v_lshlrev_b32_e32 v50, 16, v24
	v_and_b32_e32 v48, 0xffff0000, v24
	v_pk_mul_f32 v[32:33], v[32:33], v[32:33]
	v_add_f32_e32 v22, v22, v23
	v_mov_b32_e32 v30, v48
	v_mov_b32_e32 v31, v50
	v_add_f32_e32 v22, v33, v22
	v_lshlrev_b32_e32 v46, 16, v25
	v_and_b32_e32 v44, 0xffff0000, v25
	v_pk_mul_f32 v[30:31], v[30:31], v[30:31]
	v_add_f32_e32 v22, v32, v22
	v_mov_b32_e32 v24, v44
	v_mov_b32_e32 v25, v46
	v_add_f32_e32 v22, v31, v22
	v_pk_mul_f32 v[24:25], v[24:25], v[24:25]
	v_add_f32_e32 v22, v30, v22
	v_add_f32_e32 v22, v25, v22
	v_add_f32_e32 v30, v24, v22
	ds_bpermute_b32 v31, v1, v30
	s_waitcnt vmcnt(2)
	v_mov_b32_e32 v112, v60
	v_mov_b32_e32 v113, v100
	s_waitcnt vmcnt(1)
	v_mov_b32_e32 v120, v106
	s_waitcnt vmcnt(0)
	v_mov_b32_e32 v121, v104
	s_waitcnt lgkmcnt(0)
	v_add_f32_e32 v30, v30, v31
	v_fmamk_f32 v30, v30, 0x3c000000, v199
	v_mul_f32_e32 v31, 0x4f800000, v30
	v_cmp_gt_f32_e32 vcc, s76, v30
	v_lshl_add_u64 v[28:29], s[54:55], 0, v[36:37]
	global_load_dwordx4 v[22:25], v[18:19], off
	s_nop 0
	global_load_dwordx4 v[18:21], v[20:21], off
	v_cndmask_b32_e32 v39, v30, v31, vcc
	v_sqrt_f32_e32 v41, v39
	global_load_dwordx4 v[30:33], v[28:29], off
	s_nop 0
	global_load_dwordx4 v[26:29], v[26:27], off
	v_add_u32_e32 v60, -1, v41
	v_fma_f32 v67, -v60, v41, v39
	v_cmp_ge_f32_e64 s[0:1], 0, v67
	v_add_u32_e32 v67, 1, v41
	s_nop 0
	v_cndmask_b32_e64 v60, v41, v60, s[0:1]
	v_fma_f32 v41, -v67, v41, v39
	v_cmp_lt_f32_e64 s[0:1], 0, v41
	s_nop 1
	v_cndmask_b32_e64 v41, v60, v67, s[0:1]
	v_mul_f32_e32 v60, 0x37800000, v41
	v_cndmask_b32_e32 v41, v41, v60, vcc
	v_cmp_class_f32_e32 vcc, v39, v200
	s_nop 1
	v_cndmask_b32_e32 v39, v41, v39, vcc
	v_div_scale_f32 v41, s[0:1], v39, v39, s77
	v_rcp_f32_e32 v60, v41
	s_mov_b32 s0, -1
	v_fma_f32 v67, -v41, v60, 1.0
	v_fmac_f32_e32 v60, v67, v60
	v_div_scale_f32 v67, vcc, s77, v39, s77
	v_mul_f32_e32 v100, v67, v60
	v_fma_f32 v115, -v41, v100, v67
	v_fmac_f32_e32 v100, v115, v60
	v_fma_f32 v41, -v41, v100, v67
	v_div_fmas_f32 v41, v41, v60, v100
	v_div_fixup_f32 v60, v41, v39, s77
	v_pk_mul_f32 v[122:123], v[60:61], v[170:171] op_sel_hi:[0,1]
	v_pk_mul_f32 v[112:113], v[112:113], v[122:123]
	v_mov_b32_e32 v122, v104
	v_mov_b32_e32 v123, v106
	v_pk_mul_f32 v[122:123], v[122:123], v[112:113]
	v_pk_mul_f32 v[112:113], v[120:121], v[112:113]
	v_mov_b32_e32 v100, v61
	v_add_f32_e32 v41, v112, v113
	v_pk_mul_f32 v[112:113], v[60:61], v[116:117] op_sel_hi:[0,1]
	v_pk_mul_f32 v[100:101], v[100:101], v[112:113]
	v_mov_b32_e32 v106, v105
	v_mov_b32_e32 v104, v107
	v_pk_mul_f32 v[112:113], v[106:107], v[100:101]
	v_pk_mul_f32 v[100:101], v[104:105], v[100:101]
	v_sub_f32_e32 v39, v123, v122
	v_sub_f32_e32 v61, v113, v112
	v_add_f32_e32 v67, v100, v101
	v_cvt_pk_bf16_f32 v150, v39, v61
	v_cvt_pk_bf16_f32 v146, v41, v67
	global_load_dwordx2 v[100:101], v42, s[26:27] offset:136
	global_load_dwordx2 v[104:105], v42, s[26:27] offset:8
	global_load_dwordx2 v[106:107], v[78:79], off offset:8
	global_load_dwordx2 v[112:113], v[76:77], off offset:8
	v_pk_mul_f32 v[116:117], v[60:61], v[162:163] op_sel_hi:[0,1]
	s_waitcnt vmcnt(3)
; #define QF(d, e) __uint_as_float(((unsigned)(unsigned short)qr[d][e]) << 16)
; template <typename TQ> ...
;     ...
; #pragma unroll
;     for (int hf = 0; hf < 2; ++hf)
; #pragma unroll
;       for (int dd = 0; dd < 2; ++dd) {
;         const int dl = 4 * hf + dd, du = dl + 2;
;         const int f0 = 16 * dd + 8 * hi;
;         const float* cp = rc + (hf ? pcol : prow) * 32 + f0; const float* sp = rsn + (hf ? pcol : prow) * 32 + f0;
;         const float* gl = gq + 16 * dl + 8 * hi; const float* gu = gq + 16 * du + 8 * hi;
;         unsigned wl[4], wu[4];
; #pragma unroll
;         for (int e = 0; e < 8; e += 2) {
;           float o1[2], o2[2];
; #pragma unroll
;           for (int k = 0; k < 2; ++k) { const float x1 = QF(dl, e + k) * rn * gl[e + k], x2 = QF(du, e + k) * rn * gu[e + k]; const float c = cp[e + k], sn = sp[e + k];
;             o1[k] = x1 * c - x2 * sn; o2[k] = x2 * c + x1 * sn; }
;           wl[e >> 1] = cvtpk(o1[0], o1[1]); wu[e >> 1] = cvtpk(o2[0], o2[1]);
;         }
;         u32x4 vl = {wl[0], wl[1], wl[2], wl[3]}, vu = {wu[0], wu[1], wu[2], wu[3]};
;         qr[dl] = *reinterpret_cast<bf16x8*>(&vl); qr[du] = *reinterpret_cast<bf16x8*>(&vu);
;       }
	v_mov_b32_e32 v120, v100
	s_waitcnt vmcnt(2)
	v_mov_b32_e32 v121, v104
	v_pk_mul_f32 v[116:117], v[120:121], v[116:117]
	s_waitcnt vmcnt(1)
	v_mov_b32_e32 v120, v106
	s_waitcnt vmcnt(0)
	v_mov_b32_e32 v121, v112
	v_pk_mul_f32 v[120:121], v[120:121], v[116:117]
	v_mov_b32_e32 v104, v101
	v_sub_f32_e32 v39, v121, v120
	v_mov_b32_e32 v120, v112
	v_mov_b32_e32 v121, v106
	v_pk_mul_f32 v[116:117], v[120:121], v[116:117]
	v_mov_b32_e32 v112, v107
	v_add_f32_e32 v41, v116, v117
	v_pk_mul_f32 v[116:117], v[60:61], v[166:167] op_sel_hi:[0,1]
	v_pk_mul_f32 v[100:101], v[104:105], v[116:117]
	v_mov_b32_e32 v106, v113
	v_pk_mul_f32 v[104:105], v[112:113], v[100:101]
	v_pk_mul_f32 v[100:101], v[106:107], v[100:101]
	v_sub_f32_e32 v61, v105, v104
	v_add_f32_e32 v67, v100, v101
	v_cvt_pk_bf16_f32 v151, v39, v61
	v_cvt_pk_bf16_f32 v147, v41, v67
	global_load_dwordx2 v[100:101], v42, s[26:27] offset:144
	global_load_dwordx2 v[104:105], v42, s[26:27] offset:16
	global_load_dwordx2 v[106:107], v[78:79], off offset:16
	global_load_dwordx2 v[112:113], v[76:77], off offset:16
	v_pk_mul_f32 v[116:117], v[60:61], v[158:159] op_sel_hi:[0,1]
	v_pk_mul_f32 v[118:119], v[60:61], v[118:119] op_sel_hi:[0,1]
	s_waitcnt vmcnt(3)
	v_mov_b32_e32 v120, v100
	s_waitcnt vmcnt(2)
	v_mov_b32_e32 v121, v104
	v_mov_b32_e32 v104, v101
	s_waitcnt vmcnt(1)
	v_mov_b32_e32 v122, v106
	s_waitcnt vmcnt(0)
	v_mov_b32_e32 v123, v112
	v_mov_b32_e32 v124, v112
	v_mov_b32_e32 v125, v106
	v_mov_b32_e32 v112, v107
	v_mov_b32_e32 v106, v113
	v_pk_mul_f32 v[100:101], v[120:121], v[116:117]
	v_pk_mul_f32 v[104:105], v[104:105], v[118:119]
	v_pk_mul_f32 v[116:117], v[122:123], v[100:101]
	v_pk_mul_f32 v[100:101], v[124:125], v[100:101]
	v_pk_mul_f32 v[112:113], v[112:113], v[104:105]
	v_pk_mul_f32 v[104:105], v[106:107], v[104:105]
	v_sub_f32_e32 v39, v117, v116
	v_add_f32_e32 v41, v100, v101
	v_sub_f32_e32 v61, v113, v112
	v_add_f32_e32 v67, v104, v105
	v_cvt_pk_bf16_f32 v152, v39, v61
	v_cvt_pk_bf16_f32 v148, v41, v67
	global_load_dwordx2 v[100:101], v42, s[26:27] offset:152
	global_load_dwordx2 v[104:105], v42, s[26:27] offset:24
	global_load_dwordx2 v[106:107], v[78:79], off offset:24
	global_load_dwordx2 v[112:113], v[76:77], off offset:24
	v_pk_mul_f32 v[108:109], v[60:61], v[108:109] op_sel_hi:[0,1]
	v_pk_mul_f32 v[102:103], v[60:61], v[102:103] op_sel_hi:[0,1]
	s_waitcnt vmcnt(3)
	v_mov_b32_e32 v116, v100
	s_waitcnt vmcnt(2)
	v_mov_b32_e32 v117, v104
	v_mov_b32_e32 v104, v101
	s_waitcnt vmcnt(1)
	v_mov_b32_e32 v118, v106
	s_waitcnt vmcnt(0)
	v_mov_b32_e32 v119, v112
	v_mov_b32_e32 v120, v112
	v_mov_b32_e32 v121, v106
	v_mov_b32_e32 v112, v107
	v_mov_b32_e32 v106, v113
	v_pk_mul_f32 v[100:101], v[116:117], v[108:109]
	v_pk_mul_f32 v[102:103], v[104:105], v[102:103]
	v_pk_mul_f32 v[104:105], v[118:119], v[100:101]
	v_pk_mul_f32 v[100:101], v[120:121], v[100:101]
	v_pk_mul_f32 v[108:109], v[112:113], v[102:103]
	v_pk_mul_f32 v[102:103], v[106:107], v[102:103]
	v_sub_f32_e32 v39, v105, v104
	v_add_f32_e32 v41, v100, v101
	v_sub_f32_e32 v61, v109, v108
	v_add_f32_e32 v67, v102, v103
	v_cvt_pk_bf16_f32 v153, v39, v61
	v_cvt_pk_bf16_f32 v149, v41, v67
	global_load_dwordx2 v[100:101], v42, s[26:27] offset:192
	global_load_dwordx2 v[102:103], v42, s[26:27] offset:64
	global_load_dwordx2 v[104:105], v[78:79], off offset:64
	global_load_dwordx2 v[106:107], v[76:77], off offset:64
	v_pk_mul_f32 v[98:99], v[60:61], v[98:99] op_sel_hi:[0,1]
	v_pk_mul_f32 v[96:97], v[60:61], v[96:97] op_sel_hi:[0,1]
	s_waitcnt vmcnt(3)
	v_mov_b32_e32 v108, v100
	s_waitcnt vmcnt(2)
	v_mov_b32_e32 v109, v102
	v_mov_b32_e32 v102, v101
	s_waitcnt vmcnt(1)
	v_mov_b32_e32 v112, v104
	s_waitcnt vmcnt(0)
	v_mov_b32_e32 v113, v106
	v_mov_b32_e32 v116, v106
	v_mov_b32_e32 v117, v104
	v_mov_b32_e32 v106, v105
	v_mov_b32_e32 v104, v107
	v_pk_mul_f32 v[98:99], v[108:109], v[98:99]
	v_pk_mul_f32 v[96:97], v[102:103], v[96:97]
	v_pk_mul_f32 v[100:101], v[112:113], v[98:99]
	v_pk_mul_f32 v[98:99], v[116:117], v[98:99]
	v_pk_mul_f32 v[102:103], v[106:107], v[96:97]
	v_pk_mul_f32 v[96:97], v[104:105], v[96:97]
	v_sub_f32_e32 v39, v101, v100
	v_add_f32_e32 v41, v98, v99
	v_sub_f32_e32 v61, v103, v102
	v_add_f32_e32 v67, v96, v97
	v_cvt_pk_bf16_f32 v158, v39, v61
	v_cvt_pk_bf16_f32 v154, v41, v67
	global_load_dwordx2 v[96:97], v42, s[26:27] offset:200
	global_load_dwordx2 v[98:99], v42, s[26:27] offset:72
	global_load_dwordx2 v[100:101], v[78:79], off offset:72
	global_load_dwordx2 v[102:103], v[76:77], off offset:72
	v_pk_mul_f32 v[94:95], v[60:61], v[94:95] op_sel_hi:[0,1]
	v_pk_mul_f32 v[92:93], v[60:61], v[92:93] op_sel_hi:[0,1]
	s_waitcnt vmcnt(3)
	v_mov_b32_e32 v104, v96
	s_waitcnt vmcnt(2)
	v_mov_b32_e32 v105, v98
	v_mov_b32_e32 v98, v97
	s_waitcnt vmcnt(1)
	v_mov_b32_e32 v106, v100
	s_waitcnt vmcnt(0)
	v_mov_b32_e32 v107, v102
	v_mov_b32_e32 v108, v102
	v_mov_b32_e32 v109, v100
	v_mov_b32_e32 v102, v101
	v_mov_b32_e32 v100, v103
	v_pk_mul_f32 v[94:95], v[104:105], v[94:95]
	v_pk_mul_f32 v[92:93], v[98:99], v[92:93]
	v_pk_mul_f32 v[96:97], v[106:107], v[94:95]
	v_pk_mul_f32 v[94:95], v[108:109], v[94:95]
	v_pk_mul_f32 v[98:99], v[102:103], v[92:93]
	v_pk_mul_f32 v[92:93], v[100:101], v[92:93]
	v_sub_f32_e32 v39, v97, v96
	v_add_f32_e32 v41, v94, v95
	v_sub_f32_e32 v61, v99, v98
	v_add_f32_e32 v67, v92, v93
	v_cvt_pk_bf16_f32 v159, v39, v61
	v_cvt_pk_bf16_f32 v155, v41, v67
	global_load_dwordx2 v[92:93], v42, s[26:27] offset:208
	global_load_dwordx2 v[94:95], v42, s[26:27] offset:80
	global_load_dwordx2 v[96:97], v[78:79], off offset:80
	global_load_dwordx2 v[98:99], v[76:77], off offset:80
	v_pk_mul_f32 v[90:91], v[60:61], v[90:91] op_sel_hi:[0,1]
	v_pk_mul_f32 v[88:89], v[60:61], v[88:89] op_sel_hi:[0,1]
	s_waitcnt vmcnt(3)
; #define QF(d, e) __uint_as_float(((unsigned)(unsigned short)qr[d][e]) << 16)
; template <typename TQ> ...
;     ...
; #pragma unroll
;     for (int hf = 0; hf < 2; ++hf)
; #pragma unroll
;       for (int dd = 0; dd < 2; ++dd) {
;         const int dl = 4 * hf + dd, du = dl + 2;
;         const int f0 = 16 * dd + 8 * hi;
;         const float* cp = rc + (hf ? pcol : prow) * 32 + f0; const float* sp = rsn + (hf ? pcol : prow) * 32 + f0;
;         const float* gl = gq + 16 * dl + 8 * hi; const float* gu = gq + 16 * du + 8 * hi;
;         unsigned wl[4], wu[4];
; #pragma unroll
;         for (int e = 0; e < 8; e += 2) {
;           float o1[2], o2[2];
; #pragma unroll
;           for (int k = 0; k < 2; ++k) { const float x1 = QF(dl, e + k) * rn * gl[e + k], x2 = QF(du, e + k) * rn * gu[e + k]; const float c = cp[e + k], sn = sp[e + k];
;             o1[k] = x1 * c - x2 * sn; o2[k] = x2 * c + x1 * sn; }
;           wl[e >> 1] = cvtpk(o1[0], o1[1]); wu[e >> 1] = cvtpk(o2[0], o2[1]);
;         }
;         u32x4 vl = {wl[0], wl[1], wl[2], wl[3]}, vu = {wu[0], wu[1], wu[2], wu[3]};
;         qr[dl] = *reinterpret_cast<bf16x8*>(&vl); qr[du] = *reinterpret_cast<bf16x8*>(&vu);
;       }
	v_mov_b32_e32 v100, v92
	s_waitcnt vmcnt(2)
	v_mov_b32_e32 v101, v94
	v_mov_b32_e32 v94, v93
	s_waitcnt vmcnt(1)
	v_mov_b32_e32 v102, v96
	s_waitcnt vmcnt(0)
	v_mov_b32_e32 v103, v98
	v_mov_b32_e32 v104, v98
	v_mov_b32_e32 v105, v96
	v_mov_b32_e32 v98, v97
	v_mov_b32_e32 v96, v99
	v_pk_mul_f32 v[90:91], v[90:91], v[100:101]
	v_pk_mul_f32 v[88:89], v[88:89], v[94:95]
	v_pk_mul_f32 v[92:93], v[90:91], v[102:103]
	v_pk_mul_f32 v[90:91], v[90:91], v[104:105]
	v_pk_mul_f32 v[94:95], v[88:89], v[98:99]
	v_pk_mul_f32 v[88:89], v[88:89], v[96:97]
	v_sub_f32_e32 v39, v93, v92
	v_add_f32_e32 v41, v90, v91
	v_sub_f32_e32 v61, v95, v94
	v_add_f32_e32 v67, v88, v89
	v_cvt_pk_bf16_f32 v160, v39, v61
	v_cvt_pk_bf16_f32 v156, v41, v67
	global_load_dwordx2 v[88:89], v42, s[26:27] offset:216
	global_load_dwordx2 v[90:91], v42, s[26:27] offset:88
	s_nop 0
	global_load_dwordx2 v[78:79], v[78:79], off offset:88
	s_nop 0
	global_load_dwordx2 v[76:77], v[76:77], off offset:88
	v_lshlrev_b32_e32 v39, 7, v66
	v_mov_b32_e32 v67, v195
	v_and_b32_e32 v66, 0x1f80, v39
	v_lshl_add_u64 v[92:93], s[4:5], 0, v[66:67]
	v_lshl_add_u64 v[94:95], s[6:7], 0, v[66:67]
	v_lshl_add_u64 v[66:67], v[92:93], 0, v[42:43]
	v_pk_mul_f32 v[84:85], v[60:61], v[84:85] op_sel_hi:[0,1]
	v_pk_mul_f32 v[86:87], v[60:61], v[86:87] op_sel_hi:[0,1]
	s_waitcnt vmcnt(3)
	v_mov_b32_e32 v92, v88
	s_waitcnt vmcnt(2)
	v_mov_b32_e32 v93, v90
	v_mov_b32_e32 v90, v89
	s_waitcnt vmcnt(1)
	v_mov_b32_e32 v96, v78
	s_waitcnt vmcnt(0)
	v_mov_b32_e32 v97, v76
	v_mov_b32_e32 v98, v76
	v_mov_b32_e32 v99, v78
	v_mov_b32_e32 v76, v79
	v_mov_b32_e32 v78, v77
	v_pk_mul_f32 v[84:85], v[84:85], v[90:91]
	v_pk_mul_f32 v[86:87], v[86:87], v[92:93]
	v_pk_mul_f32 v[76:77], v[84:85], v[76:77]
	v_pk_mul_f32 v[78:79], v[84:85], v[78:79]
	v_pk_mul_f32 v[88:89], v[86:87], v[96:97]
	v_pk_mul_f32 v[86:87], v[86:87], v[98:99]
	v_sub_f32_e32 v61, v77, v76
	v_add_f32_e32 v76, v78, v79
	v_sub_f32_e32 v39, v89, v88
	v_add_f32_e32 v41, v86, v87
	v_cvt_pk_bf16_f32 v161, v39, v61
	v_cvt_pk_bf16_f32 v157, v41, v76
	global_load_dwordx2 v[78:79], v42, s[26:27] offset:256
	global_load_dwordx2 v[84:85], v42, s[26:27] offset:384
	v_lshl_add_u64 v[76:77], v[94:95], 0, v[42:43]
	global_load_dwordx2 v[86:87], v[76:77], off
	global_load_dwordx2 v[88:89], v[66:67], off
	v_pk_mul_f32 v[82:83], v[60:61], v[82:83] op_sel_hi:[0,1]
	v_pk_mul_f32 v[80:81], v[60:61], v[80:81] op_sel_hi:[0,1]
	s_waitcnt vmcnt(3)
	v_mov_b32_e32 v91, v78
	s_waitcnt vmcnt(2)
	v_mov_b32_e32 v90, v84
	v_mov_b32_e32 v78, v85
	s_waitcnt vmcnt(1)
	v_mov_b32_e32 v92, v86
	s_waitcnt vmcnt(0)
	v_mov_b32_e32 v93, v88
	v_mov_b32_e32 v94, v88
	v_mov_b32_e32 v95, v86
	v_mov_b32_e32 v88, v87
	v_mov_b32_e32 v86, v89
	v_pk_mul_f32 v[82:83], v[82:83], v[90:91]
	v_pk_mul_f32 v[78:79], v[80:81], v[78:79]
	v_pk_mul_f32 v[80:81], v[82:83], v[92:93]
	v_pk_mul_f32 v[82:83], v[82:83], v[94:95]
	v_pk_mul_f32 v[84:85], v[78:79], v[88:89]
	v_pk_mul_f32 v[78:79], v[78:79], v[86:87]
	v_sub_f32_e32 v39, v81, v80
	v_add_f32_e32 v41, v82, v83
	v_sub_f32_e32 v43, v85, v84
	v_add_f32_e32 v61, v78, v79
	v_cvt_pk_bf16_f32 v166, v39, v43
	v_cvt_pk_bf16_f32 v162, v41, v61
	global_load_dwordx2 v[78:79], v42, s[26:27] offset:392
	global_load_dwordx2 v[80:81], v42, s[26:27] offset:264
	global_load_dwordx2 v[82:83], v[76:77], off offset:8
	global_load_dwordx2 v[84:85], v[66:67], off offset:8
	v_pk_mul_f32 v[74:75], v[60:61], v[74:75] op_sel_hi:[0,1]
	v_pk_mul_f32 v[72:73], v[60:61], v[72:73] op_sel_hi:[0,1]
	s_waitcnt vmcnt(3)
	v_mov_b32_e32 v86, v78
	s_waitcnt vmcnt(2)
	v_mov_b32_e32 v87, v80
	v_mov_b32_e32 v80, v79
	s_waitcnt vmcnt(1)
	v_mov_b32_e32 v88, v82
	s_waitcnt vmcnt(0)
	v_mov_b32_e32 v89, v84
	v_mov_b32_e32 v90, v84
	v_mov_b32_e32 v91, v82
	v_mov_b32_e32 v84, v83
	v_mov_b32_e32 v82, v85
	v_pk_mul_f32 v[74:75], v[74:75], v[86:87]
	v_pk_mul_f32 v[72:73], v[72:73], v[80:81]
	v_pk_mul_f32 v[78:79], v[74:75], v[88:89]
	v_pk_mul_f32 v[74:75], v[74:75], v[90:91]
	v_pk_mul_f32 v[80:81], v[72:73], v[84:85]
	v_pk_mul_f32 v[72:73], v[72:73], v[82:83]
	v_sub_f32_e32 v39, v79, v78
	v_add_f32_e32 v41, v74, v75
	v_sub_f32_e32 v43, v81, v80
	v_add_f32_e32 v61, v72, v73
	v_cvt_pk_bf16_f32 v167, v39, v43
	v_cvt_pk_bf16_f32 v163, v41, v61
	global_load_dwordx2 v[72:73], v42, s[26:27] offset:400
	global_load_dwordx2 v[74:75], v42, s[26:27] offset:272
	global_load_dwordx2 v[78:79], v[76:77], off offset:16
	global_load_dwordx2 v[80:81], v[66:67], off offset:16
	v_pk_mul_f32 v[70:71], v[60:61], v[70:71] op_sel_hi:[0,1]
	v_pk_mul_f32 v[68:69], v[60:61], v[68:69] op_sel_hi:[0,1]
	s_waitcnt vmcnt(3)
	v_mov_b32_e32 v82, v72
	s_waitcnt vmcnt(2)
	v_mov_b32_e32 v83, v74
	v_mov_b32_e32 v74, v73
	s_waitcnt vmcnt(1)
	v_mov_b32_e32 v84, v78
	s_waitcnt vmcnt(0)
	v_mov_b32_e32 v85, v80
	v_mov_b32_e32 v86, v80
	v_mov_b32_e32 v87, v78
	v_mov_b32_e32 v80, v79
	v_mov_b32_e32 v78, v81
	v_pk_mul_f32 v[70:71], v[70:71], v[82:83]
	v_pk_mul_f32 v[68:69], v[68:69], v[74:75]
	v_pk_mul_f32 v[72:73], v[70:71], v[84:85]
	v_pk_mul_f32 v[70:71], v[70:71], v[86:87]
	v_pk_mul_f32 v[74:75], v[68:69], v[80:81]
	v_pk_mul_f32 v[68:69], v[68:69], v[78:79]
	v_sub_f32_e32 v39, v73, v72
	v_add_f32_e32 v41, v70, v71
	v_sub_f32_e32 v43, v75, v74
	v_add_f32_e32 v61, v68, v69
	v_cvt_pk_bf16_f32 v168, v39, v43
	v_cvt_pk_bf16_f32 v164, v41, v61
	global_load_dwordx2 v[68:69], v42, s[26:27] offset:280
	global_load_dwordx2 v[70:71], v42, s[26:27] offset:408
	global_load_dwordx2 v[72:73], v[66:67], off offset:24
	global_load_dwordx2 v[74:75], v[76:77], off offset:24
	v_pk_mul_f32 v[64:65], v[60:61], v[64:65] op_sel_hi:[0,1]
	v_pk_mul_f32 v[62:63], v[60:61], v[62:63] op_sel_hi:[0,1]
	s_waitcnt vmcnt(3)
; #define SBAR() __builtin_amdgcn_sched_barrier(0)
; #define QF(d, e) __uint_as_float(((unsigned)(unsigned short)qr[d][e]) << 16)
; template <typename TQ> ...
;     ...
; #pragma unroll
;     for (int hf = 0; hf < 2; ++hf)
; #pragma unroll
;       for (int dd = 0; dd < 2; ++dd) {
;         const int dl = 4 * hf + dd, du = dl + 2;
;         const int f0 = 16 * dd + 8 * hi;
;         const float* cp = rc + (hf ? pcol : prow) * 32 + f0; const float* sp = rsn + (hf ? pcol : prow) * 32 + f0;
;         const float* gl = gq + 16 * dl + 8 * hi; const float* gu = gq + 16 * du + 8 * hi;
;         unsigned wl[4], wu[4];
; #pragma unroll
;         for (int e = 0; e < 8; e += 2) {
;           float o1[2], o2[2];
; #pragma unroll
;           for (int k = 0; k < 2; ++k) { const float x1 = QF(dl, e + k) * rn * gl[e + k], x2 = QF(du, e + k) * rn * gu[e + k]; const float c = cp[e + k], sn = sp[e + k];
;             o1[k] = x1 * c - x2 * sn; o2[k] = x2 * c + x1 * sn; }
;           wl[e >> 1] = cvtpk(o1[0], o1[1]); wu[e >> 1] = cvtpk(o2[0], o2[1]);
;         }
;         u32x4 vl = {wl[0], wl[1], wl[2], wl[3]}, vu = {wu[0], wu[1], wu[2], wu[3]};
;         qr[dl] = *reinterpret_cast<bf16x8*>(&vl); qr[du] = *reinterpret_cast<bf16x8*>(&vu);
;       }
;   }
;     ...
;   SBAR();
;   f32x16 pA0, pA1, pB0, pB1; bf16x8 pa0, pa1, pa2, pa3; const int NT = seq / KVBLK;
;   f32x16 negm;
; #pragma unroll
;   for (int r = 0; r < 16; ++r) negm[r] = -mC;
;   asm volatile("" : "+v"(negm));
;   asm volatile("s_waitcnt vmcnt(0)" ::: "memory"); SWRITE(0, SE); __syncthreads();
	v_mov_b32_e32 v78, v68
	s_waitcnt vmcnt(2)
	v_mov_b32_e32 v79, v70
	v_mov_b32_e32 v70, v69
	s_waitcnt vmcnt(1)
	v_mov_b32_e32 v80, v72
	s_waitcnt vmcnt(0)
	v_mov_b32_e32 v81, v74
	v_mov_b32_e32 v82, v74
	v_mov_b32_e32 v83, v72
	v_mov_b32_e32 v74, v73
	v_mov_b32_e32 v72, v75
	v_pk_mul_f32 v[64:65], v[64:65], v[78:79]
	v_pk_mul_f32 v[62:63], v[62:63], v[70:71]
	v_pk_mul_f32 v[68:69], v[64:65], v[80:81]
	v_pk_mul_f32 v[64:65], v[64:65], v[82:83]
	v_pk_mul_f32 v[70:71], v[62:63], v[74:75]
	v_pk_mul_f32 v[62:63], v[62:63], v[72:73]
	v_sub_f32_e32 v39, v68, v69
	v_add_f32_e32 v41, v65, v64
	v_sub_f32_e32 v43, v70, v71
	v_add_f32_e32 v61, v63, v62
	v_cvt_pk_bf16_f32 v169, v39, v43
	v_cvt_pk_bf16_f32 v165, v41, v61
	global_load_dwordx2 v[62:63], v42, s[26:27] offset:448
	global_load_dwordx2 v[64:65], v42, s[26:27] offset:320
	global_load_dwordx2 v[68:69], v[76:77], off offset:64
	global_load_dwordx2 v[70:71], v[66:67], off offset:64
	v_pk_mul_f32 v[56:57], v[60:61], v[56:57] op_sel_hi:[0,1]
	v_pk_mul_f32 v[58:59], v[60:61], v[58:59] op_sel_hi:[0,1]
	v_pk_mul_f32 v[52:53], v[60:61], v[52:53] op_sel_hi:[0,1]
	v_pk_mul_f32 v[54:55], v[60:61], v[54:55] op_sel_hi:[0,1]
	v_pk_mul_f32 v[48:49], v[60:61], v[48:49] op_sel_hi:[0,1]
	v_pk_mul_f32 v[50:51], v[60:61], v[50:51] op_sel_hi:[0,1]
	s_waitcnt vmcnt(3)
	v_mov_b32_e32 v72, v62
	s_waitcnt vmcnt(2)
	v_mov_b32_e32 v73, v64
	v_mov_b32_e32 v64, v63
	s_waitcnt vmcnt(1)
	v_mov_b32_e32 v74, v68
	s_waitcnt vmcnt(0)
	v_mov_b32_e32 v75, v70
	v_mov_b32_e32 v78, v70
	v_mov_b32_e32 v79, v68
	v_mov_b32_e32 v70, v69
	v_mov_b32_e32 v68, v71
	v_pk_mul_f32 v[56:57], v[56:57], v[72:73]
	v_pk_mul_f32 v[58:59], v[58:59], v[64:65]
	v_pk_mul_f32 v[62:63], v[56:57], v[74:75]
	v_pk_mul_f32 v[56:57], v[56:57], v[78:79]
	v_pk_mul_f32 v[64:65], v[58:59], v[70:71]
	v_pk_mul_f32 v[58:59], v[58:59], v[68:69]
	v_add_f32_e32 v41, v56, v57
	v_add_f32_e32 v56, v58, v59
	v_sub_f32_e32 v39, v63, v62
	v_sub_f32_e32 v43, v65, v64
	v_cvt_pk_bf16_f32 v174, v39, v43
	v_cvt_pk_bf16_f32 v170, v41, v56
	global_load_dwordx2 v[56:57], v42, s[26:27] offset:456
	global_load_dwordx2 v[58:59], v42, s[26:27] offset:328
	global_load_dwordx2 v[62:63], v[76:77], off offset:72
	global_load_dwordx2 v[64:65], v[66:67], off offset:72
	s_waitcnt vmcnt(3)
	v_mov_b32_e32 v68, v56
	s_waitcnt vmcnt(2)
	v_mov_b32_e32 v69, v58
	v_mov_b32_e32 v58, v57
	s_waitcnt vmcnt(1)
	v_mov_b32_e32 v70, v62
	s_waitcnt vmcnt(0)
	v_mov_b32_e32 v71, v64
	v_mov_b32_e32 v72, v64
	v_mov_b32_e32 v73, v62
	v_mov_b32_e32 v64, v63
	v_mov_b32_e32 v62, v65
	v_pk_mul_f32 v[52:53], v[52:53], v[58:59]
	v_pk_mul_f32 v[54:55], v[54:55], v[68:69]
	v_pk_mul_f32 v[58:59], v[52:53], v[64:65]
	v_pk_mul_f32 v[52:53], v[52:53], v[62:63]
	v_pk_mul_f32 v[56:57], v[54:55], v[70:71]
	v_pk_mul_f32 v[54:55], v[54:55], v[72:73]
	v_add_f32_e32 v52, v52, v53
	v_sub_f32_e32 v39, v57, v56
	v_add_f32_e32 v41, v54, v55
	v_sub_f32_e32 v43, v59, v58
	v_cvt_pk_bf16_f32 v175, v39, v43
	v_cvt_pk_bf16_f32 v171, v41, v52
	global_load_dwordx2 v[52:53], v42, s[26:27] offset:464
	global_load_dwordx2 v[54:55], v42, s[26:27] offset:336
	global_load_dwordx2 v[56:57], v[76:77], off offset:80
	global_load_dwordx2 v[58:59], v[66:67], off offset:80
	s_waitcnt vmcnt(3)
	v_mov_b32_e32 v62, v52
	s_waitcnt vmcnt(2)
	v_mov_b32_e32 v63, v54
	v_mov_b32_e32 v54, v53
	s_waitcnt vmcnt(1)
	v_mov_b32_e32 v64, v56
	s_waitcnt vmcnt(0)
	v_mov_b32_e32 v65, v58
	v_mov_b32_e32 v68, v58
	v_mov_b32_e32 v69, v56
	v_mov_b32_e32 v58, v57
	v_mov_b32_e32 v56, v59
	v_pk_mul_f32 v[48:49], v[48:49], v[54:55]
	v_pk_mul_f32 v[50:51], v[50:51], v[62:63]
	v_pk_mul_f32 v[54:55], v[48:49], v[58:59]
	v_pk_mul_f32 v[48:49], v[48:49], v[56:57]
	v_pk_mul_f32 v[52:53], v[50:51], v[64:65]
	v_pk_mul_f32 v[50:51], v[50:51], v[68:69]
	v_sub_f32_e32 v43, v55, v54
	v_add_f32_e32 v48, v48, v49
	v_sub_f32_e32 v39, v53, v52
	v_add_f32_e32 v41, v50, v51
	v_cvt_pk_bf16_f32 v176, v39, v43
	v_cvt_pk_bf16_f32 v172, v41, v48
	global_load_dwordx2 v[48:49], v42, s[26:27] offset:472
	s_nop 0
	global_load_dwordx2 v[42:43], v42, s[26:27] offset:344
	s_nop 0
	global_load_dwordx2 v[50:51], v[76:77], off offset:88
	global_load_dwordx2 v[52:53], v[66:67], off offset:88
	v_and_b32_e32 v54, 0xfffff0, v38
	v_lshlrev_b32_e32 v55, 1, v38
	v_lshrrev_b32_e32 v56, 1, v38
	v_and_b32_e32 v58, 3, v38
	v_lshlrev_b32_e32 v39, 4, v114
	v_and_or_b32 v54, v55, 8, v54
	v_and_or_b32 v55, v56, 4, v58
	v_and_b32_e32 v56, 0xfffff0, v40
	v_lshlrev_b32_e32 v58, 1, v40
	v_lshlrev_b32_e32 v41, 1, v114
	v_bfe_u32 v57, v111, 5, 2
	v_lshlrev_b32_e32 v59, 3, v203
	v_and_b32_e32 v61, 0xc0, v39
	v_lshrrev_b32_e32 v54, 1, v54
	v_lshlrev_b32_e32 v62, 6, v55
	v_and_or_b32 v55, v58, 8, v56
	v_and_b32_e32 v41, 32, v41
	v_and_or_b32 v61, v59, 24, v61
	v_and_b32_e32 v59, 0x100, v59
	v_or_b32_e32 v54, v54, v57
	v_lshrrev_b32_e32 v55, 1, v55
	v_or3_b32 v76, v61, v41, v59
	v_lshlrev_b32_e32 v61, 9, v54
	v_or_b32_e32 v54, v55, v57
	v_and_b32_e32 v41, 48, v110
	v_lshlrev_b32_e32 v54, 9, v54
	v_or3_b32 v63, v54, v62, v41
	v_pk_mul_f32 v[46:47], v[60:61], v[46:47] op_sel_hi:[0,1]
	v_pk_mul_f32 v[44:45], v[60:61], v[44:45] op_sel_hi:[0,1]
	v_or3_b32 v41, v61, v62, v41
	s_waitcnt vmcnt(3)
	v_mov_b32_e32 v54, v48
	s_waitcnt vmcnt(2)
	v_mov_b32_e32 v55, v42
	v_mov_b32_e32 v42, v49
	s_waitcnt vmcnt(1)
	v_mov_b32_e32 v56, v50
	s_waitcnt vmcnt(0)
	v_mov_b32_e32 v57, v52
	v_mov_b32_e32 v58, v52
	v_mov_b32_e32 v59, v50
	v_mov_b32_e32 v52, v51
	v_mov_b32_e32 v50, v53
	v_pk_mul_f32 v[46:47], v[46:47], v[54:55]
	v_pk_mul_f32 v[42:43], v[44:45], v[42:43]
	v_pk_mul_f32 v[44:45], v[46:47], v[56:57]
	v_pk_mul_f32 v[46:47], v[46:47], v[58:59]
	v_pk_mul_f32 v[48:49], v[42:43], v[52:53]
	v_pk_mul_f32 v[42:43], v[42:43], v[50:51]
	v_sub_f32_e32 v44, v45, v44
	v_add_f32_e32 v45, v46, v47
	v_sub_f32_e32 v46, v49, v48
	v_add_f32_e32 v42, v42, v43
	v_cvt_pk_bf16_f32 v177, v44, v46
	v_cvt_pk_bf16_f32 v173, v45, v42
	v_mov_b64_e32 v[96:97], v[16:17]
	v_mov_b64_e32 v[94:95], v[14:15]
	v_mov_b64_e32 v[92:93], v[12:13]
	v_mov_b64_e32 v[90:91], v[10:11]
	v_mov_b64_e32 v[88:89], v[8:9]
	v_mov_b64_e32 v[86:87], v[6:7]
	v_mov_b64_e32 v[84:85], v[4:5]
	v_mov_b64_e32 v[82:83], v[2:3]
	v_add_u32_e32 v207, 0, v41
	v_add_u32_e32 v208, 0, v63
	s_waitcnt vmcnt(0)
	ds_write_b128 v207, v[22:25]
	ds_write_b128 v208, v[18:21]
	v_lshlrev_b32_e32 v18, 8, v38
	v_and_b32_e32 v19, 0x70, v114
	v_bitop3_b32 v18, v110, v18, v19 bitop3:0xde
	v_add_u32_e32 v209, 0x10000, v18
	v_lshlrev_b32_e32 v18, 8, v40
	v_bitop3_b32 v18, v110, v18, v19 bitop3:0xde
	v_lshlrev_b32_e32 v56, 8, v202
	v_and_b32_e32 v57, 0x70, v39
	v_add_u32_e32 v211, 0x10000, v18
	v_bitop3_b32 v18, v194, v56, v57 bitop3:0xde
	v_add_u32_e32 v210, 0x10000, v18
	ds_write_b128 v209, v[30:33] offset:0
	ds_write_b128 v211, v[26:29] offset:0
	s_waitcnt lgkmcnt(0)
	s_barrier
; #define SLOAD(i, k0) do { sr_[i].vs0 = St::ld8(&Vh[(long)((k0) + sr) * LDK + sc]); sr_[i].vs1 = St::ld8(&Vh[(long)((k0) + 32 + sr) * LDK + sc]); \
;     sr_[i].ks0 = St::ld8(&Kh[(long)((k0) + sr) * LDK + sc]); sr_[i].ks1 = St::ld8(&Kh[(long)((k0) + 32 + sr) * LDK + sc]); } while (0)
; #define SWAIT() do { if constexpr (SDEPTH == 2) asm volatile("s_waitcnt vmcnt(4)" ::: "memory"); else asm volatile("s_waitcnt vmcnt(0)" ::: "memory"); } while (0)
; __device__ __forceinline__ void qkt(f32x16& p0, f32x16& p1, const bf16* Ks, const bf16x8* qr, int r32, int hi, const f32x16& negm) {
; #pragma unroll
;   for (int d0 = 0; d0 < 8; ++d0) { int cb = (d0 * 16 + hi * 8) * 2;
;     bf16x8 b0 = *reinterpret_cast<const bf16x8*>((const char*)Ks + KSWZ(r32, cb));
;     bf16x8 b1 = *reinterpret_cast<const bf16x8*>((const char*)Ks + KSWZ(32 + r32, cb));
;     if (d0 == 0) { p0 = __builtin_amdgcn_mfma_f32_32x32x16_bf16(b0, qr[0], negm, 0, 0, 0); p1 = __builtin_amdgcn_mfma_f32_32x32x16_bf16(b1, qr[0], negm, 0, 0, 0); }
;     else { p0 = __builtin_amdgcn_mfma_f32_32x32x16_bf16(b0, qr[d0], p0, 0, 0, 0); p1 = __builtin_amdgcn_mfma_f32_32x32x16_bf16(b1, qr[d0], p1, 0, 0, 0); } }
; }
; template <typename TQ> ...
;     ...
;   f32x16 pA0, pA1, pB0, pB1; bf16x8 pa0, pa1, pa2, pa3; const int NT = seq / KVBLK;
;   f32x16 negm;
; #pragma unroll
;   for (int r = 0; r < 16; ++r) negm[r] = -mC;
;   asm volatile("" : "+v"(negm));
;   asm volatile("s_waitcnt vmcnt(0)" ::: "memory"); SWRITE(0, SE); __syncthreads();
;   qkt(pA0, pA1, K_lds, qr, r32, hi, negm); partialSM(pA0, pA1, mC);
;   SLOAD(SO, KVBLK); if constexpr (SDEPTH == 2) { if (2 < NT) SLOAD(SE, 2 * KVBLK); }
;   SWAIT(); SWRITE(1, SO); __syncthreads();
	ds_read_b128 v[38:41], v210 offset:0
	s_waitcnt lgkmcnt(0)
	v_mfma_f32_32x32x16_bf16 v[18:33], v[38:41], v[150:153], v[82:97]
	ds_read_b128 v[38:41], v210 offset:8192
	v_or_b32_e32 v52, 0x80, v194
	v_lshl_add_u64 v[44:45], v[36:37], 0, s[10:11]
	v_lshl_add_u64 v[46:47], v[36:37], 0, s[24:25]
	v_bitop3_b32 v52, v52, v56, v57 bitop3:0xde
	v_lshl_add_u64 v[42:43], s[64:65], 0, v[44:45]
	v_lshl_add_u64 v[44:45], s[54:55], 0, v[44:45]
	s_waitcnt lgkmcnt(0)
	v_mfma_f32_32x32x16_bf16 v[98:113], v[38:41], v[150:153], v[82:97]
	v_or_b32_e32 v38, 32, v194
	v_bitop3_b32 v38, v38, v56, v57 bitop3:0xde
	v_add_u32_e32 v212, 0x10000, v38
	ds_read_b128 v[38:41], v212 offset:0
	v_lshl_add_u64 v[48:49], s[54:55], 0, v[46:47]
	v_add_u32_e32 v218, 0x10000, v52
	v_or_b32_e32 v58, 0xe0, v194
	s_waitcnt lgkmcnt(0)
	v_mfma_f32_32x32x16_bf16 v[18:33], v[38:41], v[158:161], v[18:33]
	ds_read_b128 v[38:41], v212 offset:8192
	s_cmp_lg_u32 0, -1
	s_cselect_b32 s1, 0, 0
	v_add_u32_e32 v206, s1, v76
	s_addk_i32 s1, 0x4000
	v_add_u32_e32 v204, s1, v76
	v_mov_b32_e32 v76, v205
	s_waitcnt lgkmcnt(0)
	v_mfma_f32_32x32x16_bf16 v[98:113], v[38:41], v[158:161], v[98:113]
	v_or_b32_e32 v38, 64, v194
	v_bitop3_b32 v38, v38, v56, v57 bitop3:0xde
	v_add_u32_e32 v213, 0x10000, v38
	ds_read_b128 v[38:41], v213 offset:0
	v_mov_b32_e32 v77, v205
	v_mov_b32_e32 v78, v205
	v_mov_b32_e32 v79, v205
	s_waitcnt lgkmcnt(0)
	v_mfma_f32_32x32x16_bf16 v[18:33], v[38:41], v[146:149], v[18:33]
	v_or_b32_e32 v38, 0x60, v194
	v_bitop3_b32 v38, v38, v56, v57 bitop3:0xde
	v_add_u32_e32 v214, 0x10000, v38
	ds_read_b128 v[38:41], v214 offset:0
	v_mov_b32_e32 v80, v205
	v_mov_b32_e32 v81, v205
	s_waitcnt lgkmcnt(0)
	v_mfma_f32_32x32x16_bf16 v[18:33], v[38:41], v[154:157], v[18:33]
	v_lshl_add_u64 v[40:41], s[64:65], 0, v[46:47]
	global_load_dwordx4 v[36:39], v[42:43], off
	s_nop 0
	global_load_dwordx4 v[40:43], v[40:41], off
	s_nop 0
	global_load_dwordx4 v[44:47], v[44:45], off
	s_nop 0
	global_load_dwordx4 v[48:51], v[48:49], off
	ds_read_b128 v[52:55], v218 offset:0
	s_waitcnt lgkmcnt(0)
	v_mfma_f32_32x32x16_bf16 v[18:33], v[52:55], v[166:169], v[18:33]
	v_or_b32_e32 v52, 0xa0, v194
	v_bitop3_b32 v52, v52, v56, v57 bitop3:0xde
	v_add_u32_e32 v217, 0x10000, v52
	ds_read_b128 v[52:55], v217 offset:0
	s_waitcnt lgkmcnt(0)
	v_mfma_f32_32x32x16_bf16 v[18:33], v[52:55], v[174:177], v[18:33]
	v_or_b32_e32 v52, 0xc0, v194
	v_bitop3_b32 v52, v52, v56, v57 bitop3:0xde
	v_add_u32_e32 v216, 0x10000, v52
	ds_read_b128 v[52:55], v216 offset:0
	v_bitop3_b32 v56, v58, v56, v57 bitop3:0xde
	v_add_u32_e32 v215, 0x10000, v56
	s_waitcnt lgkmcnt(0)
	v_mfma_f32_32x32x16_bf16 v[18:33], v[52:55], v[162:165], v[18:33]
	ds_read_b128 v[52:55], v215 offset:0
	ds_read_b128 v[56:59], v213 offset:8192
	ds_read_b128 v[60:63], v214 offset:8192
	ds_read_b128 v[64:67], v218 offset:8192
	ds_read_b128 v[68:71], v217 offset:8192
	ds_read_b128 v[72:75], v216 offset:8192
	s_waitcnt lgkmcnt(4)
	v_mfma_f32_32x32x16_bf16 v[98:113], v[56:59], v[146:149], v[98:113]
	v_mov_b32_e32 v56, v205
	v_mov_b32_e32 v57, v205
	v_mov_b32_e32 v58, v205
	v_mov_b32_e32 v59, v205
	s_waitcnt lgkmcnt(3)
	v_mfma_f32_32x32x16_bf16 v[98:113], v[60:63], v[154:157], v[98:113]
	v_mov_b32_e32 v60, v205
	v_mov_b32_e32 v61, v205
	v_mov_b32_e32 v62, v205
	v_mov_b32_e32 v63, v205
	s_waitcnt lgkmcnt(2)
	v_mfma_f32_32x32x16_bf16 v[98:113], v[64:67], v[166:169], v[98:113]
	v_mov_b32_e32 v64, v205
	v_mov_b32_e32 v65, v205
	v_mov_b32_e32 v66, 0
	v_mov_b32_e32 v67, v205
	s_waitcnt lgkmcnt(1)
	v_mfma_f32_32x32x16_bf16 v[98:113], v[68:71], v[174:177], v[98:113]
	v_mov_b32_e32 v68, v205
	v_mov_b32_e32 v69, v205
	v_mov_b32_e32 v70, v205
	v_mov_b32_e32 v71, v205
	v_mfma_f32_32x32x16_bf16 v[18:33], v[52:55], v[170:173], v[18:33]
	ds_read_b128 v[52:55], v215 offset:8192
	s_waitcnt vmcnt(0)
	s_waitcnt vmcnt(3)
	ds_write_b128 v207, v[36:39] offset:16384
	s_waitcnt vmcnt(2)
	ds_write_b128 v208, v[40:43] offset:16384
	s_waitcnt vmcnt(1)
	ds_write_b128 v209, v[44:47] offset:16384
	s_waitcnt vmcnt(0)
	ds_write_b128 v211, v[48:51] offset:16384
	v_mov_b32_e32 v36, v205
	v_mov_b32_e32 v37, v205
	v_mov_b32_e32 v38, v205
	s_waitcnt lgkmcnt(5)
	v_mfma_f32_32x32x16_bf16 v[98:113], v[72:75], v[162:165], v[98:113]
	v_exp_f32_e32 v232, v18
	v_exp_f32_e32 v234, v19
	v_exp_f32_e32 v230, v20
	v_exp_f32_e32 v233, v21
	v_exp_f32_e32 v229, v22
	v_exp_f32_e32 v231, v23
	v_exp_f32_e32 v227, v24
	s_waitcnt lgkmcnt(4)
	v_mfma_f32_32x32x16_bf16 v[98:113], v[52:55], v[170:173], v[98:113]
	v_exp_f32_e32 v228, v25
	v_exp_f32_e32 v224, v26
	v_exp_f32_e32 v226, v27
	v_exp_f32_e32 v223, v28
	v_exp_f32_e32 v225, v29
	v_exp_f32_e32 v220, v30
	v_exp_f32_e32 v222, v31
	v_exp_f32_e32 v219, v32
	v_exp_f32_e32 v221, v33
	v_and_b32_e32 v20, 15, v114
	v_mad_i64_i32 v[18:19], s[12:13], s96, v201, v[34:35]
	v_lshlrev_b32_e32 v20, 4, v20
	v_or3_b32 v18, v18, s95, v20
	v_lshl_add_u64 v[196:197], s[8:9], 0, v[18:19]
	v_mov_b32_e32 v18, 0
	v_mov_b32_e32 v19, v205
	v_mov_b32_e32 v20, v205
	v_mov_b32_e32 v21, v205
	v_mov_b32_e32 v22, v205
	v_mov_b32_e32 v23, v205
	v_mov_b32_e32 v24, v205
	v_mov_b32_e32 v25, v205
	v_mov_b32_e32 v26, v205
	v_mov_b32_e32 v27, v205
	v_mov_b32_e32 v28, v205
	v_mov_b32_e32 v29, v205
	v_mov_b32_e32 v30, v205
	v_mov_b32_e32 v31, v205
	v_mov_b32_e32 v32, v205
	v_mov_b32_e32 v33, v205
	v_mov_b32_e32 v34, 0
	v_mov_b32_e32 v35, v205
	v_mov_b32_e32 v39, v205
	v_mov_b32_e32 v40, v205
	v_mov_b32_e32 v41, v205
	v_mov_b32_e32 v42, v205
	v_mov_b32_e32 v43, v205
	v_mov_b32_e32 v44, v205
	v_mov_b32_e32 v45, v205
	v_mov_b32_e32 v46, v205
	v_mov_b32_e32 v47, v205
	v_mov_b32_e32 v48, v205
	v_mov_b32_e32 v49, v205
	v_mov_b32_e32 v50, 0
	v_mov_b32_e32 v51, v205
	v_mov_b32_e32 v52, v205
	v_mov_b32_e32 v53, v205
	v_mov_b32_e32 v54, v205
	v_mov_b32_e32 v55, v205
	v_mov_b32_e32 v72, v205
	v_mov_b32_e32 v73, v205
	v_mov_b32_e32 v74, v205
	v_mov_b32_e32 v75, v205
	s_waitcnt lgkmcnt(0)
	s_barrier
; #define SBAR() __builtin_amdgcn_sched_barrier(0)
; #define SLOAD(i, k0) do { sr_[i].vs0 = St::ld8(&Vh[(long)((k0) + sr) * LDK + sc]); sr_[i].vs1 = St::ld8(&Vh[(long)((k0) + 32 + sr) * LDK + sc]); \
;     sr_[i].ks0 = St::ld8(&Kh[(long)((k0) + sr) * LDK + sc]); sr_[i].ks1 = St::ld8(&Kh[(long)((k0) + 32 + sr) * LDK + sc]); } while (0)
; #define SWAIT() do { if constexpr (SDEPTH == 2) asm volatile("s_waitcnt vmcnt(4)" ::: "memory"); else asm volatile("s_waitcnt vmcnt(0)" ::: "memory"); } while (0)
; __device__ __forceinline__ void finishSM(f32x16& p0, f32x16& p1, float& l_reg, bf16x8& pa0, bf16x8& pa1, bf16x8& pa2, bf16x8& pa3) {
;   for (int r = 0; r < 16; ++r) p1[r] = __builtin_amdgcn_exp2f(p1[r]);
;   float ps = 0; for (int r = 0; r < 16; ++r) ps += p0[r]; for (int r = 0; r < 16; ++r) ps += p1[r];
;   { auto rr = __builtin_amdgcn_permlane32_swap(__float_as_uint(ps), __float_as_uint(ps), false, false);
;     ps = __uint_as_float(rr[0]) + __uint_as_float(rr[1]); }
;   l_reg += ps;
;     ...
;   PK4(p0, 0, pa0); PK4(p0, 8, pa1); PK4(p1, 0, pa2); PK4(p1, 8, pa3);
;     ...
; }
; template <typename TQ> ...
;     ...
;   for (int j = 1; j + 1 < NT; j += 2) {
;     SBAR(); SLOAD(SO, (j + SDEPTH) * KVBLK); SBAR();
;     qkt(pB0, pB1, (bf16*)((char*)K_lds + SHM_K), qr, r32, hi, negm);
;     finishSM(pA0, pA1, l_reg, pa0, pa1, pa2, pa3); SBAR();
;     pv_d0(o, vb0, pa0, pa1, pa2, pa3); partialSM(pB0, pB1, mC);
;     __syncthreads(); SWAIT(); SWRITE(0, SE);
;     __syncthreads();
;     SBAR(); if (SDEPTH == 1 || j + 3 < NT) SLOAD(SE, (j + 1 + SDEPTH) * KVBLK); SBAR();
;     qkt(pA0, pA1, K_lds, qr, r32, hi, negm);
;     finishSM(pB0, pB1, l_reg, pa0, pa1, pa2, pa3); SBAR();
;     pv_d0(o, vb0 + (int)SHM_V, pa0, pa1, pa2, pa3); partialSM(pA0, pA1, mC);
;     __syncthreads(); SWAIT(); SWRITE(1, SO);
;     __syncthreads();
;   }
	v_lshrrev_b32_e32 v196, 4, v0
	v_lshlrev_b32_e32 v196, 9, v196
	v_and_b32_e32 v197, 15, v0
	v_lshl_or_b32 v196, v197, 4, v196
	v_add_u32_e32 v197, 0x4000, v196
	s_add_u32 s98, s54, 0x10000
	s_addc_u32 s99, s55, 0
	s_add_u32 s100, s64, 0x10000
	s_addc_u32 s101, s65, 0
	global_load_dwordx4 v[178:181], v196, s[100:101]
	global_load_dwordx4 v[182:185], v197, s[100:101]
	global_load_dwordx4 v[186:189], v196, s[98:99]
	global_load_dwordx4 v[190:193], v197, s[98:99]
	v_mov_b32_e32 v82, v232
	v_mov_b32_e32 v83, v234
	v_mov_b32_e32 v84, v230
	v_mov_b32_e32 v85, v233
	v_mov_b32_e32 v86, v229
	v_mov_b32_e32 v87, v231
	v_mov_b32_e32 v88, v227
	v_mov_b32_e32 v89, v228
	v_mov_b32_e32 v90, v224
	v_mov_b32_e32 v91, v226
	v_mov_b32_e32 v92, v223
	v_mov_b32_e32 v93, v225
	v_mov_b32_e32 v94, v220
	v_mov_b32_e32 v95, v222
	v_mov_b32_e32 v96, v219
	v_mov_b32_e32 v97, v221
	v_exp_f32_e32 v98, v98
	v_exp_f32_e32 v99, v99
	v_exp_f32_e32 v100, v100
	v_exp_f32_e32 v101, v101
	v_exp_f32_e32 v102, v102
	v_exp_f32_e32 v103, v103
	v_exp_f32_e32 v104, v104
	v_exp_f32_e32 v105, v105
	v_exp_f32_e32 v106, v106
	v_exp_f32_e32 v107, v107
	v_exp_f32_e32 v108, v108
	v_exp_f32_e32 v109, v109
	v_exp_f32_e32 v110, v110
	v_exp_f32_e32 v111, v111
	v_exp_f32_e32 v112, v112
	v_exp_f32_e32 v113, v113
	v_mov_b32_e32 v204, 0
	s_waitcnt vmcnt(0)
	ds_write_b128 v207, v[178:181] offset:32768
	ds_write_b128 v208, v[182:185] offset:32768
	ds_write_b128 v209, v[186:189] offset:32768
	ds_write_b128 v211, v[190:193] offset:32768
	s_add_u32 s98, s98, 0x8000
	s_addc_u32 s99, s99, 0
	s_add_u32 s100, s100, 0x8000
	s_addc_u32 s101, s101, 0
	global_load_dwordx4 v[178:181], v196, s[100:101]
	global_load_dwordx4 v[182:185], v197, s[100:101]
	global_load_dwordx4 v[186:189], v196, s[98:99]
	global_load_dwordx4 v[190:193], v197, s[98:99]
	s_waitcnt lgkmcnt(0)
	s_barrier
	ds_read_b128 v[220:223], v210 offset:16384
	ds_read_b128 v[224:227], v210 offset:24576
	ds_read_b128 v[228:231], v212 offset:16384
	ds_read_b128 v[232:235], v212 offset:24576
	s_mov_b32 s0, 0
.Lattn_loop:
	s_barrier
	s_waitcnt lgkmcnt(3)
	v_mfma_f32_32x32x16_bf16 v[114:129], v[220:223], v[150:153], v[2:17]
	ds_read_b128 v[220:223], v213 offset:16384
	v_add_f32_e32 v205, v82, v205
	v_add_f32_e32 v204, v83, v204
	v_cvt_pk_bf16_f32 v82, v82, v83
	s_waitcnt lgkmcnt(3)
	v_mfma_f32_32x32x16_bf16 v[130:145], v[224:227], v[150:153], v[2:17]
	ds_read_b128 v[224:227], v213 offset:24576
	v_add_f32_e32 v205, v84, v205
	v_add_f32_e32 v204, v85, v204
	v_cvt_pk_bf16_f32 v83, v84, v85
	s_waitcnt lgkmcnt(3)
	v_mfma_f32_32x32x16_bf16 v[114:129], v[228:231], v[158:161], v[114:129]
	ds_read_b128 v[228:231], v214 offset:16384
	v_add_f32_e32 v205, v86, v205
	v_add_f32_e32 v204, v87, v204
	v_cvt_pk_bf16_f32 v84, v86, v87
	s_waitcnt vmcnt(0)
	ds_write_b128 v207, v[178:181] offset:49152
	ds_write_b128 v208, v[182:185] offset:49152
	s_waitcnt lgkmcnt(5)
	v_mfma_f32_32x32x16_bf16 v[130:145], v[232:235], v[158:161], v[130:145]
	ds_read_b128 v[232:235], v214 offset:24576
	v_add_f32_e32 v205, v88, v205
	v_add_f32_e32 v204, v89, v204
	v_cvt_pk_bf16_f32 v85, v88, v89
	ds_write_b128 v209, v[186:189] offset:49152
	ds_write_b128 v211, v[190:193] offset:49152
	s_waitcnt lgkmcnt(7)
	v_mfma_f32_32x32x16_bf16 v[114:129], v[220:223], v[146:149], v[114:129]
	ds_read_b128 v[220:223], v218 offset:16384
	v_add_f32_e32 v205, v90, v205
	v_add_f32_e32 v204, v91, v204
	v_cvt_pk_bf16_f32 v86, v90, v91
	v_permlane32_swap_b32_e32 v82, v84
	s_waitcnt lgkmcnt(7)
	v_mfma_f32_32x32x16_bf16 v[130:145], v[224:227], v[146:149], v[130:145]
	ds_read_b128 v[224:227], v218 offset:24576
	v_add_f32_e32 v205, v92, v205
	v_add_f32_e32 v204, v93, v204
	v_cvt_pk_bf16_f32 v87, v92, v93
	v_permlane32_swap_b32_e32 v83, v85
	s_add_u32 s98, s98, 0x8000
	s_addc_u32 s99, s99, 0
	s_add_u32 s100, s100, 0x8000
	s_addc_u32 s101, s101, 0
	s_waitcnt lgkmcnt(7)
	v_mfma_f32_32x32x16_bf16 v[114:129], v[228:231], v[154:157], v[114:129]
	ds_read_b128 v[228:231], v217 offset:16384
	v_add_f32_e32 v205, v94, v205
	v_add_f32_e32 v204, v95, v204
	v_cvt_pk_bf16_f32 v88, v94, v95
	global_load_dwordx4 v[178:181], v196, s[100:101]
	global_load_dwordx4 v[182:185], v197, s[100:101]
	s_waitcnt lgkmcnt(5)
	v_mfma_f32_32x32x16_bf16 v[130:145], v[232:235], v[154:157], v[130:145]
	ds_read_b128 v[232:235], v217 offset:24576
	v_add_f32_e32 v205, v96, v205
	v_add_f32_e32 v204, v97, v204
	v_cvt_pk_bf16_f32 v89, v96, v97
	global_load_dwordx4 v[186:189], v196, s[98:99]
	global_load_dwordx4 v[190:193], v197, s[98:99]
	s_waitcnt lgkmcnt(3)
	v_mfma_f32_32x32x16_bf16 v[114:129], v[220:223], v[166:169], v[114:129]
	ds_read_b128 v[220:223], v216 offset:16384
	v_add_f32_e32 v205, v98, v205
	v_add_f32_e32 v204, v99, v204
	v_cvt_pk_bf16_f32 v90, v98, v99
	v_permlane32_swap_b32_e32 v86, v88
	ds_read_b64_tr_b16 v[236:237], v206 offset:0
	s_waitcnt lgkmcnt(4)
	v_mfma_f32_32x32x16_bf16 v[130:145], v[224:227], v[166:169], v[130:145]
	ds_read_b128 v[224:227], v216 offset:24576
	v_add_f32_e32 v205, v100, v205
	v_add_f32_e32 v204, v101, v204
	v_cvt_pk_bf16_f32 v91, v100, v101
	v_permlane32_swap_b32_e32 v87, v89
	ds_read_b64_tr_b16 v[238:239], v206 offset:2048
	s_waitcnt lgkmcnt(5)
	v_mfma_f32_32x32x16_bf16 v[114:129], v[228:231], v[174:177], v[114:129]
	ds_read_b128 v[228:231], v215 offset:16384
	v_add_f32_e32 v205, v102, v205
	v_add_f32_e32 v204, v103, v204
	v_cvt_pk_bf16_f32 v92, v102, v103
	ds_read_b64_tr_b16 v[240:241], v206 offset:4096
	s_waitcnt lgkmcnt(6)
	v_mfma_f32_32x32x16_bf16 v[130:145], v[232:235], v[174:177], v[130:145]
	ds_read_b128 v[232:235], v215 offset:24576
	v_add_f32_e32 v205, v104, v205
	v_add_f32_e32 v204, v105, v204
	v_cvt_pk_bf16_f32 v93, v104, v105
	ds_read_b64_tr_b16 v[242:243], v206 offset:6144
	s_waitcnt lgkmcnt(7)
; #define SBAR() __builtin_amdgcn_sched_barrier(0)
; __device__ __forceinline__ void finishSM(f32x16& p0, f32x16& p1, float& l_reg, bf16x8& pa0, bf16x8& pa1, bf16x8& pa2, bf16x8& pa3) {
;   for (int r = 0; r < 16; ++r) p1[r] = __builtin_amdgcn_exp2f(p1[r]);
;   float ps = 0; for (int r = 0; r < 16; ++r) ps += p0[r]; for (int r = 0; r < 16; ++r) ps += p1[r];
;   { auto rr = __builtin_amdgcn_permlane32_swap(__float_as_uint(ps), __float_as_uint(ps), false, false);
;     ps = __uint_as_float(rr[0]) + __uint_as_float(rr[1]); }
;   l_reg += ps;
;     ...
;   PK4(p0, 0, pa0); PK4(p0, 8, pa1); PK4(p1, 0, pa2); PK4(p1, 8, pa3);
;     ...
; }
; template <int D0> __device__ __forceinline__ void pv_one(f32x16& od, int vb, bf16x8 pa0, bf16x8 pa1, bf16x8 pa2, bf16x8 pa3) {
;   const s16x4 l0 = tr_read<v_rd_off(D0, 0, 0)>(vb), h0 = tr_read<v_rd_off(D0, 0, 1)>(vb), l1 = tr_read<v_rd_off(D0, 1, 0)>(vb), h1 = tr_read<v_rd_off(D0, 1, 1)>(vb);
;   const s16x4 l2 = tr_read<v_rd_off(D0, 2, 0)>(vb), h2 = tr_read<v_rd_off(D0, 2, 1)>(vb), l3 = tr_read<v_rd_off(D0, 3, 0)>(vb), h3 = tr_read<v_rd_off(D0, 3, 1)>(vb);
;   asm volatile("s_waitcnt lgkmcnt(0)" ::: "memory"); SBAR();
;     ...
;   od = __builtin_amdgcn_mfma_f32_32x32x16_bf16(pa0, PK(l0, h0), od, 0, 0, 0);
;   od = __builtin_amdgcn_mfma_f32_32x32x16_bf16(pa1, PK(l1, h1), od, 0, 0, 0);
;   od = __builtin_amdgcn_mfma_f32_32x32x16_bf16(pa2, PK(l2, h2), od, 0, 0, 0);
;   od = __builtin_amdgcn_mfma_f32_32x32x16_bf16(pa3, PK(l3, h3), od, 0, 0, 0);
;     ...
; }
; __device__ __forceinline__ void pv_d0(f32x16* o, int vb, bf16x8 pa0, bf16x8 pa1, bf16x8 pa2, bf16x8 pa3) {
;   pv_one<0>(o[0], vb, pa0, pa1, pa2, pa3); pv_one<1>(o[1], vb, pa0, pa1, pa2, pa3); pv_one<2>(o[2], vb, pa0, pa1, pa2, pa3); pv_one<3>(o[3], vb, pa0, pa1, pa2, pa3);
	v_mfma_f32_32x32x16_bf16 v[114:129], v[220:223], v[162:165], v[114:129]
	v_add_f32_e32 v205, v106, v205
	v_add_f32_e32 v204, v107, v204
	v_cvt_pk_bf16_f32 v94, v106, v107
	v_permlane32_swap_b32_e32 v90, v92
	ds_read_b64_tr_b16 v[244:245], v206 offset:8192
	ds_read_b64_tr_b16 v[98:99], v206 offset:512
	s_waitcnt lgkmcnt(7)
	v_mfma_f32_32x32x16_bf16 v[130:145], v[224:227], v[162:165], v[130:145]
	v_add_f32_e32 v205, v108, v205
	v_add_f32_e32 v204, v109, v204
	v_cvt_pk_bf16_f32 v95, v108, v109
	v_permlane32_swap_b32_e32 v91, v93
	ds_read_b64_tr_b16 v[246:247], v206 offset:10240
	ds_read_b64_tr_b16 v[100:101], v206 offset:2560
	s_waitcnt lgkmcnt(7)
	v_mfma_f32_32x32x16_bf16 v[114:129], v[228:231], v[170:173], v[114:129]
	v_add_f32_e32 v205, v110, v205
	v_add_f32_e32 v204, v111, v204
	v_cvt_pk_bf16_f32 v96, v110, v111
	ds_read_b64_tr_b16 v[248:249], v206 offset:12288
	ds_read_b64_tr_b16 v[102:103], v206 offset:4608
	s_waitcnt lgkmcnt(7)
	v_mfma_f32_32x32x16_bf16 v[130:145], v[232:235], v[170:173], v[130:145]
	v_add_f32_e32 v205, v112, v205
	v_add_f32_e32 v204, v113, v204
	v_cvt_pk_bf16_f32 v97, v112, v113
	ds_read_b64_tr_b16 v[250:251], v206 offset:14336
	ds_read_b64_tr_b16 v[104:105], v206 offset:6656
	v_mfma_f32_32x32x16_bf16 v[18:33], v[82:85], v[236:239], v[18:33]
	v_permlane32_swap_b32_e32 v94, v96
	v_permlane32_swap_b32_e32 v95, v97
	ds_read_b64_tr_b16 v[236:237], v206 offset:8704
	ds_read_b64_tr_b16 v[238:239], v206 offset:10752
	s_waitcnt lgkmcnt(10)
	v_mfma_f32_32x32x16_bf16 v[18:33], v[86:89], v[240:243], v[18:33]
	ds_read_b64_tr_b16 v[240:241], v206 offset:12800
	ds_read_b64_tr_b16 v[242:243], v206 offset:14848
	v_exp_f32_e32 v114, v114
	v_exp_f32_e32 v115, v115
	s_waitcnt lgkmcnt(9)
	v_mfma_f32_32x32x16_bf16 v[18:33], v[90:93], v[244:247], v[18:33]
	ds_read_b64_tr_b16 v[244:245], v206 offset:1024
	ds_read_b64_tr_b16 v[246:247], v206 offset:3072
	v_exp_f32_e32 v116, v116
	v_exp_f32_e32 v117, v117
	s_waitcnt lgkmcnt(7)
	v_mfma_f32_32x32x16_bf16 v[18:33], v[94:97], v[248:251], v[18:33]
	ds_read_b64_tr_b16 v[248:249], v206 offset:5120
	ds_read_b64_tr_b16 v[250:251], v206 offset:7168
	v_exp_f32_e32 v118, v118
	v_exp_f32_e32 v119, v119
	v_mfma_f32_32x32x16_bf16 v[34:49], v[82:85], v[98:101], v[34:49]
	ds_read_b64_tr_b16 v[98:99], v206 offset:9216
	ds_read_b64_tr_b16 v[100:101], v206 offset:11264
	v_exp_f32_e32 v120, v120
	v_exp_f32_e32 v121, v121
	s_waitcnt lgkmcnt(10)
	v_mfma_f32_32x32x16_bf16 v[34:49], v[86:89], v[102:105], v[34:49]
	ds_read_b64_tr_b16 v[102:103], v206 offset:13312
	ds_read_b64_tr_b16 v[104:105], v206 offset:15360
	v_exp_f32_e32 v122, v122
	v_exp_f32_e32 v123, v123
	s_waitcnt lgkmcnt(10)
	v_mfma_f32_32x32x16_bf16 v[34:49], v[90:93], v[236:239], v[34:49]
	ds_read_b64_tr_b16 v[236:237], v206 offset:1536
	ds_read_b64_tr_b16 v[238:239], v206 offset:3584
	v_exp_f32_e32 v124, v124
	v_exp_f32_e32 v125, v125
	s_waitcnt lgkmcnt(10)
	v_mfma_f32_32x32x16_bf16 v[34:49], v[94:97], v[240:243], v[34:49]
	ds_read_b64_tr_b16 v[240:241], v206 offset:5632
	ds_read_b64_tr_b16 v[242:243], v206 offset:7680
	v_exp_f32_e32 v126, v126
	v_exp_f32_e32 v127, v127
	s_waitcnt lgkmcnt(10)
	v_mfma_f32_32x32x16_bf16 v[50:65], v[82:85], v[244:247], v[50:65]
	ds_read_b64_tr_b16 v[244:245], v206 offset:9728
	ds_read_b64_tr_b16 v[246:247], v206 offset:11776
	v_exp_f32_e32 v128, v128
	v_exp_f32_e32 v129, v129
	s_waitcnt lgkmcnt(10)
	v_mfma_f32_32x32x16_bf16 v[50:65], v[86:89], v[248:251], v[50:65]
	ds_read_b64_tr_b16 v[248:249], v206 offset:13824
	ds_read_b64_tr_b16 v[250:251], v206 offset:15872
	v_exp_f32_e32 v130, v130
	v_exp_f32_e32 v131, v131
	s_waitcnt lgkmcnt(10)
	v_mfma_f32_32x32x16_bf16 v[50:65], v[90:93], v[98:101], v[50:65]
	v_exp_f32_e32 v132, v132
	v_exp_f32_e32 v133, v133
	s_waitcnt lgkmcnt(8)
	v_mfma_f32_32x32x16_bf16 v[50:65], v[94:97], v[102:105], v[50:65]
	v_exp_f32_e32 v134, v134
	v_exp_f32_e32 v135, v135
	s_waitcnt lgkmcnt(6)
	v_mfma_f32_32x32x16_bf16 v[66:81], v[82:85], v[236:239], v[66:81]
	v_exp_f32_e32 v136, v136
	v_exp_f32_e32 v137, v137
	ds_read_b128 v[220:223], v210 offset:32768
	s_waitcnt lgkmcnt(5)
	v_mfma_f32_32x32x16_bf16 v[66:81], v[86:89], v[240:243], v[66:81]
	v_exp_f32_e32 v138, v138
	v_exp_f32_e32 v139, v139
	ds_read_b128 v[224:227], v210 offset:40960
	s_waitcnt lgkmcnt(4)
	v_mfma_f32_32x32x16_bf16 v[66:81], v[90:93], v[244:247], v[66:81]
	v_exp_f32_e32 v140, v140
	v_exp_f32_e32 v141, v141
	ds_read_b128 v[228:231], v212 offset:32768
	s_waitcnt lgkmcnt(3)
	v_mfma_f32_32x32x16_bf16 v[66:81], v[94:97], v[248:251], v[66:81]
	v_exp_f32_e32 v142, v142
	v_exp_f32_e32 v143, v143
	v_exp_f32_e32 v144, v144
	v_exp_f32_e32 v145, v145
	ds_read_b128 v[232:235], v212 offset:40960
	s_barrier
; #define SBAR() __builtin_amdgcn_sched_barrier(0)
; #define SLOAD(i, k0) do { sr_[i].vs0 = St::ld8(&Vh[(long)((k0) + sr) * LDK + sc]); sr_[i].vs1 = St::ld8(&Vh[(long)((k0) + 32 + sr) * LDK + sc]); \
;     sr_[i].ks0 = St::ld8(&Kh[(long)((k0) + sr) * LDK + sc]); sr_[i].ks1 = St::ld8(&Kh[(long)((k0) + 32 + sr) * LDK + sc]); } while (0)
; #define SWAIT() do { if constexpr (SDEPTH == 2) asm volatile("s_waitcnt vmcnt(4)" ::: "memory"); else asm volatile("s_waitcnt vmcnt(0)" ::: "memory"); } while (0)
; __device__ __forceinline__ void finishSM(f32x16& p0, f32x16& p1, float& l_reg, bf16x8& pa0, bf16x8& pa1, bf16x8& pa2, bf16x8& pa3) {
;   for (int r = 0; r < 16; ++r) p1[r] = __builtin_amdgcn_exp2f(p1[r]);
;   float ps = 0; for (int r = 0; r < 16; ++r) ps += p0[r]; for (int r = 0; r < 16; ++r) ps += p1[r];
;   { auto rr = __builtin_amdgcn_permlane32_swap(__float_as_uint(ps), __float_as_uint(ps), false, false);
;     ps = __uint_as_float(rr[0]) + __uint_as_float(rr[1]); }
;   l_reg += ps;
;     ...
;   PK4(p0, 0, pa0); PK4(p0, 8, pa1); PK4(p1, 0, pa2); PK4(p1, 8, pa3);
;     ...
; }
; template <typename TQ> ...
;     ...
;   for (int j = 1; j + 1 < NT; j += 2) {
;     SBAR(); SLOAD(SO, (j + SDEPTH) * KVBLK); SBAR();
;     qkt(pB0, pB1, (bf16*)((char*)K_lds + SHM_K), qr, r32, hi, negm);
;     finishSM(pA0, pA1, l_reg, pa0, pa1, pa2, pa3); SBAR();
;     pv_d0(o, vb0, pa0, pa1, pa2, pa3); partialSM(pB0, pB1, mC);
;     __syncthreads(); SWAIT(); SWRITE(0, SE);
;     __syncthreads();
;     SBAR(); if (SDEPTH == 1 || j + 3 < NT) SLOAD(SE, (j + 1 + SDEPTH) * KVBLK); SBAR();
;     qkt(pA0, pA1, K_lds, qr, r32, hi, negm);
;     finishSM(pB0, pB1, l_reg, pa0, pa1, pa2, pa3); SBAR();
;     pv_d0(o, vb0 + (int)SHM_V, pa0, pa1, pa2, pa3); partialSM(pA0, pA1, mC);
;     __syncthreads(); SWAIT(); SWRITE(1, SO);
;     __syncthreads();
;   }
	s_waitcnt lgkmcnt(3)
	v_mfma_f32_32x32x16_bf16 v[82:97], v[220:223], v[150:153], v[2:17]
	ds_read_b128 v[220:223], v213 offset:32768
	v_add_f32_e32 v205, v114, v205
	v_add_f32_e32 v204, v115, v204
	v_cvt_pk_bf16_f32 v114, v114, v115
	s_waitcnt lgkmcnt(3)
	v_mfma_f32_32x32x16_bf16 v[98:113], v[224:227], v[150:153], v[2:17]
	ds_read_b128 v[224:227], v213 offset:40960
	v_add_f32_e32 v205, v116, v205
	v_add_f32_e32 v204, v117, v204
	v_cvt_pk_bf16_f32 v115, v116, v117
	s_waitcnt lgkmcnt(3)
	v_mfma_f32_32x32x16_bf16 v[82:97], v[228:231], v[158:161], v[82:97]
	ds_read_b128 v[228:231], v214 offset:32768
	v_add_f32_e32 v205, v118, v205
	v_add_f32_e32 v204, v119, v204
	v_cvt_pk_bf16_f32 v116, v118, v119
	s_waitcnt vmcnt(0)
	ds_write_b128 v207, v[178:181] offset:0
	ds_write_b128 v208, v[182:185] offset:0
	s_waitcnt lgkmcnt(5)
	v_mfma_f32_32x32x16_bf16 v[98:113], v[232:235], v[158:161], v[98:113]
	ds_read_b128 v[232:235], v214 offset:40960
	v_add_f32_e32 v205, v120, v205
	v_add_f32_e32 v204, v121, v204
	v_cvt_pk_bf16_f32 v117, v120, v121
	ds_write_b128 v209, v[186:189] offset:0
	ds_write_b128 v211, v[190:193] offset:0
	s_waitcnt lgkmcnt(7)
	v_mfma_f32_32x32x16_bf16 v[82:97], v[220:223], v[146:149], v[82:97]
	ds_read_b128 v[220:223], v218 offset:32768
	v_add_f32_e32 v205, v122, v205
	v_add_f32_e32 v204, v123, v204
	v_cvt_pk_bf16_f32 v118, v122, v123
	v_permlane32_swap_b32_e32 v114, v116
	s_waitcnt lgkmcnt(7)
	v_mfma_f32_32x32x16_bf16 v[98:113], v[224:227], v[146:149], v[98:113]
	ds_read_b128 v[224:227], v218 offset:40960
	v_add_f32_e32 v205, v124, v205
	v_add_f32_e32 v204, v125, v204
	v_cvt_pk_bf16_f32 v119, v124, v125
	v_permlane32_swap_b32_e32 v115, v117
	s_add_u32 s98, s98, 0x8000
	s_addc_u32 s99, s99, 0
	s_add_u32 s100, s100, 0x8000
	s_addc_u32 s101, s101, 0
	s_waitcnt lgkmcnt(7)
	v_mfma_f32_32x32x16_bf16 v[82:97], v[228:231], v[154:157], v[82:97]
	ds_read_b128 v[228:231], v217 offset:32768
	v_add_f32_e32 v205, v126, v205
	v_add_f32_e32 v204, v127, v204
	v_cvt_pk_bf16_f32 v120, v126, v127
	global_load_dwordx4 v[178:181], v196, s[100:101]
	global_load_dwordx4 v[182:185], v197, s[100:101]
	s_waitcnt lgkmcnt(5)
	v_mfma_f32_32x32x16_bf16 v[98:113], v[232:235], v[154:157], v[98:113]
	ds_read_b128 v[232:235], v217 offset:40960
	v_add_f32_e32 v205, v128, v205
	v_add_f32_e32 v204, v129, v204
	v_cvt_pk_bf16_f32 v121, v128, v129
	global_load_dwordx4 v[186:189], v196, s[98:99]
	global_load_dwordx4 v[190:193], v197, s[98:99]
	s_waitcnt lgkmcnt(3)
	v_mfma_f32_32x32x16_bf16 v[82:97], v[220:223], v[166:169], v[82:97]
	ds_read_b128 v[220:223], v216 offset:32768
	v_add_f32_e32 v205, v130, v205
	v_add_f32_e32 v204, v131, v204
	v_cvt_pk_bf16_f32 v122, v130, v131
	v_permlane32_swap_b32_e32 v118, v120
	ds_read_b64_tr_b16 v[236:237], v206 offset:16384
	s_waitcnt lgkmcnt(4)
	v_mfma_f32_32x32x16_bf16 v[98:113], v[224:227], v[166:169], v[98:113]
	ds_read_b128 v[224:227], v216 offset:40960
	v_add_f32_e32 v205, v132, v205
	v_add_f32_e32 v204, v133, v204
	v_cvt_pk_bf16_f32 v123, v132, v133
	v_permlane32_swap_b32_e32 v119, v121
	ds_read_b64_tr_b16 v[238:239], v206 offset:18432
	s_waitcnt lgkmcnt(5)
	v_mfma_f32_32x32x16_bf16 v[82:97], v[228:231], v[174:177], v[82:97]
	ds_read_b128 v[228:231], v215 offset:32768
	v_add_f32_e32 v205, v134, v205
	v_add_f32_e32 v204, v135, v204
	v_cvt_pk_bf16_f32 v124, v134, v135
	ds_read_b64_tr_b16 v[240:241], v206 offset:20480
	s_waitcnt lgkmcnt(6)
	v_mfma_f32_32x32x16_bf16 v[98:113], v[232:235], v[174:177], v[98:113]
	ds_read_b128 v[232:235], v215 offset:40960
	v_add_f32_e32 v205, v136, v205
	v_add_f32_e32 v204, v137, v204
	v_cvt_pk_bf16_f32 v125, v136, v137
	ds_read_b64_tr_b16 v[242:243], v206 offset:22528
	s_waitcnt lgkmcnt(7)
	v_mfma_f32_32x32x16_bf16 v[82:97], v[220:223], v[162:165], v[82:97]
	v_add_f32_e32 v205, v138, v205
	v_add_f32_e32 v204, v139, v204
	v_cvt_pk_bf16_f32 v126, v138, v139
	v_permlane32_swap_b32_e32 v122, v124
	ds_read_b64_tr_b16 v[244:245], v206 offset:24576
	ds_read_b64_tr_b16 v[130:131], v206 offset:16896
	s_waitcnt lgkmcnt(7)
	v_mfma_f32_32x32x16_bf16 v[98:113], v[224:227], v[162:165], v[98:113]
	v_add_f32_e32 v205, v140, v205
	v_add_f32_e32 v204, v141, v204
	v_cvt_pk_bf16_f32 v127, v140, v141
	v_permlane32_swap_b32_e32 v123, v125
	ds_read_b64_tr_b16 v[246:247], v206 offset:26624
	ds_read_b64_tr_b16 v[132:133], v206 offset:18944
	s_waitcnt lgkmcnt(7)
	v_mfma_f32_32x32x16_bf16 v[82:97], v[228:231], v[170:173], v[82:97]
	v_add_f32_e32 v205, v142, v205
	v_add_f32_e32 v204, v143, v204
	v_cvt_pk_bf16_f32 v128, v142, v143
	ds_read_b64_tr_b16 v[248:249], v206 offset:28672
	ds_read_b64_tr_b16 v[134:135], v206 offset:20992
	s_waitcnt lgkmcnt(7)
	v_mfma_f32_32x32x16_bf16 v[98:113], v[232:235], v[170:173], v[98:113]
	v_add_f32_e32 v205, v144, v205
	v_add_f32_e32 v204, v145, v204
	v_cvt_pk_bf16_f32 v129, v144, v145
	ds_read_b64_tr_b16 v[250:251], v206 offset:30720
	ds_read_b64_tr_b16 v[136:137], v206 offset:23040
	v_mfma_f32_32x32x16_bf16 v[18:33], v[114:117], v[236:239], v[18:33]
	v_permlane32_swap_b32_e32 v126, v128
	v_permlane32_swap_b32_e32 v127, v129
	ds_read_b64_tr_b16 v[236:237], v206 offset:25088
	ds_read_b64_tr_b16 v[238:239], v206 offset:27136
	s_waitcnt lgkmcnt(10)
	v_mfma_f32_32x32x16_bf16 v[18:33], v[118:121], v[240:243], v[18:33]
	ds_read_b64_tr_b16 v[240:241], v206 offset:29184
	ds_read_b64_tr_b16 v[242:243], v206 offset:31232
	v_exp_f32_e32 v82, v82
	v_exp_f32_e32 v83, v83
	s_waitcnt lgkmcnt(9)
	v_mfma_f32_32x32x16_bf16 v[18:33], v[122:125], v[244:247], v[18:33]
	ds_read_b64_tr_b16 v[244:245], v206 offset:17408
	ds_read_b64_tr_b16 v[246:247], v206 offset:19456
	v_exp_f32_e32 v84, v84
	v_exp_f32_e32 v85, v85
	s_waitcnt lgkmcnt(7)
; #define SBAR() __builtin_amdgcn_sched_barrier(0)
; #define SLOAD(i, k0) do { sr_[i].vs0 = St::ld8(&Vh[(long)((k0) + sr) * LDK + sc]); sr_[i].vs1 = St::ld8(&Vh[(long)((k0) + 32 + sr) * LDK + sc]); \
;     sr_[i].ks0 = St::ld8(&Kh[(long)((k0) + sr) * LDK + sc]); sr_[i].ks1 = St::ld8(&Kh[(long)((k0) + 32 + sr) * LDK + sc]); } while (0)
; #define SWAIT() do { if constexpr (SDEPTH == 2) asm volatile("s_waitcnt vmcnt(4)" ::: "memory"); else asm volatile("s_waitcnt vmcnt(0)" ::: "memory"); } while (0)
; template <int D0> __device__ __forceinline__ void pv_one(f32x16& od, int vb, bf16x8 pa0, bf16x8 pa1, bf16x8 pa2, bf16x8 pa3) {
;   const s16x4 l0 = tr_read<v_rd_off(D0, 0, 0)>(vb), h0 = tr_read<v_rd_off(D0, 0, 1)>(vb), l1 = tr_read<v_rd_off(D0, 1, 0)>(vb), h1 = tr_read<v_rd_off(D0, 1, 1)>(vb);
;   const s16x4 l2 = tr_read<v_rd_off(D0, 2, 0)>(vb), h2 = tr_read<v_rd_off(D0, 2, 1)>(vb), l3 = tr_read<v_rd_off(D0, 3, 0)>(vb), h3 = tr_read<v_rd_off(D0, 3, 1)>(vb);
;   asm volatile("s_waitcnt lgkmcnt(0)" ::: "memory"); SBAR();
;     ...
;   od = __builtin_amdgcn_mfma_f32_32x32x16_bf16(pa0, PK(l0, h0), od, 0, 0, 0);
;   od = __builtin_amdgcn_mfma_f32_32x32x16_bf16(pa1, PK(l1, h1), od, 0, 0, 0);
;   od = __builtin_amdgcn_mfma_f32_32x32x16_bf16(pa2, PK(l2, h2), od, 0, 0, 0);
;   od = __builtin_amdgcn_mfma_f32_32x32x16_bf16(pa3, PK(l3, h3), od, 0, 0, 0);
;     ...
; }
; __device__ __forceinline__ void pv_d0(f32x16* o, int vb, bf16x8 pa0, bf16x8 pa1, bf16x8 pa2, bf16x8 pa3) {
;   pv_one<0>(o[0], vb, pa0, pa1, pa2, pa3); pv_one<1>(o[1], vb, pa0, pa1, pa2, pa3); pv_one<2>(o[2], vb, pa0, pa1, pa2, pa3); pv_one<3>(o[3], vb, pa0, pa1, pa2, pa3);
; template <typename TQ> ...
;     ...
;   for (int j = 1; j + 1 < NT; j += 2) {
;     SBAR(); SLOAD(SO, (j + SDEPTH) * KVBLK); SBAR();
;     qkt(pB0, pB1, (bf16*)((char*)K_lds + SHM_K), qr, r32, hi, negm);
;     finishSM(pA0, pA1, l_reg, pa0, pa1, pa2, pa3); SBAR();
;     pv_d0(o, vb0, pa0, pa1, pa2, pa3); partialSM(pB0, pB1, mC);
;     __syncthreads(); SWAIT(); SWRITE(0, SE);
;     __syncthreads();
;     SBAR(); if (SDEPTH == 1 || j + 3 < NT) SLOAD(SE, (j + 1 + SDEPTH) * KVBLK); SBAR();
;     qkt(pA0, pA1, K_lds, qr, r32, hi, negm);
;     finishSM(pB0, pB1, l_reg, pa0, pa1, pa2, pa3); SBAR();
;     pv_d0(o, vb0 + (int)SHM_V, pa0, pa1, pa2, pa3); partialSM(pA0, pA1, mC);
;     __syncthreads(); SWAIT(); SWRITE(1, SO);
;     __syncthreads();
;   }
	v_mfma_f32_32x32x16_bf16 v[18:33], v[126:129], v[248:251], v[18:33]
	ds_read_b64_tr_b16 v[248:249], v206 offset:21504
	ds_read_b64_tr_b16 v[250:251], v206 offset:23552
	v_exp_f32_e32 v86, v86
	v_exp_f32_e32 v87, v87
	v_mfma_f32_32x32x16_bf16 v[34:49], v[114:117], v[130:133], v[34:49]
	ds_read_b64_tr_b16 v[130:131], v206 offset:25600
	ds_read_b64_tr_b16 v[132:133], v206 offset:27648
	v_exp_f32_e32 v88, v88
	v_exp_f32_e32 v89, v89
	s_waitcnt lgkmcnt(10)
	v_mfma_f32_32x32x16_bf16 v[34:49], v[118:121], v[134:137], v[34:49]
	ds_read_b64_tr_b16 v[134:135], v206 offset:29696
	ds_read_b64_tr_b16 v[136:137], v206 offset:31744
	v_exp_f32_e32 v90, v90
	v_exp_f32_e32 v91, v91
	s_waitcnt lgkmcnt(10)
	v_mfma_f32_32x32x16_bf16 v[34:49], v[122:125], v[236:239], v[34:49]
	ds_read_b64_tr_b16 v[236:237], v206 offset:17920
	ds_read_b64_tr_b16 v[238:239], v206 offset:19968
	v_exp_f32_e32 v92, v92
	v_exp_f32_e32 v93, v93
	s_waitcnt lgkmcnt(10)
	v_mfma_f32_32x32x16_bf16 v[34:49], v[126:129], v[240:243], v[34:49]
	ds_read_b64_tr_b16 v[240:241], v206 offset:22016
	ds_read_b64_tr_b16 v[242:243], v206 offset:24064
	v_exp_f32_e32 v94, v94
	v_exp_f32_e32 v95, v95
	s_waitcnt lgkmcnt(10)
	v_mfma_f32_32x32x16_bf16 v[50:65], v[114:117], v[244:247], v[50:65]
	ds_read_b64_tr_b16 v[244:245], v206 offset:26112
	ds_read_b64_tr_b16 v[246:247], v206 offset:28160
	v_exp_f32_e32 v96, v96
	v_exp_f32_e32 v97, v97
	s_waitcnt lgkmcnt(10)
	v_mfma_f32_32x32x16_bf16 v[50:65], v[118:121], v[248:251], v[50:65]
	ds_read_b64_tr_b16 v[248:249], v206 offset:30208
	ds_read_b64_tr_b16 v[250:251], v206 offset:32256
	v_exp_f32_e32 v98, v98
	v_exp_f32_e32 v99, v99
	s_waitcnt lgkmcnt(10)
	v_mfma_f32_32x32x16_bf16 v[50:65], v[122:125], v[130:133], v[50:65]
	v_exp_f32_e32 v100, v100
	v_exp_f32_e32 v101, v101
	s_waitcnt lgkmcnt(8)
	v_mfma_f32_32x32x16_bf16 v[50:65], v[126:129], v[134:137], v[50:65]
	v_exp_f32_e32 v102, v102
	v_exp_f32_e32 v103, v103
	s_waitcnt lgkmcnt(6)
	v_mfma_f32_32x32x16_bf16 v[66:81], v[114:117], v[236:239], v[66:81]
	v_exp_f32_e32 v104, v104
	v_exp_f32_e32 v105, v105
	ds_read_b128 v[220:223], v210 offset:49152
	s_waitcnt lgkmcnt(5)
	v_mfma_f32_32x32x16_bf16 v[66:81], v[118:121], v[240:243], v[66:81]
	v_exp_f32_e32 v106, v106
	v_exp_f32_e32 v107, v107
	ds_read_b128 v[224:227], v210 offset:57344
	s_waitcnt lgkmcnt(4)
	v_mfma_f32_32x32x16_bf16 v[66:81], v[122:125], v[244:247], v[66:81]
	v_exp_f32_e32 v108, v108
	v_exp_f32_e32 v109, v109
	ds_read_b128 v[228:231], v212 offset:49152
	s_waitcnt lgkmcnt(3)
	v_mfma_f32_32x32x16_bf16 v[66:81], v[126:129], v[248:251], v[66:81]
	v_exp_f32_e32 v110, v110
	v_exp_f32_e32 v111, v111
	v_exp_f32_e32 v112, v112
	v_exp_f32_e32 v113, v113
	ds_read_b128 v[232:235], v212 offset:57344
	s_barrier
	s_waitcnt lgkmcnt(3)
	v_mfma_f32_32x32x16_bf16 v[114:129], v[220:223], v[150:153], v[2:17]
	ds_read_b128 v[220:223], v213 offset:49152
	v_add_f32_e32 v205, v82, v205
	v_add_f32_e32 v204, v83, v204
	v_cvt_pk_bf16_f32 v82, v82, v83
	s_waitcnt lgkmcnt(3)
	v_mfma_f32_32x32x16_bf16 v[130:145], v[224:227], v[150:153], v[2:17]
	ds_read_b128 v[224:227], v213 offset:57344
	v_add_f32_e32 v205, v84, v205
	v_add_f32_e32 v204, v85, v204
	v_cvt_pk_bf16_f32 v83, v84, v85
	s_waitcnt lgkmcnt(3)
	v_mfma_f32_32x32x16_bf16 v[114:129], v[228:231], v[158:161], v[114:129]
	ds_read_b128 v[228:231], v214 offset:49152
	v_add_f32_e32 v205, v86, v205
	v_add_f32_e32 v204, v87, v204
	v_cvt_pk_bf16_f32 v84, v86, v87
	s_waitcnt vmcnt(0)
	ds_write_b128 v207, v[178:181] offset:16384
	ds_write_b128 v208, v[182:185] offset:16384
	s_waitcnt lgkmcnt(5)
	v_mfma_f32_32x32x16_bf16 v[130:145], v[232:235], v[158:161], v[130:145]
	ds_read_b128 v[232:235], v214 offset:57344
	v_add_f32_e32 v205, v88, v205
	v_add_f32_e32 v204, v89, v204
	v_cvt_pk_bf16_f32 v85, v88, v89
	ds_write_b128 v209, v[186:189] offset:16384
	ds_write_b128 v211, v[190:193] offset:16384
	s_waitcnt lgkmcnt(7)
	v_mfma_f32_32x32x16_bf16 v[114:129], v[220:223], v[146:149], v[114:129]
	ds_read_b128 v[220:223], v218 offset:49152
	v_add_f32_e32 v205, v90, v205
	v_add_f32_e32 v204, v91, v204
	v_cvt_pk_bf16_f32 v86, v90, v91
	v_permlane32_swap_b32_e32 v82, v84
	s_waitcnt lgkmcnt(7)
	v_mfma_f32_32x32x16_bf16 v[130:145], v[224:227], v[146:149], v[130:145]
	ds_read_b128 v[224:227], v218 offset:57344
	v_add_f32_e32 v205, v92, v205
	v_add_f32_e32 v204, v93, v204
	v_cvt_pk_bf16_f32 v87, v92, v93
	v_permlane32_swap_b32_e32 v83, v85
	s_add_u32 s98, s98, 0x8000
	s_addc_u32 s99, s99, 0
	s_add_u32 s100, s100, 0x8000
	s_addc_u32 s101, s101, 0
	s_waitcnt lgkmcnt(7)
	v_mfma_f32_32x32x16_bf16 v[114:129], v[228:231], v[154:157], v[114:129]
	ds_read_b128 v[228:231], v217 offset:49152
	v_add_f32_e32 v205, v94, v205
	v_add_f32_e32 v204, v95, v204
	v_cvt_pk_bf16_f32 v88, v94, v95
	global_load_dwordx4 v[178:181], v196, s[100:101]
	global_load_dwordx4 v[182:185], v197, s[100:101]
	s_waitcnt lgkmcnt(5)
	v_mfma_f32_32x32x16_bf16 v[130:145], v[232:235], v[154:157], v[130:145]
	ds_read_b128 v[232:235], v217 offset:57344
	v_add_f32_e32 v205, v96, v205
	v_add_f32_e32 v204, v97, v204
	v_cvt_pk_bf16_f32 v89, v96, v97
	global_load_dwordx4 v[186:189], v196, s[98:99]
	global_load_dwordx4 v[190:193], v197, s[98:99]
	s_waitcnt lgkmcnt(3)
	v_mfma_f32_32x32x16_bf16 v[114:129], v[220:223], v[166:169], v[114:129]
	ds_read_b128 v[220:223], v216 offset:49152
	v_add_f32_e32 v205, v98, v205
	v_add_f32_e32 v204, v99, v204
	v_cvt_pk_bf16_f32 v90, v98, v99
	v_permlane32_swap_b32_e32 v86, v88
	ds_read_b64_tr_b16 v[236:237], v206 offset:32768
	s_waitcnt lgkmcnt(4)
; #define SBAR() __builtin_amdgcn_sched_barrier(0)
; #define SLOAD(i, k0) do { sr_[i].vs0 = St::ld8(&Vh[(long)((k0) + sr) * LDK + sc]); sr_[i].vs1 = St::ld8(&Vh[(long)((k0) + 32 + sr) * LDK + sc]); \
;     sr_[i].ks0 = St::ld8(&Kh[(long)((k0) + sr) * LDK + sc]); sr_[i].ks1 = St::ld8(&Kh[(long)((k0) + 32 + sr) * LDK + sc]); } while (0)
; #define SWAIT() do { if constexpr (SDEPTH == 2) asm volatile("s_waitcnt vmcnt(4)" ::: "memory"); else asm volatile("s_waitcnt vmcnt(0)" ::: "memory"); } while (0)
; template <int D0> __device__ __forceinline__ void pv_one(f32x16& od, int vb, bf16x8 pa0, bf16x8 pa1, bf16x8 pa2, bf16x8 pa3) {
;   const s16x4 l0 = tr_read<v_rd_off(D0, 0, 0)>(vb), h0 = tr_read<v_rd_off(D0, 0, 1)>(vb), l1 = tr_read<v_rd_off(D0, 1, 0)>(vb), h1 = tr_read<v_rd_off(D0, 1, 1)>(vb);
;   const s16x4 l2 = tr_read<v_rd_off(D0, 2, 0)>(vb), h2 = tr_read<v_rd_off(D0, 2, 1)>(vb), l3 = tr_read<v_rd_off(D0, 3, 0)>(vb), h3 = tr_read<v_rd_off(D0, 3, 1)>(vb);
;   asm volatile("s_waitcnt lgkmcnt(0)" ::: "memory"); SBAR();
;     ...
;   od = __builtin_amdgcn_mfma_f32_32x32x16_bf16(pa0, PK(l0, h0), od, 0, 0, 0);
;   od = __builtin_amdgcn_mfma_f32_32x32x16_bf16(pa1, PK(l1, h1), od, 0, 0, 0);
;   od = __builtin_amdgcn_mfma_f32_32x32x16_bf16(pa2, PK(l2, h2), od, 0, 0, 0);
;   od = __builtin_amdgcn_mfma_f32_32x32x16_bf16(pa3, PK(l3, h3), od, 0, 0, 0);
;     ...
; }
; __device__ __forceinline__ void pv_d0(f32x16* o, int vb, bf16x8 pa0, bf16x8 pa1, bf16x8 pa2, bf16x8 pa3) {
;   pv_one<0>(o[0], vb, pa0, pa1, pa2, pa3); pv_one<1>(o[1], vb, pa0, pa1, pa2, pa3); pv_one<2>(o[2], vb, pa0, pa1, pa2, pa3); pv_one<3>(o[3], vb, pa0, pa1, pa2, pa3);
; template <typename TQ> ...
;     ...
;   for (int j = 1; j + 1 < NT; j += 2) {
;     SBAR(); SLOAD(SO, (j + SDEPTH) * KVBLK); SBAR();
;     qkt(pB0, pB1, (bf16*)((char*)K_lds + SHM_K), qr, r32, hi, negm);
;     finishSM(pA0, pA1, l_reg, pa0, pa1, pa2, pa3); SBAR();
;     pv_d0(o, vb0, pa0, pa1, pa2, pa3); partialSM(pB0, pB1, mC);
;     __syncthreads(); SWAIT(); SWRITE(0, SE);
;     __syncthreads();
;     SBAR(); if (SDEPTH == 1 || j + 3 < NT) SLOAD(SE, (j + 1 + SDEPTH) * KVBLK); SBAR();
;     qkt(pA0, pA1, K_lds, qr, r32, hi, negm);
;     finishSM(pB0, pB1, l_reg, pa0, pa1, pa2, pa3); SBAR();
;     pv_d0(o, vb0 + (int)SHM_V, pa0, pa1, pa2, pa3); partialSM(pA0, pA1, mC);
;     __syncthreads(); SWAIT(); SWRITE(1, SO);
;     __syncthreads();
;   }
	v_mfma_f32_32x32x16_bf16 v[130:145], v[224:227], v[166:169], v[130:145]
	ds_read_b128 v[224:227], v216 offset:57344
	v_add_f32_e32 v205, v100, v205
	v_add_f32_e32 v204, v101, v204
	v_cvt_pk_bf16_f32 v91, v100, v101
	v_permlane32_swap_b32_e32 v87, v89
	ds_read_b64_tr_b16 v[238:239], v206 offset:34816
	s_waitcnt lgkmcnt(5)
	v_mfma_f32_32x32x16_bf16 v[114:129], v[228:231], v[174:177], v[114:129]
	ds_read_b128 v[228:231], v215 offset:49152
	v_add_f32_e32 v205, v102, v205
	v_add_f32_e32 v204, v103, v204
	v_cvt_pk_bf16_f32 v92, v102, v103
	ds_read_b64_tr_b16 v[240:241], v206 offset:36864
	s_waitcnt lgkmcnt(6)
	v_mfma_f32_32x32x16_bf16 v[130:145], v[232:235], v[174:177], v[130:145]
	ds_read_b128 v[232:235], v215 offset:57344
	v_add_f32_e32 v205, v104, v205
	v_add_f32_e32 v204, v105, v204
	v_cvt_pk_bf16_f32 v93, v104, v105
	ds_read_b64_tr_b16 v[242:243], v206 offset:38912
	s_waitcnt lgkmcnt(7)
	v_mfma_f32_32x32x16_bf16 v[114:129], v[220:223], v[162:165], v[114:129]
	v_add_f32_e32 v205, v106, v205
	v_add_f32_e32 v204, v107, v204
	v_cvt_pk_bf16_f32 v94, v106, v107
	v_permlane32_swap_b32_e32 v90, v92
	ds_read_b64_tr_b16 v[244:245], v206 offset:40960
	ds_read_b64_tr_b16 v[98:99], v206 offset:33280
	s_waitcnt lgkmcnt(7)
	v_mfma_f32_32x32x16_bf16 v[130:145], v[224:227], v[162:165], v[130:145]
	v_add_f32_e32 v205, v108, v205
	v_add_f32_e32 v204, v109, v204
	v_cvt_pk_bf16_f32 v95, v108, v109
	v_permlane32_swap_b32_e32 v91, v93
	ds_read_b64_tr_b16 v[246:247], v206 offset:43008
	ds_read_b64_tr_b16 v[100:101], v206 offset:35328
	s_waitcnt lgkmcnt(7)
	v_mfma_f32_32x32x16_bf16 v[114:129], v[228:231], v[170:173], v[114:129]
	v_add_f32_e32 v205, v110, v205
	v_add_f32_e32 v204, v111, v204
	v_cvt_pk_bf16_f32 v96, v110, v111
	ds_read_b64_tr_b16 v[248:249], v206 offset:45056
	ds_read_b64_tr_b16 v[102:103], v206 offset:37376
	s_waitcnt lgkmcnt(7)
	v_mfma_f32_32x32x16_bf16 v[130:145], v[232:235], v[170:173], v[130:145]
	v_add_f32_e32 v205, v112, v205
	v_add_f32_e32 v204, v113, v204
	v_cvt_pk_bf16_f32 v97, v112, v113
	ds_read_b64_tr_b16 v[250:251], v206 offset:47104
	ds_read_b64_tr_b16 v[104:105], v206 offset:39424
	v_mfma_f32_32x32x16_bf16 v[18:33], v[82:85], v[236:239], v[18:33]
	v_permlane32_swap_b32_e32 v94, v96
	v_permlane32_swap_b32_e32 v95, v97
	ds_read_b64_tr_b16 v[236:237], v206 offset:41472
	ds_read_b64_tr_b16 v[238:239], v206 offset:43520
	s_waitcnt lgkmcnt(10)
	v_mfma_f32_32x32x16_bf16 v[18:33], v[86:89], v[240:243], v[18:33]
	ds_read_b64_tr_b16 v[240:241], v206 offset:45568
	ds_read_b64_tr_b16 v[242:243], v206 offset:47616
	v_exp_f32_e32 v114, v114
	v_exp_f32_e32 v115, v115
	s_waitcnt lgkmcnt(9)
	v_mfma_f32_32x32x16_bf16 v[18:33], v[90:93], v[244:247], v[18:33]
	ds_read_b64_tr_b16 v[244:245], v206 offset:33792
	ds_read_b64_tr_b16 v[246:247], v206 offset:35840
	v_exp_f32_e32 v116, v116
	v_exp_f32_e32 v117, v117
	s_waitcnt lgkmcnt(7)
	v_mfma_f32_32x32x16_bf16 v[18:33], v[94:97], v[248:251], v[18:33]
	ds_read_b64_tr_b16 v[248:249], v206 offset:37888
	ds_read_b64_tr_b16 v[250:251], v206 offset:39936
	v_exp_f32_e32 v118, v118
	v_exp_f32_e32 v119, v119
	v_mfma_f32_32x32x16_bf16 v[34:49], v[82:85], v[98:101], v[34:49]
	ds_read_b64_tr_b16 v[98:99], v206 offset:41984
	ds_read_b64_tr_b16 v[100:101], v206 offset:44032
	v_exp_f32_e32 v120, v120
	v_exp_f32_e32 v121, v121
	s_waitcnt lgkmcnt(10)
	v_mfma_f32_32x32x16_bf16 v[34:49], v[86:89], v[102:105], v[34:49]
	ds_read_b64_tr_b16 v[102:103], v206 offset:46080
	ds_read_b64_tr_b16 v[104:105], v206 offset:48128
	v_exp_f32_e32 v122, v122
	v_exp_f32_e32 v123, v123
	s_waitcnt lgkmcnt(10)
	v_mfma_f32_32x32x16_bf16 v[34:49], v[90:93], v[236:239], v[34:49]
	ds_read_b64_tr_b16 v[236:237], v206 offset:34304
	ds_read_b64_tr_b16 v[238:239], v206 offset:36352
	v_exp_f32_e32 v124, v124
	v_exp_f32_e32 v125, v125
	s_waitcnt lgkmcnt(10)
	v_mfma_f32_32x32x16_bf16 v[34:49], v[94:97], v[240:243], v[34:49]
	ds_read_b64_tr_b16 v[240:241], v206 offset:38400
	ds_read_b64_tr_b16 v[242:243], v206 offset:40448
	v_exp_f32_e32 v126, v126
	v_exp_f32_e32 v127, v127
	s_waitcnt lgkmcnt(10)
	v_mfma_f32_32x32x16_bf16 v[50:65], v[82:85], v[244:247], v[50:65]
	ds_read_b64_tr_b16 v[244:245], v206 offset:42496
	ds_read_b64_tr_b16 v[246:247], v206 offset:44544
	v_exp_f32_e32 v128, v128
	v_exp_f32_e32 v129, v129
	s_waitcnt lgkmcnt(10)
	v_mfma_f32_32x32x16_bf16 v[50:65], v[86:89], v[248:251], v[50:65]
	ds_read_b64_tr_b16 v[248:249], v206 offset:46592
	ds_read_b64_tr_b16 v[250:251], v206 offset:48640
	v_exp_f32_e32 v130, v130
	v_exp_f32_e32 v131, v131
	s_waitcnt lgkmcnt(10)
	v_mfma_f32_32x32x16_bf16 v[50:65], v[90:93], v[98:101], v[50:65]
	v_exp_f32_e32 v132, v132
	v_exp_f32_e32 v133, v133
	s_waitcnt lgkmcnt(8)
	v_mfma_f32_32x32x16_bf16 v[50:65], v[94:97], v[102:105], v[50:65]
	v_exp_f32_e32 v134, v134
	v_exp_f32_e32 v135, v135
	s_waitcnt lgkmcnt(6)
	v_mfma_f32_32x32x16_bf16 v[66:81], v[82:85], v[236:239], v[66:81]
	v_exp_f32_e32 v136, v136
	v_exp_f32_e32 v137, v137
	ds_read_b128 v[220:223], v210 offset:0
	s_waitcnt lgkmcnt(5)
	v_mfma_f32_32x32x16_bf16 v[66:81], v[86:89], v[240:243], v[66:81]
	v_exp_f32_e32 v138, v138
	v_exp_f32_e32 v139, v139
	ds_read_b128 v[224:227], v210 offset:8192
	s_waitcnt lgkmcnt(4)
	v_mfma_f32_32x32x16_bf16 v[66:81], v[90:93], v[244:247], v[66:81]
	v_exp_f32_e32 v140, v140
	v_exp_f32_e32 v141, v141
	ds_read_b128 v[228:231], v212 offset:0
	s_waitcnt lgkmcnt(3)
	v_mfma_f32_32x32x16_bf16 v[66:81], v[94:97], v[248:251], v[66:81]
	v_exp_f32_e32 v142, v142
	v_exp_f32_e32 v143, v143
	v_exp_f32_e32 v144, v144
	v_exp_f32_e32 v145, v145
	ds_read_b128 v[232:235], v212 offset:8192
	s_barrier
; #define SBAR() __builtin_amdgcn_sched_barrier(0)
; #define SLOAD(i, k0) do { sr_[i].vs0 = St::ld8(&Vh[(long)((k0) + sr) * LDK + sc]); sr_[i].vs1 = St::ld8(&Vh[(long)((k0) + 32 + sr) * LDK + sc]); \
;     sr_[i].ks0 = St::ld8(&Kh[(long)((k0) + sr) * LDK + sc]); sr_[i].ks1 = St::ld8(&Kh[(long)((k0) + 32 + sr) * LDK + sc]); } while (0)
; #define SWAIT() do { if constexpr (SDEPTH == 2) asm volatile("s_waitcnt vmcnt(4)" ::: "memory"); else asm volatile("s_waitcnt vmcnt(0)" ::: "memory"); } while (0)
; __device__ __forceinline__ void finishSM(f32x16& p0, f32x16& p1, float& l_reg, bf16x8& pa0, bf16x8& pa1, bf16x8& pa2, bf16x8& pa3) {
;   for (int r = 0; r < 16; ++r) p1[r] = __builtin_amdgcn_exp2f(p1[r]);
;   float ps = 0; for (int r = 0; r < 16; ++r) ps += p0[r]; for (int r = 0; r < 16; ++r) ps += p1[r];
;   { auto rr = __builtin_amdgcn_permlane32_swap(__float_as_uint(ps), __float_as_uint(ps), false, false);
;     ps = __uint_as_float(rr[0]) + __uint_as_float(rr[1]); }
;   l_reg += ps;
;     ...
;   PK4(p0, 0, pa0); PK4(p0, 8, pa1); PK4(p1, 0, pa2); PK4(p1, 8, pa3);
;     ...
; }
; template <typename TQ> ...
;     ...
;   for (int j = 1; j + 1 < NT; j += 2) {
;     SBAR(); SLOAD(SO, (j + SDEPTH) * KVBLK); SBAR();
;     qkt(pB0, pB1, (bf16*)((char*)K_lds + SHM_K), qr, r32, hi, negm);
;     finishSM(pA0, pA1, l_reg, pa0, pa1, pa2, pa3); SBAR();
;     pv_d0(o, vb0, pa0, pa1, pa2, pa3); partialSM(pB0, pB1, mC);
;     __syncthreads(); SWAIT(); SWRITE(0, SE);
;     __syncthreads();
;     SBAR(); if (SDEPTH == 1 || j + 3 < NT) SLOAD(SE, (j + 1 + SDEPTH) * KVBLK); SBAR();
;     qkt(pA0, pA1, K_lds, qr, r32, hi, negm);
;     finishSM(pB0, pB1, l_reg, pa0, pa1, pa2, pa3); SBAR();
;     pv_d0(o, vb0 + (int)SHM_V, pa0, pa1, pa2, pa3); partialSM(pA0, pA1, mC);
;     __syncthreads(); SWAIT(); SWRITE(1, SO);
;     __syncthreads();
;   }
	s_waitcnt lgkmcnt(3)
	v_mfma_f32_32x32x16_bf16 v[82:97], v[220:223], v[150:153], v[2:17]
	ds_read_b128 v[220:223], v213 offset:0
	v_add_f32_e32 v205, v114, v205
	v_add_f32_e32 v204, v115, v204
	v_cvt_pk_bf16_f32 v114, v114, v115
	s_waitcnt lgkmcnt(3)
	v_mfma_f32_32x32x16_bf16 v[98:113], v[224:227], v[150:153], v[2:17]
	ds_read_b128 v[224:227], v213 offset:8192
	v_add_f32_e32 v205, v116, v205
	v_add_f32_e32 v204, v117, v204
	v_cvt_pk_bf16_f32 v115, v116, v117
	s_waitcnt lgkmcnt(3)
	v_mfma_f32_32x32x16_bf16 v[82:97], v[228:231], v[158:161], v[82:97]
	ds_read_b128 v[228:231], v214 offset:0
	v_add_f32_e32 v205, v118, v205
	v_add_f32_e32 v204, v119, v204
	v_cvt_pk_bf16_f32 v116, v118, v119
	s_waitcnt vmcnt(0)
	ds_write_b128 v207, v[178:181] offset:32768
	ds_write_b128 v208, v[182:185] offset:32768
	s_waitcnt lgkmcnt(5)
	v_mfma_f32_32x32x16_bf16 v[98:113], v[232:235], v[158:161], v[98:113]
	ds_read_b128 v[232:235], v214 offset:8192
	v_add_f32_e32 v205, v120, v205
	v_add_f32_e32 v204, v121, v204
	v_cvt_pk_bf16_f32 v117, v120, v121
	ds_write_b128 v209, v[186:189] offset:32768
	ds_write_b128 v211, v[190:193] offset:32768
	s_waitcnt lgkmcnt(7)
	v_mfma_f32_32x32x16_bf16 v[82:97], v[220:223], v[146:149], v[82:97]
	ds_read_b128 v[220:223], v218 offset:0
	v_add_f32_e32 v205, v122, v205
	v_add_f32_e32 v204, v123, v204
	v_cvt_pk_bf16_f32 v118, v122, v123
	v_permlane32_swap_b32_e32 v114, v116
	s_waitcnt lgkmcnt(7)
	v_mfma_f32_32x32x16_bf16 v[98:113], v[224:227], v[146:149], v[98:113]
	ds_read_b128 v[224:227], v218 offset:8192
	v_add_f32_e32 v205, v124, v205
	v_add_f32_e32 v204, v125, v204
	v_cvt_pk_bf16_f32 v119, v124, v125
	v_permlane32_swap_b32_e32 v115, v117
	s_add_u32 s98, s98, 0x8000
	s_addc_u32 s99, s99, 0
	s_add_u32 s100, s100, 0x8000
	s_addc_u32 s101, s101, 0
	s_waitcnt lgkmcnt(7)
	v_mfma_f32_32x32x16_bf16 v[82:97], v[228:231], v[154:157], v[82:97]
	ds_read_b128 v[228:231], v217 offset:0
	v_add_f32_e32 v205, v126, v205
	v_add_f32_e32 v204, v127, v204
	v_cvt_pk_bf16_f32 v120, v126, v127
	global_load_dwordx4 v[178:181], v196, s[100:101]
	global_load_dwordx4 v[182:185], v197, s[100:101]
	s_waitcnt lgkmcnt(5)
	v_mfma_f32_32x32x16_bf16 v[98:113], v[232:235], v[154:157], v[98:113]
	ds_read_b128 v[232:235], v217 offset:8192
	v_add_f32_e32 v205, v128, v205
	v_add_f32_e32 v204, v129, v204
	v_cvt_pk_bf16_f32 v121, v128, v129
	global_load_dwordx4 v[186:189], v196, s[98:99]
	global_load_dwordx4 v[190:193], v197, s[98:99]
	s_waitcnt lgkmcnt(3)
	v_mfma_f32_32x32x16_bf16 v[82:97], v[220:223], v[166:169], v[82:97]
	ds_read_b128 v[220:223], v216 offset:0
	v_add_f32_e32 v205, v130, v205
	v_add_f32_e32 v204, v131, v204
	v_cvt_pk_bf16_f32 v122, v130, v131
	v_permlane32_swap_b32_e32 v118, v120
	ds_read_b64_tr_b16 v[236:237], v206 offset:49152
	s_waitcnt lgkmcnt(4)
	v_mfma_f32_32x32x16_bf16 v[98:113], v[224:227], v[166:169], v[98:113]
	ds_read_b128 v[224:227], v216 offset:8192
	v_add_f32_e32 v205, v132, v205
	v_add_f32_e32 v204, v133, v204
	v_cvt_pk_bf16_f32 v123, v132, v133
	v_permlane32_swap_b32_e32 v119, v121
	ds_read_b64_tr_b16 v[238:239], v206 offset:51200
	s_waitcnt lgkmcnt(5)
	v_mfma_f32_32x32x16_bf16 v[82:97], v[228:231], v[174:177], v[82:97]
	ds_read_b128 v[228:231], v215 offset:0
	v_add_f32_e32 v205, v134, v205
	v_add_f32_e32 v204, v135, v204
	v_cvt_pk_bf16_f32 v124, v134, v135
	ds_read_b64_tr_b16 v[240:241], v206 offset:53248
	s_waitcnt lgkmcnt(6)
	v_mfma_f32_32x32x16_bf16 v[98:113], v[232:235], v[174:177], v[98:113]
	ds_read_b128 v[232:235], v215 offset:8192
	v_add_f32_e32 v205, v136, v205
	v_add_f32_e32 v204, v137, v204
	v_cvt_pk_bf16_f32 v125, v136, v137
	ds_read_b64_tr_b16 v[242:243], v206 offset:55296
	s_waitcnt lgkmcnt(7)
	v_mfma_f32_32x32x16_bf16 v[82:97], v[220:223], v[162:165], v[82:97]
	v_add_f32_e32 v205, v138, v205
	v_add_f32_e32 v204, v139, v204
	v_cvt_pk_bf16_f32 v126, v138, v139
	v_permlane32_swap_b32_e32 v122, v124
	ds_read_b64_tr_b16 v[244:245], v206 offset:57344
	ds_read_b64_tr_b16 v[130:131], v206 offset:49664
	s_waitcnt lgkmcnt(7)
	v_mfma_f32_32x32x16_bf16 v[98:113], v[224:227], v[162:165], v[98:113]
	v_add_f32_e32 v205, v140, v205
	v_add_f32_e32 v204, v141, v204
	v_cvt_pk_bf16_f32 v127, v140, v141
	v_permlane32_swap_b32_e32 v123, v125
	ds_read_b64_tr_b16 v[246:247], v206 offset:59392
	ds_read_b64_tr_b16 v[132:133], v206 offset:51712
	s_waitcnt lgkmcnt(7)
	v_mfma_f32_32x32x16_bf16 v[82:97], v[228:231], v[170:173], v[82:97]
	v_add_f32_e32 v205, v142, v205
	v_add_f32_e32 v204, v143, v204
	v_cvt_pk_bf16_f32 v128, v142, v143
	ds_read_b64_tr_b16 v[248:249], v206 offset:61440
	ds_read_b64_tr_b16 v[134:135], v206 offset:53760
	s_waitcnt lgkmcnt(7)
	v_mfma_f32_32x32x16_bf16 v[98:113], v[232:235], v[170:173], v[98:113]
	v_add_f32_e32 v205, v144, v205
	v_add_f32_e32 v204, v145, v204
	v_cvt_pk_bf16_f32 v129, v144, v145
	ds_read_b64_tr_b16 v[250:251], v206 offset:63488
	ds_read_b64_tr_b16 v[136:137], v206 offset:55808
	v_mfma_f32_32x32x16_bf16 v[18:33], v[114:117], v[236:239], v[18:33]
	v_permlane32_swap_b32_e32 v126, v128
	v_permlane32_swap_b32_e32 v127, v129
	ds_read_b64_tr_b16 v[236:237], v206 offset:57856
	ds_read_b64_tr_b16 v[238:239], v206 offset:59904
	s_waitcnt lgkmcnt(10)
	v_mfma_f32_32x32x16_bf16 v[18:33], v[118:121], v[240:243], v[18:33]
	ds_read_b64_tr_b16 v[240:241], v206 offset:61952
	ds_read_b64_tr_b16 v[242:243], v206 offset:64000
	v_exp_f32_e32 v82, v82
	v_exp_f32_e32 v83, v83
	s_waitcnt lgkmcnt(9)
	v_mfma_f32_32x32x16_bf16 v[18:33], v[122:125], v[244:247], v[18:33]
	ds_read_b64_tr_b16 v[244:245], v206 offset:50176
	ds_read_b64_tr_b16 v[246:247], v206 offset:52224
	v_exp_f32_e32 v84, v84
	v_exp_f32_e32 v85, v85
	s_waitcnt lgkmcnt(7)
; #define SBAR() __builtin_amdgcn_sched_barrier(0)
; #define SLOAD(i, k0) do { sr_[i].vs0 = St::ld8(&Vh[(long)((k0) + sr) * LDK + sc]); sr_[i].vs1 = St::ld8(&Vh[(long)((k0) + 32 + sr) * LDK + sc]); \
;     sr_[i].ks0 = St::ld8(&Kh[(long)((k0) + sr) * LDK + sc]); sr_[i].ks1 = St::ld8(&Kh[(long)((k0) + 32 + sr) * LDK + sc]); } while (0)
; #define SWAIT() do { if constexpr (SDEPTH == 2) asm volatile("s_waitcnt vmcnt(4)" ::: "memory"); else asm volatile("s_waitcnt vmcnt(0)" ::: "memory"); } while (0)
; template <typename TQ> ...
;     ...
;   for (int j = 1; j + 1 < NT; j += 2) {
;     SBAR(); SLOAD(SO, (j + SDEPTH) * KVBLK); SBAR();
;     qkt(pB0, pB1, (bf16*)((char*)K_lds + SHM_K), qr, r32, hi, negm);
;     finishSM(pA0, pA1, l_reg, pa0, pa1, pa2, pa3); SBAR();
;     pv_d0(o, vb0, pa0, pa1, pa2, pa3); partialSM(pB0, pB1, mC);
;     __syncthreads(); SWAIT(); SWRITE(0, SE);
;     __syncthreads();
;     SBAR(); if (SDEPTH == 1 || j + 3 < NT) SLOAD(SE, (j + 1 + SDEPTH) * KVBLK); SBAR();
;     qkt(pA0, pA1, K_lds, qr, r32, hi, negm);
;     finishSM(pB0, pB1, l_reg, pa0, pa1, pa2, pa3); SBAR();
;     pv_d0(o, vb0 + (int)SHM_V, pa0, pa1, pa2, pa3); partialSM(pA0, pA1, mC);
;     __syncthreads(); SWAIT(); SWRITE(1, SO);
;     __syncthreads();
;   }
;   SBAR(); qkt(pB0, pB1, (bf16*)((char*)K_lds + SHM_K), qr, r32, hi, negm);
;   finishSM(pA0, pA1, l_reg, pa0, pa1, pa2, pa3); SBAR();
;   pv_d0(o, vb0, pa0, pa1, pa2, pa3); partialSM(pB0, pB1, mC);
;   __syncthreads();
	v_mfma_f32_32x32x16_bf16 v[18:33], v[126:129], v[248:251], v[18:33]
	ds_read_b64_tr_b16 v[248:249], v206 offset:54272
	ds_read_b64_tr_b16 v[250:251], v206 offset:56320
	v_exp_f32_e32 v86, v86
	v_exp_f32_e32 v87, v87
	v_mfma_f32_32x32x16_bf16 v[34:49], v[114:117], v[130:133], v[34:49]
	ds_read_b64_tr_b16 v[130:131], v206 offset:58368
	ds_read_b64_tr_b16 v[132:133], v206 offset:60416
	v_exp_f32_e32 v88, v88
	v_exp_f32_e32 v89, v89
	s_waitcnt lgkmcnt(10)
	v_mfma_f32_32x32x16_bf16 v[34:49], v[118:121], v[134:137], v[34:49]
	ds_read_b64_tr_b16 v[134:135], v206 offset:62464
	ds_read_b64_tr_b16 v[136:137], v206 offset:64512
	v_exp_f32_e32 v90, v90
	v_exp_f32_e32 v91, v91
	s_waitcnt lgkmcnt(10)
	v_mfma_f32_32x32x16_bf16 v[34:49], v[122:125], v[236:239], v[34:49]
	ds_read_b64_tr_b16 v[236:237], v206 offset:50688
	ds_read_b64_tr_b16 v[238:239], v206 offset:52736
	v_exp_f32_e32 v92, v92
	v_exp_f32_e32 v93, v93
	s_waitcnt lgkmcnt(10)
	v_mfma_f32_32x32x16_bf16 v[34:49], v[126:129], v[240:243], v[34:49]
	ds_read_b64_tr_b16 v[240:241], v206 offset:54784
	ds_read_b64_tr_b16 v[242:243], v206 offset:56832
	v_exp_f32_e32 v94, v94
	v_exp_f32_e32 v95, v95
	s_waitcnt lgkmcnt(10)
	v_mfma_f32_32x32x16_bf16 v[50:65], v[114:117], v[244:247], v[50:65]
	ds_read_b64_tr_b16 v[244:245], v206 offset:58880
	ds_read_b64_tr_b16 v[246:247], v206 offset:60928
	v_exp_f32_e32 v96, v96
	v_exp_f32_e32 v97, v97
	s_waitcnt lgkmcnt(10)
	v_mfma_f32_32x32x16_bf16 v[50:65], v[118:121], v[248:251], v[50:65]
	ds_read_b64_tr_b16 v[248:249], v206 offset:62976
	ds_read_b64_tr_b16 v[250:251], v206 offset:65024
	v_exp_f32_e32 v98, v98
	v_exp_f32_e32 v99, v99
	s_waitcnt lgkmcnt(10)
	v_mfma_f32_32x32x16_bf16 v[50:65], v[122:125], v[130:133], v[50:65]
	v_exp_f32_e32 v100, v100
	v_exp_f32_e32 v101, v101
	s_waitcnt lgkmcnt(8)
	v_mfma_f32_32x32x16_bf16 v[50:65], v[126:129], v[134:137], v[50:65]
	v_exp_f32_e32 v102, v102
	v_exp_f32_e32 v103, v103
	s_waitcnt lgkmcnt(6)
	v_mfma_f32_32x32x16_bf16 v[66:81], v[114:117], v[236:239], v[66:81]
	v_exp_f32_e32 v104, v104
	v_exp_f32_e32 v105, v105
	ds_read_b128 v[220:223], v210 offset:16384
	s_waitcnt lgkmcnt(5)
	v_mfma_f32_32x32x16_bf16 v[66:81], v[118:121], v[240:243], v[66:81]
	v_exp_f32_e32 v106, v106
	v_exp_f32_e32 v107, v107
	ds_read_b128 v[224:227], v210 offset:24576
	s_waitcnt lgkmcnt(4)
	v_mfma_f32_32x32x16_bf16 v[66:81], v[122:125], v[244:247], v[66:81]
	v_exp_f32_e32 v108, v108
	v_exp_f32_e32 v109, v109
	ds_read_b128 v[228:231], v212 offset:16384
	s_waitcnt lgkmcnt(3)
	v_mfma_f32_32x32x16_bf16 v[66:81], v[126:129], v[248:251], v[66:81]
	v_exp_f32_e32 v110, v110
	v_exp_f32_e32 v111, v111
	v_exp_f32_e32 v112, v112
	v_exp_f32_e32 v113, v113
	ds_read_b128 v[232:235], v212 offset:24576
	s_add_i32 s0, s0, 1
	s_cmp_lt_u32 s0, 32
	s_cbranch_scc1 .Lattn_loop
	s_barrier
	s_waitcnt lgkmcnt(3)
	v_mfma_f32_32x32x16_bf16 v[114:129], v[220:223], v[150:153], v[2:17]
	ds_read_b128 v[220:223], v213 offset:16384
	v_add_f32_e32 v205, v82, v205
	v_add_f32_e32 v204, v83, v204
	v_cvt_pk_bf16_f32 v82, v82, v83
	s_waitcnt lgkmcnt(3)
	v_mfma_f32_32x32x16_bf16 v[130:145], v[224:227], v[150:153], v[2:17]
	ds_read_b128 v[224:227], v213 offset:24576
	v_add_f32_e32 v205, v84, v205
	v_add_f32_e32 v204, v85, v204
	v_cvt_pk_bf16_f32 v83, v84, v85
	s_waitcnt lgkmcnt(3)
	v_mfma_f32_32x32x16_bf16 v[114:129], v[228:231], v[158:161], v[114:129]
	ds_read_b128 v[228:231], v214 offset:16384
	v_add_f32_e32 v205, v86, v205
	v_add_f32_e32 v204, v87, v204
	v_cvt_pk_bf16_f32 v84, v86, v87
	s_waitcnt vmcnt(0)
	ds_write_b128 v207, v[178:181] offset:49152
	ds_write_b128 v208, v[182:185] offset:49152
	s_waitcnt lgkmcnt(5)
	v_mfma_f32_32x32x16_bf16 v[130:145], v[232:235], v[158:161], v[130:145]
	ds_read_b128 v[232:235], v214 offset:24576
	v_add_f32_e32 v205, v88, v205
	v_add_f32_e32 v204, v89, v204
	v_cvt_pk_bf16_f32 v85, v88, v89
	ds_write_b128 v209, v[186:189] offset:49152
	ds_write_b128 v211, v[190:193] offset:49152
	s_waitcnt lgkmcnt(7)
	v_mfma_f32_32x32x16_bf16 v[114:129], v[220:223], v[146:149], v[114:129]
	ds_read_b128 v[220:223], v218 offset:16384
	v_add_f32_e32 v205, v90, v205
	v_add_f32_e32 v204, v91, v204
	v_cvt_pk_bf16_f32 v86, v90, v91
	v_permlane32_swap_b32_e32 v82, v84
	s_waitcnt lgkmcnt(7)
	v_mfma_f32_32x32x16_bf16 v[130:145], v[224:227], v[146:149], v[130:145]
	ds_read_b128 v[224:227], v218 offset:24576
	v_add_f32_e32 v205, v92, v205
	v_add_f32_e32 v204, v93, v204
	v_cvt_pk_bf16_f32 v87, v92, v93
	v_permlane32_swap_b32_e32 v83, v85
	s_waitcnt lgkmcnt(7)
	v_mfma_f32_32x32x16_bf16 v[114:129], v[228:231], v[154:157], v[114:129]
	ds_read_b128 v[228:231], v217 offset:16384
	v_add_f32_e32 v205, v94, v205
	v_add_f32_e32 v204, v95, v204
	v_cvt_pk_bf16_f32 v88, v94, v95
	s_waitcnt lgkmcnt(5)
	v_mfma_f32_32x32x16_bf16 v[130:145], v[232:235], v[154:157], v[130:145]
	ds_read_b128 v[232:235], v217 offset:24576
	v_add_f32_e32 v205, v96, v205
	v_add_f32_e32 v204, v97, v204
	v_cvt_pk_bf16_f32 v89, v96, v97
	s_waitcnt lgkmcnt(3)
	v_mfma_f32_32x32x16_bf16 v[114:129], v[220:223], v[166:169], v[114:129]
	ds_read_b128 v[220:223], v216 offset:16384
	v_add_f32_e32 v205, v98, v205
	v_add_f32_e32 v204, v99, v204
	v_cvt_pk_bf16_f32 v90, v98, v99
	v_permlane32_swap_b32_e32 v86, v88
	ds_read_b64_tr_b16 v[236:237], v206 offset:0
	s_waitcnt lgkmcnt(4)
	v_mfma_f32_32x32x16_bf16 v[130:145], v[224:227], v[166:169], v[130:145]
	ds_read_b128 v[224:227], v216 offset:24576
	v_add_f32_e32 v205, v100, v205
	v_add_f32_e32 v204, v101, v204
	v_cvt_pk_bf16_f32 v91, v100, v101
	v_permlane32_swap_b32_e32 v87, v89
	ds_read_b64_tr_b16 v[238:239], v206 offset:2048
	s_waitcnt lgkmcnt(5)
; #define SBAR() __builtin_amdgcn_sched_barrier(0)
; template <typename TQ> ...
;     ...
;   SBAR(); qkt(pB0, pB1, (bf16*)((char*)K_lds + SHM_K), qr, r32, hi, negm);
;   finishSM(pA0, pA1, l_reg, pa0, pa1, pa2, pa3); SBAR();
;   pv_d0(o, vb0, pa0, pa1, pa2, pa3); partialSM(pB0, pB1, mC);
;   __syncthreads();
;   finishSM(pB0, pB1, l_reg, pa0, pa1, pa2, pa3); SBAR();
	v_mfma_f32_32x32x16_bf16 v[114:129], v[228:231], v[174:177], v[114:129]
	ds_read_b128 v[228:231], v215 offset:16384
	v_add_f32_e32 v205, v102, v205
	v_add_f32_e32 v204, v103, v204
	v_cvt_pk_bf16_f32 v92, v102, v103
	ds_read_b64_tr_b16 v[240:241], v206 offset:4096
	s_waitcnt lgkmcnt(6)
	v_mfma_f32_32x32x16_bf16 v[130:145], v[232:235], v[174:177], v[130:145]
	ds_read_b128 v[232:235], v215 offset:24576
	v_add_f32_e32 v205, v104, v205
	v_add_f32_e32 v204, v105, v204
	v_cvt_pk_bf16_f32 v93, v104, v105
	ds_read_b64_tr_b16 v[242:243], v206 offset:6144
	s_waitcnt lgkmcnt(7)
	v_mfma_f32_32x32x16_bf16 v[114:129], v[220:223], v[162:165], v[114:129]
	v_add_f32_e32 v205, v106, v205
	v_add_f32_e32 v204, v107, v204
	v_cvt_pk_bf16_f32 v94, v106, v107
	v_permlane32_swap_b32_e32 v90, v92
	ds_read_b64_tr_b16 v[244:245], v206 offset:8192
	ds_read_b64_tr_b16 v[98:99], v206 offset:512
	s_waitcnt lgkmcnt(7)
	v_mfma_f32_32x32x16_bf16 v[130:145], v[224:227], v[162:165], v[130:145]
	v_add_f32_e32 v205, v108, v205
	v_add_f32_e32 v204, v109, v204
	v_cvt_pk_bf16_f32 v95, v108, v109
	v_permlane32_swap_b32_e32 v91, v93
	ds_read_b64_tr_b16 v[246:247], v206 offset:10240
	ds_read_b64_tr_b16 v[100:101], v206 offset:2560
	s_waitcnt lgkmcnt(7)
	v_mfma_f32_32x32x16_bf16 v[114:129], v[228:231], v[170:173], v[114:129]
	v_add_f32_e32 v205, v110, v205
	v_add_f32_e32 v204, v111, v204
	v_cvt_pk_bf16_f32 v96, v110, v111
	ds_read_b64_tr_b16 v[248:249], v206 offset:12288
	ds_read_b64_tr_b16 v[102:103], v206 offset:4608
	s_waitcnt lgkmcnt(7)
	v_mfma_f32_32x32x16_bf16 v[130:145], v[232:235], v[170:173], v[130:145]
	v_add_f32_e32 v205, v112, v205
	v_add_f32_e32 v204, v113, v204
	v_cvt_pk_bf16_f32 v97, v112, v113
	ds_read_b64_tr_b16 v[250:251], v206 offset:14336
	ds_read_b64_tr_b16 v[104:105], v206 offset:6656
	v_mfma_f32_32x32x16_bf16 v[18:33], v[82:85], v[236:239], v[18:33]
	v_permlane32_swap_b32_e32 v94, v96
	v_permlane32_swap_b32_e32 v95, v97
	ds_read_b64_tr_b16 v[236:237], v206 offset:8704
	ds_read_b64_tr_b16 v[238:239], v206 offset:10752
	s_waitcnt lgkmcnt(10)
	v_mfma_f32_32x32x16_bf16 v[18:33], v[86:89], v[240:243], v[18:33]
	ds_read_b64_tr_b16 v[240:241], v206 offset:12800
	ds_read_b64_tr_b16 v[242:243], v206 offset:14848
	v_exp_f32_e32 v114, v114
	v_exp_f32_e32 v115, v115
	s_waitcnt lgkmcnt(9)
	v_mfma_f32_32x32x16_bf16 v[18:33], v[90:93], v[244:247], v[18:33]
	ds_read_b64_tr_b16 v[244:245], v206 offset:1024
	ds_read_b64_tr_b16 v[246:247], v206 offset:3072
	v_exp_f32_e32 v116, v116
	v_exp_f32_e32 v117, v117
	s_waitcnt lgkmcnt(7)
	v_mfma_f32_32x32x16_bf16 v[18:33], v[94:97], v[248:251], v[18:33]
	ds_read_b64_tr_b16 v[248:249], v206 offset:5120
	ds_read_b64_tr_b16 v[250:251], v206 offset:7168
	v_exp_f32_e32 v118, v118
	v_exp_f32_e32 v119, v119
	v_mfma_f32_32x32x16_bf16 v[34:49], v[82:85], v[98:101], v[34:49]
	ds_read_b64_tr_b16 v[98:99], v206 offset:9216
	ds_read_b64_tr_b16 v[100:101], v206 offset:11264
	v_exp_f32_e32 v120, v120
	v_exp_f32_e32 v121, v121
	s_waitcnt lgkmcnt(10)
	v_mfma_f32_32x32x16_bf16 v[34:49], v[86:89], v[102:105], v[34:49]
	ds_read_b64_tr_b16 v[102:103], v206 offset:13312
	ds_read_b64_tr_b16 v[104:105], v206 offset:15360
	v_exp_f32_e32 v122, v122
	v_exp_f32_e32 v123, v123
	s_waitcnt lgkmcnt(10)
	v_mfma_f32_32x32x16_bf16 v[34:49], v[90:93], v[236:239], v[34:49]
	ds_read_b64_tr_b16 v[236:237], v206 offset:1536
	ds_read_b64_tr_b16 v[238:239], v206 offset:3584
	v_exp_f32_e32 v124, v124
	v_exp_f32_e32 v125, v125
	s_waitcnt lgkmcnt(10)
	v_mfma_f32_32x32x16_bf16 v[34:49], v[94:97], v[240:243], v[34:49]
	ds_read_b64_tr_b16 v[240:241], v206 offset:5632
	ds_read_b64_tr_b16 v[242:243], v206 offset:7680
	v_exp_f32_e32 v126, v126
	v_exp_f32_e32 v127, v127
	s_waitcnt lgkmcnt(10)
	v_mfma_f32_32x32x16_bf16 v[50:65], v[82:85], v[244:247], v[50:65]
	ds_read_b64_tr_b16 v[244:245], v206 offset:9728
	ds_read_b64_tr_b16 v[246:247], v206 offset:11776
	v_exp_f32_e32 v128, v128
	v_exp_f32_e32 v129, v129
	s_waitcnt lgkmcnt(10)
	v_mfma_f32_32x32x16_bf16 v[50:65], v[86:89], v[248:251], v[50:65]
	ds_read_b64_tr_b16 v[248:249], v206 offset:13824
	ds_read_b64_tr_b16 v[250:251], v206 offset:15872
	v_exp_f32_e32 v130, v130
	v_exp_f32_e32 v131, v131
	s_waitcnt lgkmcnt(10)
	v_mfma_f32_32x32x16_bf16 v[50:65], v[90:93], v[98:101], v[50:65]
	v_exp_f32_e32 v132, v132
	v_exp_f32_e32 v133, v133
	s_waitcnt lgkmcnt(8)
	v_mfma_f32_32x32x16_bf16 v[50:65], v[94:97], v[102:105], v[50:65]
	v_exp_f32_e32 v134, v134
	v_exp_f32_e32 v135, v135
	s_waitcnt lgkmcnt(6)
	v_mfma_f32_32x32x16_bf16 v[66:81], v[82:85], v[236:239], v[66:81]
	v_exp_f32_e32 v136, v136
	v_exp_f32_e32 v137, v137
	ds_read_b128 v[220:223], v210 offset:32768
	s_waitcnt lgkmcnt(5)
	v_mfma_f32_32x32x16_bf16 v[66:81], v[86:89], v[240:243], v[66:81]
	v_exp_f32_e32 v138, v138
	v_exp_f32_e32 v139, v139
	ds_read_b128 v[224:227], v210 offset:40960
	s_waitcnt lgkmcnt(4)
	v_mfma_f32_32x32x16_bf16 v[66:81], v[90:93], v[244:247], v[66:81]
	v_exp_f32_e32 v140, v140
	v_exp_f32_e32 v141, v141
	ds_read_b128 v[228:231], v212 offset:32768
	s_waitcnt lgkmcnt(3)
	v_mfma_f32_32x32x16_bf16 v[66:81], v[94:97], v[248:251], v[66:81]
	v_exp_f32_e32 v142, v142
	v_exp_f32_e32 v143, v143
	v_exp_f32_e32 v144, v144
	v_exp_f32_e32 v145, v145
	ds_read_b128 v[232:235], v212 offset:40960
	s_barrier
; #define SBAR() __builtin_amdgcn_sched_barrier(0)
; template <typename TQ> ...
;     ...
;   SBAR(); qkt(pB0, pB1, (bf16*)((char*)K_lds + SHM_K), qr, r32, hi, negm);
;   finishSM(pA0, pA1, l_reg, pa0, pa1, pa2, pa3); SBAR();
;   pv_d0(o, vb0, pa0, pa1, pa2, pa3); partialSM(pB0, pB1, mC);
;   __syncthreads();
;   finishSM(pB0, pB1, l_reg, pa0, pa1, pa2, pa3); SBAR();
	s_waitcnt lgkmcnt(3)
	v_mfma_f32_32x32x16_bf16 v[82:97], v[220:223], v[150:153], v[2:17]
	ds_read_b128 v[220:223], v213 offset:32768
	v_add_f32_e32 v205, v114, v205
	v_add_f32_e32 v204, v115, v204
	v_cvt_pk_bf16_f32 v114, v114, v115
	s_waitcnt lgkmcnt(3)
	v_mfma_f32_32x32x16_bf16 v[98:113], v[224:227], v[150:153], v[2:17]
	ds_read_b128 v[224:227], v213 offset:40960
	v_add_f32_e32 v205, v116, v205
	v_add_f32_e32 v204, v117, v204
	v_cvt_pk_bf16_f32 v115, v116, v117
	s_waitcnt lgkmcnt(3)
	v_mfma_f32_32x32x16_bf16 v[82:97], v[228:231], v[158:161], v[82:97]
	ds_read_b128 v[228:231], v214 offset:32768
	v_add_f32_e32 v205, v118, v205
	v_add_f32_e32 v204, v119, v204
	v_cvt_pk_bf16_f32 v116, v118, v119
	s_waitcnt lgkmcnt(3)
	v_mfma_f32_32x32x16_bf16 v[98:113], v[232:235], v[158:161], v[98:113]
	ds_read_b128 v[232:235], v214 offset:40960
	v_add_f32_e32 v205, v120, v205
	v_add_f32_e32 v204, v121, v204
	v_cvt_pk_bf16_f32 v117, v120, v121
	s_waitcnt lgkmcnt(3)
	v_mfma_f32_32x32x16_bf16 v[82:97], v[220:223], v[146:149], v[82:97]
	ds_read_b128 v[220:223], v218 offset:32768
	v_add_f32_e32 v205, v122, v205
	v_add_f32_e32 v204, v123, v204
	v_cvt_pk_bf16_f32 v118, v122, v123
	v_permlane32_swap_b32_e32 v114, v116
	s_waitcnt lgkmcnt(3)
	v_mfma_f32_32x32x16_bf16 v[98:113], v[224:227], v[146:149], v[98:113]
	ds_read_b128 v[224:227], v218 offset:40960
	v_add_f32_e32 v205, v124, v205
	v_add_f32_e32 v204, v125, v204
	v_cvt_pk_bf16_f32 v119, v124, v125
	v_permlane32_swap_b32_e32 v115, v117
	s_waitcnt lgkmcnt(3)
	v_mfma_f32_32x32x16_bf16 v[82:97], v[228:231], v[154:157], v[82:97]
	ds_read_b128 v[228:231], v217 offset:32768
	v_add_f32_e32 v205, v126, v205
	v_add_f32_e32 v204, v127, v204
	v_cvt_pk_bf16_f32 v120, v126, v127
	s_waitcnt lgkmcnt(3)
	v_mfma_f32_32x32x16_bf16 v[98:113], v[232:235], v[154:157], v[98:113]
	ds_read_b128 v[232:235], v217 offset:40960
	v_add_f32_e32 v205, v128, v205
	v_add_f32_e32 v204, v129, v204
	v_cvt_pk_bf16_f32 v121, v128, v129
	s_waitcnt lgkmcnt(3)
	v_mfma_f32_32x32x16_bf16 v[82:97], v[220:223], v[166:169], v[82:97]
	ds_read_b128 v[220:223], v216 offset:32768
	v_add_f32_e32 v205, v130, v205
	v_add_f32_e32 v204, v131, v204
	v_cvt_pk_bf16_f32 v122, v130, v131
	v_permlane32_swap_b32_e32 v118, v120
	ds_read_b64_tr_b16 v[236:237], v206 offset:16384
	s_waitcnt lgkmcnt(4)
	v_mfma_f32_32x32x16_bf16 v[98:113], v[224:227], v[166:169], v[98:113]
	ds_read_b128 v[224:227], v216 offset:40960
	v_add_f32_e32 v205, v132, v205
	v_add_f32_e32 v204, v133, v204
	v_cvt_pk_bf16_f32 v123, v132, v133
	v_permlane32_swap_b32_e32 v119, v121
	ds_read_b64_tr_b16 v[238:239], v206 offset:18432
	s_waitcnt lgkmcnt(5)
	v_mfma_f32_32x32x16_bf16 v[82:97], v[228:231], v[174:177], v[82:97]
	ds_read_b128 v[228:231], v215 offset:32768
	v_add_f32_e32 v205, v134, v205
	v_add_f32_e32 v204, v135, v204
	v_cvt_pk_bf16_f32 v124, v134, v135
	ds_read_b64_tr_b16 v[240:241], v206 offset:20480
	s_waitcnt lgkmcnt(6)
	v_mfma_f32_32x32x16_bf16 v[98:113], v[232:235], v[174:177], v[98:113]
	ds_read_b128 v[232:235], v215 offset:40960
	v_add_f32_e32 v205, v136, v205
	v_add_f32_e32 v204, v137, v204
	v_cvt_pk_bf16_f32 v125, v136, v137
	ds_read_b64_tr_b16 v[242:243], v206 offset:22528
	s_waitcnt lgkmcnt(7)
	v_mfma_f32_32x32x16_bf16 v[82:97], v[220:223], v[162:165], v[82:97]
	v_add_f32_e32 v205, v138, v205
	v_add_f32_e32 v204, v139, v204
	v_cvt_pk_bf16_f32 v126, v138, v139
	v_permlane32_swap_b32_e32 v122, v124
	ds_read_b64_tr_b16 v[244:245], v206 offset:24576
	ds_read_b64_tr_b16 v[130:131], v206 offset:16896
	s_waitcnt lgkmcnt(7)
	v_mfma_f32_32x32x16_bf16 v[98:113], v[224:227], v[162:165], v[98:113]
	v_add_f32_e32 v205, v140, v205
	v_add_f32_e32 v204, v141, v204
	v_cvt_pk_bf16_f32 v127, v140, v141
	v_permlane32_swap_b32_e32 v123, v125
	ds_read_b64_tr_b16 v[246:247], v206 offset:26624
	ds_read_b64_tr_b16 v[132:133], v206 offset:18944
	s_waitcnt lgkmcnt(7)
	v_mfma_f32_32x32x16_bf16 v[82:97], v[228:231], v[170:173], v[82:97]
	v_add_f32_e32 v205, v142, v205
	v_add_f32_e32 v204, v143, v204
	v_cvt_pk_bf16_f32 v128, v142, v143
	ds_read_b64_tr_b16 v[248:249], v206 offset:28672
	ds_read_b64_tr_b16 v[134:135], v206 offset:20992
	s_waitcnt lgkmcnt(7)
	v_mfma_f32_32x32x16_bf16 v[98:113], v[232:235], v[170:173], v[98:113]
	v_add_f32_e32 v205, v144, v205
	v_add_f32_e32 v204, v145, v204
	v_cvt_pk_bf16_f32 v129, v144, v145
	ds_read_b64_tr_b16 v[250:251], v206 offset:30720
	ds_read_b64_tr_b16 v[136:137], v206 offset:23040
	v_mfma_f32_32x32x16_bf16 v[18:33], v[114:117], v[236:239], v[18:33]
	v_permlane32_swap_b32_e32 v126, v128
	v_permlane32_swap_b32_e32 v127, v129
	ds_read_b64_tr_b16 v[236:237], v206 offset:25088
	ds_read_b64_tr_b16 v[238:239], v206 offset:27136
	s_waitcnt lgkmcnt(10)
	v_mfma_f32_32x32x16_bf16 v[18:33], v[118:121], v[240:243], v[18:33]
	ds_read_b64_tr_b16 v[240:241], v206 offset:29184
	ds_read_b64_tr_b16 v[242:243], v206 offset:31232
	v_exp_f32_e32 v82, v82
	v_exp_f32_e32 v83, v83
	s_waitcnt lgkmcnt(9)
	v_mfma_f32_32x32x16_bf16 v[18:33], v[122:125], v[244:247], v[18:33]
	ds_read_b64_tr_b16 v[244:245], v206 offset:17408
	ds_read_b64_tr_b16 v[246:247], v206 offset:19456
	v_exp_f32_e32 v84, v84
	v_exp_f32_e32 v85, v85
	s_waitcnt lgkmcnt(7)
	v_mfma_f32_32x32x16_bf16 v[18:33], v[126:129], v[248:251], v[18:33]
	ds_read_b64_tr_b16 v[248:249], v206 offset:21504
	ds_read_b64_tr_b16 v[250:251], v206 offset:23552
	v_exp_f32_e32 v86, v86
	v_exp_f32_e32 v87, v87
	v_mfma_f32_32x32x16_bf16 v[34:49], v[114:117], v[130:133], v[34:49]
	ds_read_b64_tr_b16 v[130:131], v206 offset:25600
	ds_read_b64_tr_b16 v[132:133], v206 offset:27648
	v_exp_f32_e32 v88, v88
	v_exp_f32_e32 v89, v89
	s_waitcnt lgkmcnt(10)
; #define SBAR() __builtin_amdgcn_sched_barrier(0)
; template <typename TQ> ...
;     ...
;   SBAR(); qkt(pB0, pB1, (bf16*)((char*)K_lds + SHM_K), qr, r32, hi, negm);
;   finishSM(pA0, pA1, l_reg, pa0, pa1, pa2, pa3); SBAR();
;   pv_d0(o, vb0, pa0, pa1, pa2, pa3); partialSM(pB0, pB1, mC);
;   __syncthreads();
;   finishSM(pB0, pB1, l_reg, pa0, pa1, pa2, pa3); SBAR();
	v_mfma_f32_32x32x16_bf16 v[34:49], v[118:121], v[134:137], v[34:49]
	ds_read_b64_tr_b16 v[134:135], v206 offset:29696
	ds_read_b64_tr_b16 v[136:137], v206 offset:31744
	v_exp_f32_e32 v90, v90
	v_exp_f32_e32 v91, v91
	s_waitcnt lgkmcnt(10)
	v_mfma_f32_32x32x16_bf16 v[34:49], v[122:125], v[236:239], v[34:49]
	ds_read_b64_tr_b16 v[236:237], v206 offset:17920
	ds_read_b64_tr_b16 v[238:239], v206 offset:19968
	v_exp_f32_e32 v92, v92
	v_exp_f32_e32 v93, v93
	s_waitcnt lgkmcnt(10)
	v_mfma_f32_32x32x16_bf16 v[34:49], v[126:129], v[240:243], v[34:49]
	ds_read_b64_tr_b16 v[240:241], v206 offset:22016
	ds_read_b64_tr_b16 v[242:243], v206 offset:24064
	v_exp_f32_e32 v94, v94
	v_exp_f32_e32 v95, v95
	s_waitcnt lgkmcnt(10)
	v_mfma_f32_32x32x16_bf16 v[50:65], v[114:117], v[244:247], v[50:65]
	ds_read_b64_tr_b16 v[244:245], v206 offset:26112
	ds_read_b64_tr_b16 v[246:247], v206 offset:28160
	v_exp_f32_e32 v96, v96
	v_exp_f32_e32 v97, v97
	s_waitcnt lgkmcnt(10)
	v_mfma_f32_32x32x16_bf16 v[50:65], v[118:121], v[248:251], v[50:65]
	ds_read_b64_tr_b16 v[248:249], v206 offset:30208
	ds_read_b64_tr_b16 v[250:251], v206 offset:32256
	v_exp_f32_e32 v98, v98
	v_exp_f32_e32 v99, v99
	s_waitcnt lgkmcnt(10)
	v_mfma_f32_32x32x16_bf16 v[50:65], v[122:125], v[130:133], v[50:65]
	v_exp_f32_e32 v100, v100
	v_exp_f32_e32 v101, v101
	s_waitcnt lgkmcnt(8)
	v_mfma_f32_32x32x16_bf16 v[50:65], v[126:129], v[134:137], v[50:65]
	v_exp_f32_e32 v102, v102
	v_exp_f32_e32 v103, v103
	s_waitcnt lgkmcnt(6)
	v_mfma_f32_32x32x16_bf16 v[66:81], v[114:117], v[236:239], v[66:81]
	v_exp_f32_e32 v104, v104
	v_exp_f32_e32 v105, v105
	ds_read_b128 v[220:223], v210 offset:49152
	s_waitcnt lgkmcnt(5)
	v_mfma_f32_32x32x16_bf16 v[66:81], v[118:121], v[240:243], v[66:81]
	v_exp_f32_e32 v106, v106
	v_exp_f32_e32 v107, v107
	ds_read_b128 v[224:227], v210 offset:57344
	s_waitcnt lgkmcnt(4)
	v_mfma_f32_32x32x16_bf16 v[66:81], v[122:125], v[244:247], v[66:81]
	v_exp_f32_e32 v108, v108
	v_exp_f32_e32 v109, v109
	ds_read_b128 v[228:231], v212 offset:49152
	s_waitcnt lgkmcnt(3)
	v_mfma_f32_32x32x16_bf16 v[66:81], v[126:129], v[248:251], v[66:81]
	v_exp_f32_e32 v110, v110
	v_exp_f32_e32 v111, v111
	v_exp_f32_e32 v112, v112
	v_exp_f32_e32 v113, v113
	ds_read_b128 v[232:235], v212 offset:57344
	s_barrier
	s_waitcnt lgkmcnt(3)
	v_mfma_f32_32x32x16_bf16 v[114:129], v[220:223], v[150:153], v[2:17]
	ds_read_b128 v[220:223], v213 offset:49152
	v_add_f32_e32 v205, v82, v205
	v_add_f32_e32 v204, v83, v204
	v_cvt_pk_bf16_f32 v82, v82, v83
	s_waitcnt lgkmcnt(3)
	v_mfma_f32_32x32x16_bf16 v[130:145], v[224:227], v[150:153], v[2:17]
	ds_read_b128 v[224:227], v213 offset:57344
	v_add_f32_e32 v205, v84, v205
	v_add_f32_e32 v204, v85, v204
	v_cvt_pk_bf16_f32 v83, v84, v85
	s_waitcnt lgkmcnt(3)
	v_mfma_f32_32x32x16_bf16 v[114:129], v[228:231], v[158:161], v[114:129]
	ds_read_b128 v[228:231], v214 offset:49152
	v_add_f32_e32 v205, v86, v205
	v_add_f32_e32 v204, v87, v204
	v_cvt_pk_bf16_f32 v84, v86, v87
	s_waitcnt lgkmcnt(3)
	v_mfma_f32_32x32x16_bf16 v[130:145], v[232:235], v[158:161], v[130:145]
	ds_read_b128 v[232:235], v214 offset:57344
	v_add_f32_e32 v205, v88, v205
	v_add_f32_e32 v204, v89, v204
	v_cvt_pk_bf16_f32 v85, v88, v89
	s_waitcnt lgkmcnt(3)
	v_mfma_f32_32x32x16_bf16 v[114:129], v[220:223], v[146:149], v[114:129]
	ds_read_b128 v[220:223], v218 offset:49152
	v_add_f32_e32 v205, v90, v205
	v_add_f32_e32 v204, v91, v204
	v_cvt_pk_bf16_f32 v86, v90, v91
	v_permlane32_swap_b32_e32 v82, v84
	s_waitcnt lgkmcnt(3)
	v_mfma_f32_32x32x16_bf16 v[130:145], v[224:227], v[146:149], v[130:145]
	ds_read_b128 v[224:227], v218 offset:57344
	v_add_f32_e32 v205, v92, v205
	v_add_f32_e32 v204, v93, v204
	v_cvt_pk_bf16_f32 v87, v92, v93
	v_permlane32_swap_b32_e32 v83, v85
	s_waitcnt lgkmcnt(3)
	v_mfma_f32_32x32x16_bf16 v[114:129], v[228:231], v[154:157], v[114:129]
	ds_read_b128 v[228:231], v217 offset:49152
	v_add_f32_e32 v205, v94, v205
	v_add_f32_e32 v204, v95, v204
	v_cvt_pk_bf16_f32 v88, v94, v95
	s_waitcnt lgkmcnt(3)
	v_mfma_f32_32x32x16_bf16 v[130:145], v[232:235], v[154:157], v[130:145]
	ds_read_b128 v[232:235], v217 offset:57344
	v_add_f32_e32 v205, v96, v205
	v_add_f32_e32 v204, v97, v204
	v_cvt_pk_bf16_f32 v89, v96, v97
	s_waitcnt lgkmcnt(3)
	v_mfma_f32_32x32x16_bf16 v[114:129], v[220:223], v[166:169], v[114:129]
	ds_read_b128 v[220:223], v216 offset:49152
	v_add_f32_e32 v205, v98, v205
	v_add_f32_e32 v204, v99, v204
	v_cvt_pk_bf16_f32 v90, v98, v99
	v_permlane32_swap_b32_e32 v86, v88
	ds_read_b64_tr_b16 v[236:237], v206 offset:32768
	s_waitcnt lgkmcnt(4)
	v_mfma_f32_32x32x16_bf16 v[130:145], v[224:227], v[166:169], v[130:145]
	ds_read_b128 v[224:227], v216 offset:57344
	v_add_f32_e32 v205, v100, v205
	v_add_f32_e32 v204, v101, v204
	v_cvt_pk_bf16_f32 v91, v100, v101
	v_permlane32_swap_b32_e32 v87, v89
	ds_read_b64_tr_b16 v[238:239], v206 offset:34816
	s_waitcnt lgkmcnt(5)
	v_mfma_f32_32x32x16_bf16 v[114:129], v[228:231], v[174:177], v[114:129]
	ds_read_b128 v[228:231], v215 offset:49152
	v_add_f32_e32 v205, v102, v205
	v_add_f32_e32 v204, v103, v204
	v_cvt_pk_bf16_f32 v92, v102, v103
	ds_read_b64_tr_b16 v[240:241], v206 offset:36864
	s_waitcnt lgkmcnt(6)
	v_mfma_f32_32x32x16_bf16 v[130:145], v[232:235], v[174:177], v[130:145]
	ds_read_b128 v[232:235], v215 offset:57344
	v_add_f32_e32 v205, v104, v205
	v_add_f32_e32 v204, v105, v204
	v_cvt_pk_bf16_f32 v93, v104, v105
	ds_read_b64_tr_b16 v[242:243], v206 offset:38912
	s_waitcnt lgkmcnt(7)
	v_mfma_f32_32x32x16_bf16 v[114:129], v[220:223], v[162:165], v[114:129]
	v_add_f32_e32 v205, v106, v205
	v_add_f32_e32 v204, v107, v204
	v_cvt_pk_bf16_f32 v94, v106, v107
	v_permlane32_swap_b32_e32 v90, v92
	ds_read_b64_tr_b16 v[244:245], v206 offset:40960
	ds_read_b64_tr_b16 v[98:99], v206 offset:33280
	s_waitcnt lgkmcnt(7)
; #define SBAR() __builtin_amdgcn_sched_barrier(0)
; template <typename TQ> ...
;     ...
;   SBAR(); qkt(pB0, pB1, (bf16*)((char*)K_lds + SHM_K), qr, r32, hi, negm);
;   finishSM(pA0, pA1, l_reg, pa0, pa1, pa2, pa3); SBAR();
;   pv_d0(o, vb0, pa0, pa1, pa2, pa3); partialSM(pB0, pB1, mC);
;   __syncthreads();
;   finishSM(pB0, pB1, l_reg, pa0, pa1, pa2, pa3); SBAR();
	v_mfma_f32_32x32x16_bf16 v[130:145], v[224:227], v[162:165], v[130:145]
	v_add_f32_e32 v205, v108, v205
	v_add_f32_e32 v204, v109, v204
	v_cvt_pk_bf16_f32 v95, v108, v109
	v_permlane32_swap_b32_e32 v91, v93
	ds_read_b64_tr_b16 v[246:247], v206 offset:43008
	ds_read_b64_tr_b16 v[100:101], v206 offset:35328
	s_waitcnt lgkmcnt(7)
	v_mfma_f32_32x32x16_bf16 v[114:129], v[228:231], v[170:173], v[114:129]
	v_add_f32_e32 v205, v110, v205
	v_add_f32_e32 v204, v111, v204
	v_cvt_pk_bf16_f32 v96, v110, v111
	ds_read_b64_tr_b16 v[248:249], v206 offset:45056
	ds_read_b64_tr_b16 v[102:103], v206 offset:37376
	s_waitcnt lgkmcnt(7)
	v_mfma_f32_32x32x16_bf16 v[130:145], v[232:235], v[170:173], v[130:145]
	v_add_f32_e32 v205, v112, v205
	v_add_f32_e32 v204, v113, v204
	v_cvt_pk_bf16_f32 v97, v112, v113
	ds_read_b64_tr_b16 v[250:251], v206 offset:47104
	ds_read_b64_tr_b16 v[104:105], v206 offset:39424
	v_mfma_f32_32x32x16_bf16 v[18:33], v[82:85], v[236:239], v[18:33]
	v_permlane32_swap_b32_e32 v94, v96
	v_permlane32_swap_b32_e32 v95, v97
	ds_read_b64_tr_b16 v[236:237], v206 offset:41472
	ds_read_b64_tr_b16 v[238:239], v206 offset:43520
	s_waitcnt lgkmcnt(10)
	v_mfma_f32_32x32x16_bf16 v[18:33], v[86:89], v[240:243], v[18:33]
	ds_read_b64_tr_b16 v[240:241], v206 offset:45568
	ds_read_b64_tr_b16 v[242:243], v206 offset:47616
	v_exp_f32_e32 v114, v114
	v_exp_f32_e32 v115, v115
	s_waitcnt lgkmcnt(9)
	v_mfma_f32_32x32x16_bf16 v[18:33], v[90:93], v[244:247], v[18:33]
	ds_read_b64_tr_b16 v[244:245], v206 offset:33792
	ds_read_b64_tr_b16 v[246:247], v206 offset:35840
	v_exp_f32_e32 v116, v116
	v_exp_f32_e32 v117, v117
	s_waitcnt lgkmcnt(7)
	v_mfma_f32_32x32x16_bf16 v[18:33], v[94:97], v[248:251], v[18:33]
	ds_read_b64_tr_b16 v[248:249], v206 offset:37888
	ds_read_b64_tr_b16 v[250:251], v206 offset:39936
	v_exp_f32_e32 v118, v118
	v_exp_f32_e32 v119, v119
	v_mfma_f32_32x32x16_bf16 v[34:49], v[82:85], v[98:101], v[34:49]
	ds_read_b64_tr_b16 v[98:99], v206 offset:41984
	ds_read_b64_tr_b16 v[100:101], v206 offset:44032
	v_exp_f32_e32 v120, v120
	v_exp_f32_e32 v121, v121
	s_waitcnt lgkmcnt(10)
	v_mfma_f32_32x32x16_bf16 v[34:49], v[86:89], v[102:105], v[34:49]
	ds_read_b64_tr_b16 v[102:103], v206 offset:46080
	ds_read_b64_tr_b16 v[104:105], v206 offset:48128
	v_exp_f32_e32 v122, v122
	v_exp_f32_e32 v123, v123
	s_waitcnt lgkmcnt(10)
	v_mfma_f32_32x32x16_bf16 v[34:49], v[90:93], v[236:239], v[34:49]
	ds_read_b64_tr_b16 v[236:237], v206 offset:34304
	ds_read_b64_tr_b16 v[238:239], v206 offset:36352
	v_exp_f32_e32 v124, v124
	v_exp_f32_e32 v125, v125
	s_waitcnt lgkmcnt(10)
	v_mfma_f32_32x32x16_bf16 v[34:49], v[94:97], v[240:243], v[34:49]
	ds_read_b64_tr_b16 v[240:241], v206 offset:38400
	ds_read_b64_tr_b16 v[242:243], v206 offset:40448
	v_exp_f32_e32 v126, v126
	v_exp_f32_e32 v127, v127
	s_waitcnt lgkmcnt(10)
	v_mfma_f32_32x32x16_bf16 v[50:65], v[82:85], v[244:247], v[50:65]
	ds_read_b64_tr_b16 v[244:245], v206 offset:42496
	ds_read_b64_tr_b16 v[246:247], v206 offset:44544
	v_exp_f32_e32 v128, v128
	v_exp_f32_e32 v129, v129
	s_waitcnt lgkmcnt(10)
	v_mfma_f32_32x32x16_bf16 v[50:65], v[86:89], v[248:251], v[50:65]
	ds_read_b64_tr_b16 v[248:249], v206 offset:46592
	ds_read_b64_tr_b16 v[250:251], v206 offset:48640
	v_exp_f32_e32 v130, v130
	v_exp_f32_e32 v131, v131
	s_waitcnt lgkmcnt(10)
	v_mfma_f32_32x32x16_bf16 v[50:65], v[90:93], v[98:101], v[50:65]
	v_exp_f32_e32 v132, v132
	v_exp_f32_e32 v133, v133
	s_waitcnt lgkmcnt(8)
	v_mfma_f32_32x32x16_bf16 v[50:65], v[94:97], v[102:105], v[50:65]
	v_exp_f32_e32 v134, v134
	v_exp_f32_e32 v135, v135
	s_waitcnt lgkmcnt(6)
	v_mfma_f32_32x32x16_bf16 v[66:81], v[82:85], v[236:239], v[66:81]
	v_exp_f32_e32 v136, v136
	v_exp_f32_e32 v137, v137
	s_waitcnt lgkmcnt(4)
	v_mfma_f32_32x32x16_bf16 v[66:81], v[86:89], v[240:243], v[66:81]
	v_exp_f32_e32 v138, v138
	v_exp_f32_e32 v139, v139
	s_waitcnt lgkmcnt(2)
	v_mfma_f32_32x32x16_bf16 v[66:81], v[90:93], v[244:247], v[66:81]
	v_exp_f32_e32 v140, v140
	v_exp_f32_e32 v141, v141
	s_waitcnt lgkmcnt(0)
; #define SBAR() __builtin_amdgcn_sched_barrier(0)
; template <typename TQ> ...
;     ...
;   finishSM(pB0, pB1, l_reg, pa0, pa1, pa2, pa3); SBAR();
;   pv_d0(o, vb0 + (int)SHM_V, pa0, pa1, pa2, pa3);
;   if (hi == 0) li_l[r32] = l_reg; asm volatile("s_waitcnt lgkmcnt(0)" ::: "memory");
	v_mfma_f32_32x32x16_bf16 v[66:81], v[94:97], v[248:251], v[66:81]
	v_exp_f32_e32 v142, v142
	v_exp_f32_e32 v143, v143
	v_exp_f32_e32 v144, v144
	v_exp_f32_e32 v145, v145
	ds_read_b64_tr_b16 v[236:237], v206 offset:49152
	ds_read_b64_tr_b16 v[238:239], v206 offset:51200
	ds_read_b64_tr_b16 v[240:241], v206 offset:53248
	ds_read_b64_tr_b16 v[242:243], v206 offset:55296
	ds_read_b64_tr_b16 v[244:245], v206 offset:57344
	ds_read_b64_tr_b16 v[246:247], v206 offset:59392
	ds_read_b64_tr_b16 v[248:249], v206 offset:61440
	ds_read_b64_tr_b16 v[250:251], v206 offset:63488
	v_add_f32_e32 v205, v114, v205
	v_add_f32_e32 v204, v115, v204
	v_cvt_pk_bf16_f32 v114, v114, v115
	v_add_f32_e32 v205, v116, v205
	v_add_f32_e32 v204, v117, v204
	v_cvt_pk_bf16_f32 v115, v116, v117
	v_add_f32_e32 v205, v118, v205
	v_add_f32_e32 v204, v119, v204
	v_cvt_pk_bf16_f32 v116, v118, v119
	v_add_f32_e32 v205, v120, v205
	v_add_f32_e32 v204, v121, v204
	v_cvt_pk_bf16_f32 v117, v120, v121
	v_add_f32_e32 v205, v122, v205
	v_add_f32_e32 v204, v123, v204
	v_cvt_pk_bf16_f32 v118, v122, v123
	v_add_f32_e32 v205, v124, v205
	v_add_f32_e32 v204, v125, v204
	v_cvt_pk_bf16_f32 v119, v124, v125
	v_add_f32_e32 v205, v126, v205
	v_add_f32_e32 v204, v127, v204
	v_cvt_pk_bf16_f32 v120, v126, v127
	v_add_f32_e32 v205, v128, v205
	v_add_f32_e32 v204, v129, v204
	v_cvt_pk_bf16_f32 v121, v128, v129
	v_add_f32_e32 v205, v130, v205
	v_add_f32_e32 v204, v131, v204
	v_cvt_pk_bf16_f32 v122, v130, v131
	v_add_f32_e32 v205, v132, v205
	v_add_f32_e32 v204, v133, v204
	v_cvt_pk_bf16_f32 v123, v132, v133
	v_add_f32_e32 v205, v134, v205
	v_add_f32_e32 v204, v135, v204
	v_cvt_pk_bf16_f32 v124, v134, v135
	v_add_f32_e32 v205, v136, v205
	v_add_f32_e32 v204, v137, v204
	v_cvt_pk_bf16_f32 v125, v136, v137
	v_add_f32_e32 v205, v138, v205
	v_add_f32_e32 v204, v139, v204
	v_cvt_pk_bf16_f32 v126, v138, v139
	v_add_f32_e32 v205, v140, v205
	v_add_f32_e32 v204, v141, v204
	v_cvt_pk_bf16_f32 v127, v140, v141
	v_add_f32_e32 v205, v142, v205
	v_add_f32_e32 v204, v143, v204
	v_cvt_pk_bf16_f32 v128, v142, v143
	v_add_f32_e32 v205, v144, v205
	v_add_f32_e32 v204, v145, v204
	v_cvt_pk_bf16_f32 v129, v144, v145
	s_nop 1
	v_permlane32_swap_b32_e32 v114, v116
	v_permlane32_swap_b32_e32 v115, v117
	v_permlane32_swap_b32_e32 v118, v120
	v_permlane32_swap_b32_e32 v119, v121
	v_permlane32_swap_b32_e32 v122, v124
	v_permlane32_swap_b32_e32 v123, v125
	v_permlane32_swap_b32_e32 v126, v128
	v_permlane32_swap_b32_e32 v127, v129
	ds_read_b64_tr_b16 v[130:131], v206 offset:49664
	ds_read_b64_tr_b16 v[132:133], v206 offset:51712
	ds_read_b64_tr_b16 v[134:135], v206 offset:53760
	ds_read_b64_tr_b16 v[136:137], v206 offset:55808
	s_waitcnt lgkmcnt(10)
	v_mfma_f32_32x32x16_bf16 v[18:33], v[114:117], v[236:239], v[18:33]
	ds_read_b64_tr_b16 v[236:237], v206 offset:57856
	ds_read_b64_tr_b16 v[238:239], v206 offset:59904
	s_waitcnt lgkmcnt(10)
	v_mfma_f32_32x32x16_bf16 v[18:33], v[118:121], v[240:243], v[18:33]
	ds_read_b64_tr_b16 v[240:241], v206 offset:61952
	ds_read_b64_tr_b16 v[242:243], v206 offset:64000
	s_waitcnt lgkmcnt(10)
	v_mfma_f32_32x32x16_bf16 v[18:33], v[122:125], v[244:247], v[18:33]
	ds_read_b64_tr_b16 v[244:245], v206 offset:50176
	ds_read_b64_tr_b16 v[246:247], v206 offset:52224
	s_waitcnt lgkmcnt(10)
	v_mfma_f32_32x32x16_bf16 v[18:33], v[126:129], v[248:251], v[18:33]
	ds_read_b64_tr_b16 v[248:249], v206 offset:54272
	ds_read_b64_tr_b16 v[250:251], v206 offset:56320
	s_waitcnt lgkmcnt(10)
	v_mfma_f32_32x32x16_bf16 v[34:49], v[114:117], v[130:133], v[34:49]
	ds_read_b64_tr_b16 v[130:131], v206 offset:58368
	ds_read_b64_tr_b16 v[132:133], v206 offset:60416
	s_waitcnt lgkmcnt(10)
	v_mfma_f32_32x32x16_bf16 v[34:49], v[118:121], v[134:137], v[34:49]
	ds_read_b64_tr_b16 v[134:135], v206 offset:62464
	ds_read_b64_tr_b16 v[136:137], v206 offset:64512
	s_waitcnt lgkmcnt(10)
	v_mfma_f32_32x32x16_bf16 v[34:49], v[122:125], v[236:239], v[34:49]
	ds_read_b64_tr_b16 v[236:237], v206 offset:50688
	ds_read_b64_tr_b16 v[238:239], v206 offset:52736
	s_waitcnt lgkmcnt(10)
	v_mfma_f32_32x32x16_bf16 v[34:49], v[126:129], v[240:243], v[34:49]
	ds_read_b64_tr_b16 v[240:241], v206 offset:54784
	ds_read_b64_tr_b16 v[242:243], v206 offset:56832
	s_waitcnt lgkmcnt(10)
	v_mfma_f32_32x32x16_bf16 v[50:65], v[114:117], v[244:247], v[50:65]
	ds_read_b64_tr_b16 v[244:245], v206 offset:58880
	ds_read_b64_tr_b16 v[246:247], v206 offset:60928
	s_waitcnt lgkmcnt(10)
	v_mfma_f32_32x32x16_bf16 v[50:65], v[118:121], v[248:251], v[50:65]
	ds_read_b64_tr_b16 v[248:249], v206 offset:62976
	ds_read_b64_tr_b16 v[250:251], v206 offset:65024
	s_waitcnt lgkmcnt(10)
	v_mfma_f32_32x32x16_bf16 v[50:65], v[122:125], v[130:133], v[50:65]
	s_waitcnt lgkmcnt(8)
	v_mfma_f32_32x32x16_bf16 v[50:65], v[126:129], v[134:137], v[50:65]
	s_waitcnt lgkmcnt(6)
	v_mfma_f32_32x32x16_bf16 v[66:81], v[114:117], v[236:239], v[66:81]
	s_waitcnt lgkmcnt(4)
	v_mfma_f32_32x32x16_bf16 v[66:81], v[118:121], v[240:243], v[66:81]
	s_waitcnt lgkmcnt(2)
	v_mfma_f32_32x32x16_bf16 v[66:81], v[122:125], v[244:247], v[66:81]
	s_waitcnt lgkmcnt(0)
	v_mfma_f32_32x32x16_bf16 v[66:81], v[126:129], v[248:251], v[66:81]
	s_and_b32 s0, s53, 0x3fffffc0
	s_lshl_b32 s0, s0, 2
	s_add_i32 s15, s0, 0x20800
	v_add_f32_e32 v205, v205, v204
	v_cmp_gt_u32_e32 vcc, 32, v203
	v_mov_b32_e32 v204, v205
	v_lshl_add_u32 v219, v202, 2, s15
	s_nop 1
	v_permlane32_swap_b32_e32 v205, v204
	v_add_f32_e32 v205, v205, v204
	s_and_saveexec_b64 s[0:1], vcc
	ds_write_b32 v219, v205
	s_branch .LBB0_817

; #define LAS __attribute__((address_space(3)))
; __global__ void __launch_bounds__(NTHR, 2) fwd_megakernel(KArgs a) {
;     extern __shared__ __attribute__((aligned(16))) unsigned char lds_raw[];
;     LAS unsigned char* lds = (LAS unsigned char*)lds_raw;
	.amdhsa_kernel _Z14fwd_megakernel5KArgs
		.amdhsa_group_segment_fixed_size 0
		.amdhsa_private_segment_fixed_size 0
		.amdhsa_kernarg_size 424
		.amdhsa_user_sgpr_count 2
		.amdhsa_user_sgpr_dispatch_ptr 0
		.amdhsa_user_sgpr_queue_ptr 0
		.amdhsa_user_sgpr_kernarg_segment_ptr 1
		.amdhsa_user_sgpr_dispatch_id 0
		.amdhsa_user_sgpr_kernarg_preload_length 0
		.amdhsa_user_sgpr_kernarg_preload_offset 0
		.amdhsa_user_sgpr_private_segment_size 0
		.amdhsa_uses_dynamic_stack 0
		.amdhsa_enable_private_segment 0
		.amdhsa_system_sgpr_workgroup_id_x 1
		.amdhsa_system_sgpr_workgroup_id_y 0
		.amdhsa_system_sgpr_workgroup_id_z 0
		.amdhsa_system_sgpr_workgroup_info 0
		.amdhsa_system_vgpr_workitem_id 0
		.amdhsa_next_free_vgpr 255
		.amdhsa_next_free_sgpr 102
		.amdhsa_accum_offset 256
		.amdhsa_reserve_vcc 1
		.amdhsa_float_round_mode_32 0
		.amdhsa_float_round_mode_16_64 0
		.amdhsa_float_denorm_mode_32 3
		.amdhsa_float_denorm_mode_16_64 3
		.amdhsa_dx10_clamp 1
		.amdhsa_ieee_mode 1
		.amdhsa_fp16_overflow 0
		.amdhsa_tg_split 0
		.amdhsa_exception_fp_ieee_invalid_op 0
		.amdhsa_exception_fp_denorm_src 0
		.amdhsa_exception_fp_ieee_div_zero 0
		.amdhsa_exception_fp_ieee_overflow 0
		.amdhsa_exception_fp_ieee_underflow 0
		.amdhsa_exception_fp_ieee_inexact 0
		.amdhsa_exception_int_div_zero 0
	.end_amdhsa_kernel

; #define LAS __attribute__((address_space(3)))
; __global__ void __launch_bounds__(NTHR, 2) fwd_megakernel(KArgs a) {
;     extern __shared__ __attribute__((aligned(16))) unsigned char lds_raw[];
;     LAS unsigned char* lds = (LAS unsigned char*)lds_raw;
amdhsa.kernels:
  - .agpr_count:     0
    .args:
      - .offset:         0
        .size:           168
        .value_kind:     by_value
      - .offset:         168
        .size:           4
        .value_kind:     hidden_block_count_x
      - .offset:         172
        .size:           4
        .value_kind:     hidden_block_count_y
      - .offset:         176
        .size:           4
        .value_kind:     hidden_block_count_z
      - .offset:         180
        .size:           2
        .value_kind:     hidden_group_size_x
      - .offset:         182
        .size:           2
        .value_kind:     hidden_group_size_y
      - .offset:         184
        .size:           2
        .value_kind:     hidden_group_size_z
      - .offset:         186
        .size:           2
        .value_kind:     hidden_remainder_x
      - .offset:         188
        .size:           2
        .value_kind:     hidden_remainder_y
      - .offset:         190
        .size:           2
        .value_kind:     hidden_remainder_z
      - .offset:         208
        .size:           8
        .value_kind:     hidden_global_offset_x
      - .offset:         216
        .size:           8
        .value_kind:     hidden_global_offset_y
      - .offset:         224
        .size:           8
        .value_kind:     hidden_global_offset_z
      - .offset:         232
        .size:           2
        .value_kind:     hidden_grid_dims
      - .offset:         256
        .size:           8
        .value_kind:     hidden_multigrid_sync_arg
      - .offset:         288
        .size:           4
        .value_kind:     hidden_dynamic_lds_size
    .group_segment_fixed_size: 0
    .kernarg_segment_align: 8
    .kernarg_segment_size: 424
    .language:       OpenCL C
    .language_version:
      - 2
      - 0
    .max_flat_workgroup_size: 512
    .name:           _Z14fwd_megakernel5KArgs
    .private_segment_fixed_size: 0
    .sgpr_count:     108
    .sgpr_spill_count: 11
    .symbol:         _Z14fwd_megakernel5KArgs.kd
    .uniform_work_group_size: 1
    .uses_dynamic_stack: false
    .vgpr_count:     255
    .vgpr_spill_count: 0
    .wavefront_size: 64
